# LayerNorm phases: integer bit-trick bf16 rounding replaced by v_cvt_pk_bf16_f32 (same RNE), sample rows spread over 128 workgroups; UP/OUT/DOWN epilogues hand-scheduled
# speedup vs baseline: 1.0206x; 1.0107x over previous
.LBB0_968:
	s_cmp_ge_i32 s22, s0
	s_mov_b64 s[12:13], -1
	s_cbranch_scc1 .LBB0_965
	s_and_b64 s[0:1], s[8:9], exec
	s_cselect_b32 s2, s19, s43
	s_cmpk_lt_i32 s2, 0x4000
	s_cbranch_scc0 .LBB0_965
	s_ashr_i32 s3, s2, 31
	s_lshl_b64 s[40:41], s[2:3], 11
	v_lshl_add_u64 v[2:3], v[82:83], 0, s[40:41]
	global_load_dwordx4 v[92:95], v[2:3], off offset:1024
	global_load_dwordx4 v[96:99], v[2:3], off
	global_load_dwordx4 v[74:77], v[84:85], off offset:16
	global_load_dwordx4 v[100:103], v[84:85], off
	global_load_dwordx4 v[78:81], v[86:87], off offset:16
	global_load_dwordx4 v[104:107], v[86:87], off
	global_load_dwordx4 v[58:61], v[84:85], off offset:2064
	global_load_dwordx4 v[66:69], v[84:85], off offset:2048
	global_load_dwordx4 v[62:65], v[86:87], off offset:2064
	global_load_dwordx4 v[70:73], v[86:87], off offset:2048
	s_or_b32 s0, s2, 1
	s_or_b32 s12, s2, 2
	s_or_b32 s16, s2, 3
	s_or_b32 s24, s2, 4
	s_or_b32 s36, s2, 5
	s_or_b32 s46, s2, 6
	s_or_b32 s2, s2, 7
	s_ashr_i32 s1, s0, 31
	s_ashr_i32 s13, s12, 31
	s_ashr_i32 s17, s16, 31
	s_ashr_i32 s25, s24, 31
	s_ashr_i32 s37, s36, 31
	s_ashr_i32 s47, s46, 31
	s_ashr_i32 s3, s2, 31
	s_lshl_b64 s[38:39], s[0:1], 11
	s_lshl_b64 s[28:29], s[12:13], 11
	s_lshl_b64 s[20:21], s[16:17], 11
	s_lshl_b64 s[24:25], s[24:25], 11
	s_lshl_b64 s[36:37], s[36:37], 11
	s_lshl_b64 s[16:17], s[46:47], 11
	s_lshl_b64 s[12:13], s[2:3], 11
	v_lshl_add_u64 v[2:3], v[82:83], 0, s[38:39]
	v_lshl_add_u64 v[4:5], v[82:83], 0, s[28:29]
	v_lshl_add_u64 v[6:7], v[82:83], 0, s[20:21]
	v_lshl_add_u64 v[8:9], v[82:83], 0, s[24:25]
	v_lshl_add_u64 v[10:11], v[82:83], 0, s[36:37]
	v_lshl_add_u64 v[12:13], v[82:83], 0, s[16:17]
	v_lshl_add_u64 v[108:109], v[82:83], 0, s[12:13]
	global_load_dwordx4 v[54:57], v[2:3], off
	global_load_dwordx4 v[50:53], v[2:3], off offset:1024
	global_load_dwordx4 v[46:49], v[4:5], off
	global_load_dwordx4 v[42:45], v[4:5], off offset:1024
	global_load_dwordx4 v[38:41], v[6:7], off
	global_load_dwordx4 v[34:37], v[6:7], off offset:1024
	global_load_dwordx4 v[30:33], v[8:9], off
	global_load_dwordx4 v[26:29], v[8:9], off offset:1024
	global_load_dwordx4 v[22:25], v[10:11], off
	global_load_dwordx4 v[18:21], v[10:11], off offset:1024
	global_load_dwordx4 v[14:17], v[12:13], off
	s_nop 0
	global_load_dwordx4 v[10:13], v[12:13], off offset:1024
	s_nop 0
	global_load_dwordx4 v[6:9], v[108:109], off
	global_load_dwordx4 v[2:5], v[108:109], off offset:1024
	s_add_i32 s22, s22, 1
	s_add_i32 s43, s43, s44
	s_waitcnt vmcnt(23)
	v_lshlrev_b32_e32 v108, 16, v92
	s_waitcnt vmcnt(22)
	v_lshlrev_b32_e32 v110, 16, v96
	v_and_b32_e32 v96, 0xffff0000, v96
	v_add_f32_e32 v0, 0, v110
	v_lshlrev_b32_e32 v111, 16, v97
	v_add_f32_e32 v0, v0, v96
	v_and_b32_e32 v97, 0xffff0000, v97
	v_add_f32_e32 v0, v0, v111
	v_lshlrev_b32_e32 v112, 16, v98
	v_add_f32_e32 v0, v0, v97
	v_and_b32_e32 v98, 0xffff0000, v98
	v_add_f32_e32 v0, v0, v112
	v_lshlrev_b32_e32 v113, 16, v99
	v_add_f32_e32 v0, v0, v98
	v_and_b32_e32 v99, 0xffff0000, v99
	v_add_f32_e32 v0, v0, v113
	v_add_f32_e32 v0, v0, v99
	v_and_b32_e32 v92, 0xffff0000, v92
	v_add_f32_e32 v0, v0, v108
	v_and_b32_e32 v114, 0xffff0000, v95
	v_lshlrev_b32_e32 v115, 16, v95
	v_lshlrev_b32_e32 v95, 16, v93
	v_add_f32_e32 v0, v0, v92
	v_and_b32_e32 v116, 0xffff0000, v94
	v_lshlrev_b32_e32 v117, 16, v94
	v_and_b32_e32 v94, 0xffff0000, v93
	v_add_f32_e32 v0, v0, v95
	v_add_f32_e32 v0, v0, v94
	v_add_f32_e32 v0, v0, v117
	v_add_f32_e32 v0, v0, v116
	v_add_f32_e32 v0, v0, v115
	v_add_f32_e32 v0, v0, v114
	s_nop 1
	v_add_f32_dpp v0, v0, v0 quad_perm:[1,0,3,2] row_mask:0xf bank_mask:0xf bound_ctrl:1
	s_nop 1
	v_add_f32_dpp v0, v0, v0 quad_perm:[2,3,0,1] row_mask:0xf bank_mask:0xf bound_ctrl:1
	s_nop 1
	v_add_f32_dpp v0, v0, v0 row_half_mirror row_mask:0xf bank_mask:0xf bound_ctrl:1
	s_nop 1
	v_add_f32_dpp v0, v0, v0 row_mirror row_mask:0xf bank_mask:0xf bound_ctrl:1
	s_nop 0
	v_readlane_b32 s2, v0, 16
	v_readlane_b32 s3, v0, 48
	v_readlane_b32 s0, v0, 0
	v_readlane_b32 s1, v0, 32
	v_mov_b32_e32 v118, s2
	v_mov_b32_e32 v119, s3
	v_pk_add_f32 v[118:119], s[0:1], v[118:119]
	s_nop 0
	v_add_f32_e32 v91, v118, v119
	v_mul_f32_e32 v0, 0x3a800000, v91
	v_pk_add_f32 v[110:111], v[110:111], v[0:1] op_sel_hi:[1,0] neg_lo:[0,1] neg_hi:[0,1]
	v_pk_add_f32 v[96:97], v[96:97], v[0:1] op_sel_hi:[1,0] neg_lo:[0,1] neg_hi:[0,1]
	v_pk_mul_f32 v[118:119], v[110:111], v[110:111]
	v_pk_mul_f32 v[120:121], v[96:97], v[96:97]
	v_fmac_f32_e32 v108, 0xba800000, v91
	v_fmac_f32_e32 v92, 0xba800000, v91
	v_add_f32_e32 v91, v118, v120
	v_pk_add_f32 v[112:113], v[112:113], v[0:1] op_sel_hi:[1,0] neg_lo:[0,1] neg_hi:[0,1]
	v_add_f32_e32 v91, v119, v91
	v_pk_add_f32 v[98:99], v[98:99], v[0:1] op_sel_hi:[1,0] neg_lo:[0,1] neg_hi:[0,1]
	v_pk_mul_f32 v[122:123], v[112:113], v[112:113]
	v_add_f32_e32 v91, v121, v91
	v_pk_mul_f32 v[124:125], v[98:99], v[98:99]
	v_add_f32_e32 v91, v122, v91
	v_add_f32_e32 v91, v124, v91
	v_add_f32_e32 v91, v123, v91
	v_add_f32_e32 v91, v125, v91
	v_pk_add_f32 v[94:95], v[94:95], v[0:1] op_sel_hi:[1,0] neg_lo:[0,1] neg_hi:[0,1]
	v_fmac_f32_e32 v91, v108, v108
	v_fmac_f32_e32 v91, v92, v92
	v_pk_mul_f32 v[118:119], v[94:95], v[94:95]
	v_pk_add_f32 v[116:117], v[116:117], v[0:1] op_sel_hi:[1,0] neg_lo:[0,1] neg_hi:[0,1]
	v_add_f32_e32 v91, v119, v91
	v_add_f32_e32 v91, v118, v91
	v_pk_mul_f32 v[118:119], v[116:117], v[116:117]
	v_pk_add_f32 v[114:115], v[114:115], v[0:1] op_sel_hi:[1,0] neg_lo:[0,1] neg_hi:[0,1]
	v_add_f32_e32 v91, v119, v91
	v_add_f32_e32 v91, v118, v91
	v_pk_mul_f32 v[118:119], v[114:115], v[114:115]
	s_waitcnt vmcnt(18)
	v_mov_b32_e32 v120, v104
	v_add_f32_e32 v0, v119, v91
	v_add_f32_e32 v0, v118, v0
	v_mov_b32_e32 v121, v106
	v_mov_b32_e32 v106, v105
	v_add_f32_dpp v0, v0, v0 quad_perm:[1,0,3,2] row_mask:0xf bank_mask:0xf bound_ctrl:1
	v_mov_b32_e32 v105, v76
	v_mov_b32_e32 v76, v75
	v_add_f32_dpp v0, v0, v0 quad_perm:[2,3,0,1] row_mask:0xf bank_mask:0xf bound_ctrl:1
	v_mov_b32_e32 v109, v95
	s_nop 0
	v_add_f32_dpp v0, v0, v0 row_half_mirror row_mask:0xf bank_mask:0xf bound_ctrl:1
	s_nop 1
	v_add_f32_dpp v0, v0, v0 row_mirror row_mask:0xf bank_mask:0xf bound_ctrl:1
	s_nop 0
	v_readlane_b32 s2, v0, 16
	v_readlane_b32 s3, v0, 48
	v_readlane_b32 s0, v0, 0
	v_readlane_b32 s1, v0, 32
	v_mov_b32_e32 v118, s2
	v_mov_b32_e32 v119, s3
	v_pk_add_f32 v[118:119], s[0:1], v[118:119]
	s_nop 0
	v_add_f32_e32 v0, v118, v119
	v_fmamk_f32 v0, v0, 0x3a800000, v216
	v_mul_f32_e32 v91, 0x4f800000, v0
	v_cmp_gt_f32_e32 vcc, s60, v0
	v_mov_b32_e32 v118, v100
	v_mov_b32_e32 v119, v102
	v_cndmask_b32_e32 v0, v0, v91, vcc
	v_sqrt_f32_e32 v91, v0
	v_mov_b32_e32 v102, v101
	v_add_u32_e32 v93, -1, v91
	v_fma_f32 v100, -v93, v91, v0
	v_cmp_ge_f32_e64 s[2:3], 0, v100
	v_add_u32_e32 v100, 1, v91
	s_nop 0
	v_cndmask_b32_e64 v93, v91, v93, s[2:3]
	v_fma_f32 v91, -v100, v91, v0
	v_cmp_lt_f32_e64 s[2:3], 0, v91
	s_nop 1
	v_cndmask_b32_e64 v91, v93, v100, s[2:3]
	v_mul_f32_e32 v93, 0x37800000, v91
	v_cndmask_b32_e32 v91, v91, v93, vcc
	v_cmp_class_f32_e32 vcc, v0, v217
	s_nop 1
	v_cndmask_b32_e32 v0, v91, v0, vcc
	v_div_scale_f32 v91, s[0:1], v0, v0, 1.0
	v_rcp_f32_e32 v93, v91
	s_nop 0
	v_fma_f32 v100, -v91, v93, 1.0
	v_fmac_f32_e32 v93, v100, v93
	v_div_scale_f32 v100, vcc, 1.0, v0, 1.0
	v_mul_f32_e32 v101, v100, v93
	v_fma_f32 v104, -v91, v101, v100
	v_fmac_f32_e32 v101, v104, v93
	v_fma_f32 v91, -v91, v101, v100
	v_div_fmas_f32 v91, v91, v93, v101
	v_div_fixup_f32 v0, v91, v0, 1.0
	v_pk_mul_f32 v[96:97], v[96:97], v[0:1] op_sel_hi:[1,0]
	v_pk_mul_f32 v[98:99], v[98:99], v[0:1] op_sel_hi:[1,0]
	v_pk_fma_f32 v[96:97], v[102:103], v[96:97], v[106:107]
	v_mov_b32_e32 v107, v80
	v_mov_b32_e32 v80, v79
	v_pk_mul_f32 v[100:101], v[110:111], v[0:1] op_sel_hi:[1,0]
	v_pk_mul_f32 v[102:103], v[112:113], v[0:1] op_sel_hi:[1,0]
	v_mov_b32_e32 v104, v74
	v_mov_b32_e32 v106, v78
	v_pk_fma_f32 v[74:75], v[76:77], v[98:99], v[80:81]
	v_pk_fma_f32 v[100:101], v[118:119], v[100:101], v[120:121]
	v_pk_fma_f32 v[102:103], v[104:105], v[102:103], v[106:107]
	s_nop 0
	v_cvt_pk_bf16_f32 v77, v103, v75
	v_cvt_pk_bf16_f32 v76, v102, v74
	v_cvt_pk_bf16_f32 v75, v101, v97
	v_cvt_pk_bf16_f32 v74, v100, v96
	v_lshl_add_u64 v[78:79], v[88:89], 0, s[40:41]
	global_store_dwordx4 v[78:79], v[74:77], off
	s_waitcnt vmcnt(15)
	v_mov_b32_e32 v80, v70
	v_mov_b32_e32 v81, v72
	v_pk_mul_f32 v[74:75], v[108:109], v[0:1] op_sel_hi:[1,0]
	v_mov_b32_e32 v76, v66
	v_mov_b32_e32 v77, v68
	v_mov_b32_e32 v93, v94
	v_pk_fma_f32 v[74:75], v[76:77], v[74:75], v[80:81]
	v_pk_mul_f32 v[76:77], v[92:93], v[0:1] op_sel_hi:[1,0]
	v_mov_b32_e32 v68, v67
	v_mov_b32_e32 v72, v71
	v_pk_fma_f32 v[66:67], v[68:69], v[76:77], v[72:73]
	v_mov_b32_e32 v68, v117
	v_mov_b32_e32 v69, v115
	v_pk_mul_f32 v[68:69], v[68:69], v[0:1] op_sel_hi:[1,0]
	v_mov_b32_e32 v70, v58
	v_mov_b32_e32 v71, v60
	v_mov_b32_e32 v72, v62
	v_mov_b32_e32 v73, v64
	v_mov_b32_e32 v117, v114
	v_pk_fma_f32 v[68:69], v[68:69], v[70:71], v[72:73]
	v_pk_mul_f32 v[70:71], v[116:117], v[0:1] op_sel_hi:[1,0]
	v_mov_b32_e32 v60, v59
	v_mov_b32_e32 v64, v63
	v_pk_fma_f32 v[58:59], v[70:71], v[60:61], v[64:65]
	s_nop 0
	v_cvt_pk_bf16_f32 v61, v69, v59
	v_cvt_pk_bf16_f32 v60, v68, v58
	v_cvt_pk_bf16_f32 v59, v75, v67
	v_cvt_pk_bf16_f32 v58, v74, v66
	global_store_dwordx4 v[78:79], v[58:61], off offset:1024
	global_load_dwordx4 v[58:61], v[84:85], off offset:16
	s_nop 0
	global_load_dwordx4 v[62:65], v[84:85], off
	global_load_dwordx4 v[66:69], v[86:87], off offset:16
	global_load_dwordx4 v[70:73], v[86:87], off
	global_load_dwordx4 v[74:77], v[84:85], off offset:2064
	global_load_dwordx4 v[78:81], v[84:85], off offset:2048
	global_load_dwordx4 v[92:95], v[86:87], off offset:2064
	global_load_dwordx4 v[96:99], v[86:87], off offset:2048
	s_waitcnt vmcnt(23)
	v_lshlrev_b32_e32 v104, 16, v54
	v_and_b32_e32 v54, 0xffff0000, v54
	v_add_f32_e32 v0, 0, v104
	v_lshlrev_b32_e32 v105, 16, v55
	v_add_f32_e32 v0, v0, v54
	v_and_b32_e32 v55, 0xffff0000, v55
	v_add_f32_e32 v0, v0, v105
	v_add_f32_e32 v0, v0, v55
	v_lshlrev_b32_e32 v106, 16, v56
	v_and_b32_e32 v56, 0xffff0000, v56
	v_add_f32_e32 v0, v0, v106
	v_lshlrev_b32_e32 v107, 16, v57
	v_add_f32_e32 v0, v0, v56
	v_and_b32_e32 v57, 0xffff0000, v57
	v_add_f32_e32 v0, v0, v107
	s_waitcnt vmcnt(22)
	v_lshlrev_b32_e32 v100, 16, v50
	v_add_f32_e32 v0, v0, v57
	v_and_b32_e32 v102, 0xffff0000, v50
	v_add_f32_e32 v0, v0, v100
	v_add_f32_e32 v0, v0, v102
	v_and_b32_e32 v50, 0xffff0000, v51
	v_lshlrev_b32_e32 v51, 16, v51
	v_add_f32_e32 v0, v0, v51
	v_lshlrev_b32_e32 v111, 16, v52
	v_add_f32_e32 v0, v0, v50
	v_and_b32_e32 v110, 0xffff0000, v52
	v_add_f32_e32 v0, v0, v111
	v_lshlrev_b32_e32 v109, 16, v53
	v_add_f32_e32 v0, v0, v110
	v_and_b32_e32 v108, 0xffff0000, v53
	v_add_f32_e32 v0, v0, v109
	v_add_f32_e32 v0, v0, v108
	s_nop 1
	v_add_f32_dpp v0, v0, v0 quad_perm:[1,0,3,2] row_mask:0xf bank_mask:0xf bound_ctrl:1
	s_nop 1
	v_add_f32_dpp v0, v0, v0 quad_perm:[2,3,0,1] row_mask:0xf bank_mask:0xf bound_ctrl:1
	s_nop 1
	v_add_f32_dpp v0, v0, v0 row_half_mirror row_mask:0xf bank_mask:0xf bound_ctrl:1
	s_nop 1
	v_add_f32_dpp v0, v0, v0 row_mirror row_mask:0xf bank_mask:0xf bound_ctrl:1
	s_nop 0
	v_readlane_b32 s2, v0, 16
	v_readlane_b32 s3, v0, 48
	v_readlane_b32 s0, v0, 0
	v_readlane_b32 s1, v0, 32
	v_mov_b32_e32 v52, s2
	v_mov_b32_e32 v53, s3
	v_pk_add_f32 v[52:53], s[0:1], v[52:53]
	s_nop 0
	v_add_f32_e32 v91, v52, v53
	v_mul_f32_e32 v0, 0x3a800000, v91
	v_pk_add_f32 v[52:53], v[104:105], v[0:1] op_sel_hi:[1,0] neg_lo:[0,1] neg_hi:[0,1]
	v_pk_add_f32 v[54:55], v[54:55], v[0:1] op_sel_hi:[1,0] neg_lo:[0,1] neg_hi:[0,1]
	v_pk_mul_f32 v[104:105], v[52:53], v[52:53]
	v_pk_mul_f32 v[112:113], v[54:55], v[54:55]
	v_pk_add_f32 v[106:107], v[106:107], v[0:1] op_sel_hi:[1,0] neg_lo:[0,1] neg_hi:[0,1]
	v_add_f32_e32 v101, v104, v112
	v_add_f32_e32 v101, v105, v101
	v_pk_mul_f32 v[114:115], v[106:107], v[106:107]
	v_pk_add_f32 v[56:57], v[56:57], v[0:1] op_sel_hi:[1,0] neg_lo:[0,1] neg_hi:[0,1]
	v_add_f32_e32 v101, v113, v101
	v_pk_mul_f32 v[116:117], v[56:57], v[56:57]
	v_add_f32_e32 v101, v114, v101
	v_add_f32_e32 v101, v116, v101
	v_add_f32_e32 v101, v115, v101
	v_add_f32_e32 v101, v117, v101
	v_fmac_f32_e32 v100, 0xba800000, v91
	v_fmac_f32_e32 v101, v100, v100
	v_fmac_f32_e32 v102, 0xba800000, v91
	v_pk_add_f32 v[104:105], v[50:51], v[0:1] op_sel_hi:[1,0] neg_lo:[0,1] neg_hi:[0,1]
	v_fmac_f32_e32 v101, v102, v102
	v_pk_mul_f32 v[50:51], v[104:105], v[104:105]
	v_pk_add_f32 v[110:111], v[110:111], v[0:1] op_sel_hi:[1,0] neg_lo:[0,1] neg_hi:[0,1]
	v_add_f32_e32 v51, v51, v101
	v_add_f32_e32 v91, v50, v51
	v_pk_mul_f32 v[50:51], v[110:111], v[110:111]
	v_pk_add_f32 v[108:109], v[108:109], v[0:1] op_sel_hi:[1,0] neg_lo:[0,1] neg_hi:[0,1]
	v_add_f32_e32 v51, v51, v91
	v_add_f32_e32 v91, v50, v51
	v_pk_mul_f32 v[50:51], v[108:109], v[108:109]
	s_waitcnt vmcnt(4)
	v_mov_b32_e32 v112, v70
	v_add_f32_e32 v0, v51, v91
	v_add_f32_e32 v0, v50, v0
	v_mov_b32_e32 v113, v72
	v_mov_b32_e32 v72, v71
	v_add_f32_dpp v0, v0, v0 quad_perm:[1,0,3,2] row_mask:0xf bank_mask:0xf bound_ctrl:1
	v_mov_b32_e32 v101, v105
	v_mov_b32_e32 v103, v104
	v_add_f32_dpp v0, v0, v0 quad_perm:[2,3,0,1] row_mask:0xf bank_mask:0xf bound_ctrl:1
	s_nop 1
	v_add_f32_dpp v0, v0, v0 row_half_mirror row_mask:0xf bank_mask:0xf bound_ctrl:1
	s_nop 1
	v_add_f32_dpp v0, v0, v0 row_mirror row_mask:0xf bank_mask:0xf bound_ctrl:1
	s_nop 0
	v_readlane_b32 s2, v0, 16
	v_readlane_b32 s3, v0, 48
	v_readlane_b32 s0, v0, 0
	v_readlane_b32 s1, v0, 32
	v_mov_b32_e32 v50, s2
	v_mov_b32_e32 v51, s3
	v_pk_add_f32 v[50:51], s[0:1], v[50:51]
	s_nop 0
	v_add_f32_e32 v0, v50, v51
	v_fmamk_f32 v0, v0, 0x3a800000, v216
	v_mul_f32_e32 v50, 0x4f800000, v0
	v_cmp_gt_f32_e32 vcc, s60, v0
	v_mov_b32_e32 v51, v64
	s_nop 0
	v_cndmask_b32_e32 v0, v0, v50, vcc
	v_sqrt_f32_e32 v91, v0
	v_mov_b32_e32 v50, v62
	v_add_u32_e32 v62, -1, v91
	v_fma_f32 v64, -v62, v91, v0
	v_cmp_ge_f32_e64 s[2:3], 0, v64
	v_add_u32_e32 v64, 1, v91
	v_fma_f32 v70, -v64, v91, v0
	v_cndmask_b32_e64 v62, v91, v62, s[2:3]
	v_cmp_lt_f32_e64 s[2:3], 0, v70
	s_nop 1
	v_cndmask_b32_e64 v62, v62, v64, s[2:3]
	v_mul_f32_e32 v64, 0x37800000, v62
	v_cndmask_b32_e32 v62, v62, v64, vcc
	v_cmp_class_f32_e32 vcc, v0, v217
	v_mov_b32_e32 v64, v63
	s_nop 0
	v_cndmask_b32_e32 v0, v62, v0, vcc
	v_div_scale_f32 v62, s[0:1], v0, v0, 1.0
	v_rcp_f32_e32 v70, v62
	s_nop 0
	v_fma_f32 v63, -v62, v70, 1.0
	v_fmac_f32_e32 v70, v63, v70
	v_div_scale_f32 v63, vcc, 1.0, v0, 1.0
	v_mul_f32_e32 v71, v63, v70
	v_fma_f32 v91, -v62, v71, v63
	v_fmac_f32_e32 v71, v91, v70
	v_fma_f32 v62, -v62, v71, v63
	v_div_fmas_f32 v62, v62, v70, v71
	v_div_fixup_f32 v0, v62, v0, 1.0
	v_pk_mul_f32 v[52:53], v[52:53], v[0:1] op_sel_hi:[1,0]
	v_mov_b32_e32 v63, v60
	v_pk_fma_f32 v[50:51], v[50:51], v[52:53], v[112:113]
	v_pk_mul_f32 v[52:53], v[54:55], v[0:1] op_sel_hi:[1,0]
	v_pk_mul_f32 v[56:57], v[56:57], v[0:1] op_sel_hi:[1,0]
	v_pk_fma_f32 v[52:53], v[64:65], v[52:53], v[72:73]
	v_mov_b32_e32 v65, v68
	v_mov_b32_e32 v60, v59
	v_mov_b32_e32 v68, v67
	v_pk_mul_f32 v[54:55], v[106:107], v[0:1] op_sel_hi:[1,0]
	v_mov_b32_e32 v62, v58
	v_mov_b32_e32 v64, v66
	v_pk_fma_f32 v[56:57], v[60:61], v[56:57], v[68:69]
	v_pk_fma_f32 v[54:55], v[62:63], v[54:55], v[64:65]
	v_cvt_pk_bf16_f32 v51, v51, v53
	v_cvt_pk_bf16_f32 v53, v55, v57
	v_cvt_pk_bf16_f32 v50, v50, v52
	v_cvt_pk_bf16_f32 v52, v54, v56
	v_lshl_add_u64 v[54:55], v[88:89], 0, s[38:39]
	global_store_dwordx4 v[54:55], v[50:53], off
	s_waitcnt vmcnt(1)
	v_mov_b32_e32 v56, v96
	v_mov_b32_e32 v57, v98
	v_pk_mul_f32 v[50:51], v[100:101], v[0:1] op_sel_hi:[1,0]
	v_mov_b32_e32 v52, v78
	v_mov_b32_e32 v53, v80
	v_pk_fma_f32 v[50:51], v[52:53], v[50:51], v[56:57]
	v_mov_b32_e32 v56, v111
	v_mov_b32_e32 v57, v109
	v_pk_mul_f32 v[56:57], v[56:57], v[0:1] op_sel_hi:[1,0]
	v_mov_b32_e32 v58, v74
	v_mov_b32_e32 v59, v76
	v_mov_b32_e32 v60, v92
	v_mov_b32_e32 v61, v94
	v_mov_b32_e32 v111, v108
	v_pk_mul_f32 v[52:53], v[102:103], v[0:1] op_sel_hi:[1,0]
	v_mov_b32_e32 v80, v79
	v_mov_b32_e32 v98, v97
	v_pk_fma_f32 v[56:57], v[56:57], v[58:59], v[60:61]
	v_pk_mul_f32 v[58:59], v[110:111], v[0:1] op_sel_hi:[1,0]
	v_mov_b32_e32 v76, v75
	v_mov_b32_e32 v94, v93
	v_pk_fma_f32 v[52:53], v[80:81], v[52:53], v[98:99]
	v_pk_fma_f32 v[58:59], v[58:59], v[76:77], v[94:95]
	v_cvt_pk_bf16_f32 v51, v51, v53
	v_cvt_pk_bf16_f32 v53, v57, v59
	v_cvt_pk_bf16_f32 v50, v50, v52
	v_cvt_pk_bf16_f32 v52, v56, v58
	global_store_dwordx4 v[54:55], v[50:53], off offset:1024
	global_load_dwordx4 v[50:53], v[84:85], off offset:16
	s_nop 0
	global_load_dwordx4 v[54:57], v[84:85], off
	global_load_dwordx4 v[58:61], v[86:87], off offset:16
	global_load_dwordx4 v[62:65], v[86:87], off
	global_load_dwordx4 v[66:69], v[84:85], off offset:2064
	global_load_dwordx4 v[70:73], v[84:85], off offset:2048
	global_load_dwordx4 v[74:77], v[86:87], off offset:2064
	global_load_dwordx4 v[78:81], v[86:87], off offset:2048
	v_lshlrev_b32_e32 v96, 16, v46
	v_and_b32_e32 v46, 0xffff0000, v46
	v_add_f32_e32 v0, 0, v96
	v_lshlrev_b32_e32 v97, 16, v47
	v_add_f32_e32 v0, v0, v46
	v_and_b32_e32 v47, 0xffff0000, v47
	v_add_f32_e32 v0, v0, v97
	v_add_f32_e32 v0, v0, v47
	v_lshlrev_b32_e32 v98, 16, v48
	v_and_b32_e32 v48, 0xffff0000, v48
	v_add_f32_e32 v0, v0, v98
	v_lshlrev_b32_e32 v99, 16, v49
	v_add_f32_e32 v0, v0, v48
	v_and_b32_e32 v49, 0xffff0000, v49
	v_add_f32_e32 v0, v0, v99
	v_lshlrev_b32_e32 v92, 16, v42
	v_add_f32_e32 v0, v0, v49
	v_and_b32_e32 v94, 0xffff0000, v42
	v_add_f32_e32 v0, v0, v92
	v_add_f32_e32 v0, v0, v94
	v_and_b32_e32 v42, 0xffff0000, v43
	v_lshlrev_b32_e32 v43, 16, v43
	v_add_f32_e32 v0, v0, v43
	v_lshlrev_b32_e32 v103, 16, v44
	v_add_f32_e32 v0, v0, v42
	v_and_b32_e32 v102, 0xffff0000, v44
	v_add_f32_e32 v0, v0, v103
	v_lshlrev_b32_e32 v101, 16, v45
	v_add_f32_e32 v0, v0, v102
	v_and_b32_e32 v100, 0xffff0000, v45
	v_add_f32_e32 v0, v0, v101
	v_add_f32_e32 v0, v0, v100
	s_nop 1
	v_add_f32_dpp v0, v0, v0 quad_perm:[1,0,3,2] row_mask:0xf bank_mask:0xf bound_ctrl:1
	s_nop 1
	v_add_f32_dpp v0, v0, v0 quad_perm:[2,3,0,1] row_mask:0xf bank_mask:0xf bound_ctrl:1
	s_nop 1
	v_add_f32_dpp v0, v0, v0 row_half_mirror row_mask:0xf bank_mask:0xf bound_ctrl:1
	s_nop 1
	v_add_f32_dpp v0, v0, v0 row_mirror row_mask:0xf bank_mask:0xf bound_ctrl:1
	s_nop 0
	v_readlane_b32 s2, v0, 16
	v_readlane_b32 s3, v0, 48
	v_readlane_b32 s0, v0, 0
	v_readlane_b32 s1, v0, 32
	v_mov_b32_e32 v44, s2
	v_mov_b32_e32 v45, s3
	v_pk_add_f32 v[44:45], s[0:1], v[44:45]
	s_nop 0
	v_add_f32_e32 v91, v44, v45
	v_mul_f32_e32 v0, 0x3a800000, v91
	v_pk_add_f32 v[44:45], v[96:97], v[0:1] op_sel_hi:[1,0] neg_lo:[0,1] neg_hi:[0,1]
	v_pk_add_f32 v[46:47], v[46:47], v[0:1] op_sel_hi:[1,0] neg_lo:[0,1] neg_hi:[0,1]
	v_pk_mul_f32 v[96:97], v[44:45], v[44:45]
	v_pk_mul_f32 v[104:105], v[46:47], v[46:47]
	v_pk_add_f32 v[98:99], v[98:99], v[0:1] op_sel_hi:[1,0] neg_lo:[0,1] neg_hi:[0,1]
	v_add_f32_e32 v93, v96, v104
	v_add_f32_e32 v93, v97, v93
	v_pk_mul_f32 v[106:107], v[98:99], v[98:99]
	v_pk_add_f32 v[48:49], v[48:49], v[0:1] op_sel_hi:[1,0] neg_lo:[0,1] neg_hi:[0,1]
	v_add_f32_e32 v93, v105, v93
	v_pk_mul_f32 v[108:109], v[48:49], v[48:49]
	v_add_f32_e32 v93, v106, v93
	v_add_f32_e32 v93, v108, v93
	v_add_f32_e32 v93, v107, v93
	v_add_f32_e32 v93, v109, v93
	v_fmac_f32_e32 v92, 0xba800000, v91
	v_fmac_f32_e32 v93, v92, v92
	v_fmac_f32_e32 v94, 0xba800000, v91
	v_pk_add_f32 v[96:97], v[42:43], v[0:1] op_sel_hi:[1,0] neg_lo:[0,1] neg_hi:[0,1]
	v_fmac_f32_e32 v93, v94, v94
	v_pk_mul_f32 v[42:43], v[96:97], v[96:97]
	v_pk_add_f32 v[102:103], v[102:103], v[0:1] op_sel_hi:[1,0] neg_lo:[0,1] neg_hi:[0,1]
	v_add_f32_e32 v43, v43, v93
	v_add_f32_e32 v91, v42, v43
	v_pk_mul_f32 v[42:43], v[102:103], v[102:103]
	v_pk_add_f32 v[100:101], v[100:101], v[0:1] op_sel_hi:[1,0] neg_lo:[0,1] neg_hi:[0,1]
	v_add_f32_e32 v43, v43, v91
	v_add_f32_e32 v91, v42, v43
	v_pk_mul_f32 v[42:43], v[100:101], v[100:101]
	s_waitcnt vmcnt(4)
	v_mov_b32_e32 v104, v62
	v_add_f32_e32 v0, v43, v91
	v_add_f32_e32 v0, v42, v0
	v_mov_b32_e32 v105, v64
	v_mov_b32_e32 v64, v63
	v_add_f32_dpp v0, v0, v0 quad_perm:[1,0,3,2] row_mask:0xf bank_mask:0xf bound_ctrl:1
	v_mov_b32_e32 v93, v97
	v_mov_b32_e32 v95, v96
	v_add_f32_dpp v0, v0, v0 quad_perm:[2,3,0,1] row_mask:0xf bank_mask:0xf bound_ctrl:1
	s_nop 1
	v_add_f32_dpp v0, v0, v0 row_half_mirror row_mask:0xf bank_mask:0xf bound_ctrl:1
	s_nop 1
	v_add_f32_dpp v0, v0, v0 row_mirror row_mask:0xf bank_mask:0xf bound_ctrl:1
	s_nop 0
	v_readlane_b32 s2, v0, 16
	v_readlane_b32 s3, v0, 48
	v_readlane_b32 s0, v0, 0
	v_readlane_b32 s1, v0, 32
	v_mov_b32_e32 v42, s2
	v_mov_b32_e32 v43, s3
	v_pk_add_f32 v[42:43], s[0:1], v[42:43]
	s_nop 0
	v_add_f32_e32 v0, v42, v43
	v_fmamk_f32 v0, v0, 0x3a800000, v216
	v_mul_f32_e32 v42, 0x4f800000, v0
	v_cmp_gt_f32_e32 vcc, s60, v0
	v_mov_b32_e32 v43, v56
	s_nop 0
	v_cndmask_b32_e32 v0, v0, v42, vcc
	v_sqrt_f32_e32 v91, v0
	v_mov_b32_e32 v42, v54
	v_add_u32_e32 v54, -1, v91
	v_fma_f32 v56, -v54, v91, v0
	v_cmp_ge_f32_e64 s[2:3], 0, v56
	v_add_u32_e32 v56, 1, v91
	v_fma_f32 v62, -v56, v91, v0
	v_cndmask_b32_e64 v54, v91, v54, s[2:3]
	v_cmp_lt_f32_e64 s[2:3], 0, v62
	s_nop 1
	v_cndmask_b32_e64 v54, v54, v56, s[2:3]
	v_mul_f32_e32 v56, 0x37800000, v54
	v_cndmask_b32_e32 v54, v54, v56, vcc
	v_cmp_class_f32_e32 vcc, v0, v217
	v_mov_b32_e32 v56, v55
	s_nop 0
	v_cndmask_b32_e32 v0, v54, v0, vcc
	v_div_scale_f32 v54, s[0:1], v0, v0, 1.0
	v_rcp_f32_e32 v62, v54
	s_nop 0
	v_fma_f32 v55, -v54, v62, 1.0
	v_fmac_f32_e32 v62, v55, v62
	v_div_scale_f32 v55, vcc, 1.0, v0, 1.0
	v_mul_f32_e32 v63, v55, v62
	v_fma_f32 v91, -v54, v63, v55
	v_fmac_f32_e32 v63, v91, v62
	v_fma_f32 v54, -v54, v63, v55
	v_div_fmas_f32 v54, v54, v62, v63
	v_div_fixup_f32 v0, v54, v0, 1.0
	v_pk_mul_f32 v[44:45], v[44:45], v[0:1] op_sel_hi:[1,0]
	v_mov_b32_e32 v55, v52
	v_pk_fma_f32 v[42:43], v[42:43], v[44:45], v[104:105]
	v_pk_mul_f32 v[44:45], v[46:47], v[0:1] op_sel_hi:[1,0]
	v_pk_mul_f32 v[48:49], v[48:49], v[0:1] op_sel_hi:[1,0]
	v_pk_fma_f32 v[44:45], v[56:57], v[44:45], v[64:65]
	v_mov_b32_e32 v57, v60
	v_mov_b32_e32 v52, v51
	v_mov_b32_e32 v60, v59
	v_pk_mul_f32 v[46:47], v[98:99], v[0:1] op_sel_hi:[1,0]
	v_mov_b32_e32 v54, v50
	v_mov_b32_e32 v56, v58
	v_pk_fma_f32 v[48:49], v[52:53], v[48:49], v[60:61]
	v_pk_fma_f32 v[46:47], v[54:55], v[46:47], v[56:57]
	v_cvt_pk_bf16_f32 v43, v43, v45
	v_cvt_pk_bf16_f32 v45, v47, v49
	v_cvt_pk_bf16_f32 v42, v42, v44
	v_cvt_pk_bf16_f32 v44, v46, v48
	v_lshl_add_u64 v[46:47], v[88:89], 0, s[28:29]
	global_store_dwordx4 v[46:47], v[42:45], off
	s_waitcnt vmcnt(1)
	v_mov_b32_e32 v48, v78
	v_mov_b32_e32 v49, v80
	v_pk_mul_f32 v[42:43], v[92:93], v[0:1] op_sel_hi:[1,0]
	v_mov_b32_e32 v44, v70
	v_mov_b32_e32 v45, v72
	v_pk_fma_f32 v[42:43], v[44:45], v[42:43], v[48:49]
	v_mov_b32_e32 v48, v103
	v_mov_b32_e32 v49, v101
	v_pk_mul_f32 v[48:49], v[48:49], v[0:1] op_sel_hi:[1,0]
	v_mov_b32_e32 v50, v66
	v_mov_b32_e32 v51, v68
	v_mov_b32_e32 v52, v74
	v_mov_b32_e32 v53, v76
	v_mov_b32_e32 v103, v100
	v_pk_mul_f32 v[44:45], v[94:95], v[0:1] op_sel_hi:[1,0]
	v_mov_b32_e32 v72, v71
	v_mov_b32_e32 v80, v79
	v_pk_fma_f32 v[48:49], v[48:49], v[50:51], v[52:53]
	v_pk_mul_f32 v[50:51], v[102:103], v[0:1] op_sel_hi:[1,0]
	v_mov_b32_e32 v68, v67
	v_mov_b32_e32 v76, v75
	v_pk_fma_f32 v[44:45], v[72:73], v[44:45], v[80:81]
	v_pk_fma_f32 v[50:51], v[50:51], v[68:69], v[76:77]
	v_cvt_pk_bf16_f32 v43, v43, v45
	v_cvt_pk_bf16_f32 v45, v49, v51
	v_cvt_pk_bf16_f32 v42, v42, v44
	v_cvt_pk_bf16_f32 v44, v48, v50
	global_store_dwordx4 v[46:47], v[42:45], off offset:1024
	global_load_dwordx4 v[42:45], v[84:85], off offset:16
	s_nop 0
	global_load_dwordx4 v[46:49], v[84:85], off
	global_load_dwordx4 v[50:53], v[86:87], off offset:16
	global_load_dwordx4 v[54:57], v[86:87], off
	global_load_dwordx4 v[58:61], v[84:85], off offset:2064
	global_load_dwordx4 v[62:65], v[84:85], off offset:2048
	global_load_dwordx4 v[66:69], v[86:87], off offset:2064
	global_load_dwordx4 v[70:73], v[86:87], off offset:2048
	v_lshlrev_b32_e32 v78, 16, v38
	v_and_b32_e32 v38, 0xffff0000, v38
	v_add_f32_e32 v0, 0, v78
	v_lshlrev_b32_e32 v79, 16, v39
	v_add_f32_e32 v0, v0, v38
	v_and_b32_e32 v39, 0xffff0000, v39
	v_add_f32_e32 v0, v0, v79
	v_add_f32_e32 v0, v0, v39
	v_lshlrev_b32_e32 v80, 16, v40
	v_and_b32_e32 v40, 0xffff0000, v40
	v_add_f32_e32 v0, v0, v80
	v_lshlrev_b32_e32 v81, 16, v41
	v_add_f32_e32 v0, v0, v40
	v_and_b32_e32 v41, 0xffff0000, v41
	v_add_f32_e32 v0, v0, v81
	v_lshlrev_b32_e32 v74, 16, v34
	v_add_f32_e32 v0, v0, v41
	v_and_b32_e32 v76, 0xffff0000, v34
	v_add_f32_e32 v0, v0, v74
	v_add_f32_e32 v0, v0, v76
	v_and_b32_e32 v34, 0xffff0000, v35
	v_lshlrev_b32_e32 v35, 16, v35
	v_add_f32_e32 v0, v0, v35
	v_lshlrev_b32_e32 v95, 16, v36
	v_add_f32_e32 v0, v0, v34
	v_and_b32_e32 v94, 0xffff0000, v36
	v_add_f32_e32 v0, v0, v95
	v_lshlrev_b32_e32 v93, 16, v37
	v_add_f32_e32 v0, v0, v94
	v_and_b32_e32 v92, 0xffff0000, v37
	v_add_f32_e32 v0, v0, v93
	v_add_f32_e32 v0, v0, v92
	s_nop 1
	v_add_f32_dpp v0, v0, v0 quad_perm:[1,0,3,2] row_mask:0xf bank_mask:0xf bound_ctrl:1
	s_nop 1
	v_add_f32_dpp v0, v0, v0 quad_perm:[2,3,0,1] row_mask:0xf bank_mask:0xf bound_ctrl:1
	s_nop 1
	v_add_f32_dpp v0, v0, v0 row_half_mirror row_mask:0xf bank_mask:0xf bound_ctrl:1
	s_nop 1
	v_add_f32_dpp v0, v0, v0 row_mirror row_mask:0xf bank_mask:0xf bound_ctrl:1
	s_nop 0
	v_readlane_b32 s2, v0, 16
	v_readlane_b32 s3, v0, 48
	v_readlane_b32 s0, v0, 0
	v_readlane_b32 s1, v0, 32
	v_mov_b32_e32 v36, s2
	v_mov_b32_e32 v37, s3
	v_pk_add_f32 v[36:37], s[0:1], v[36:37]
	s_nop 0
	v_add_f32_e32 v75, v36, v37
	v_mul_f32_e32 v0, 0x3a800000, v75
	v_pk_add_f32 v[36:37], v[78:79], v[0:1] op_sel_hi:[1,0] neg_lo:[0,1] neg_hi:[0,1]
	v_pk_add_f32 v[38:39], v[38:39], v[0:1] op_sel_hi:[1,0] neg_lo:[0,1] neg_hi:[0,1]
	v_pk_mul_f32 v[78:79], v[36:37], v[36:37]
	v_pk_mul_f32 v[96:97], v[38:39], v[38:39]
	v_pk_add_f32 v[80:81], v[80:81], v[0:1] op_sel_hi:[1,0] neg_lo:[0,1] neg_hi:[0,1]
	v_add_f32_e32 v77, v78, v96
	v_add_f32_e32 v77, v79, v77
	v_pk_mul_f32 v[98:99], v[80:81], v[80:81]
	v_pk_add_f32 v[40:41], v[40:41], v[0:1] op_sel_hi:[1,0] neg_lo:[0,1] neg_hi:[0,1]
	v_add_f32_e32 v77, v97, v77
	v_pk_mul_f32 v[100:101], v[40:41], v[40:41]
	v_add_f32_e32 v77, v98, v77
	v_add_f32_e32 v77, v100, v77
	v_add_f32_e32 v77, v99, v77
	v_add_f32_e32 v77, v101, v77
	v_fmac_f32_e32 v74, 0xba800000, v75
	v_fmac_f32_e32 v77, v74, v74
	v_fmac_f32_e32 v76, 0xba800000, v75
	v_pk_add_f32 v[78:79], v[34:35], v[0:1] op_sel_hi:[1,0] neg_lo:[0,1] neg_hi:[0,1]
	v_fmac_f32_e32 v77, v76, v76
	v_pk_mul_f32 v[34:35], v[78:79], v[78:79]
	v_pk_add_f32 v[94:95], v[94:95], v[0:1] op_sel_hi:[1,0] neg_lo:[0,1] neg_hi:[0,1]
	v_add_f32_e32 v35, v35, v77
	v_add_f32_e32 v75, v34, v35
	v_pk_mul_f32 v[34:35], v[94:95], v[94:95]
	v_pk_add_f32 v[92:93], v[92:93], v[0:1] op_sel_hi:[1,0] neg_lo:[0,1] neg_hi:[0,1]
	v_add_f32_e32 v35, v35, v75
	v_add_f32_e32 v75, v34, v35
	v_pk_mul_f32 v[34:35], v[92:93], v[92:93]
	s_waitcnt vmcnt(4)
	v_mov_b32_e32 v96, v54
	v_add_f32_e32 v0, v35, v75
	v_add_f32_e32 v0, v34, v0
	v_mov_b32_e32 v97, v56
	v_mov_b32_e32 v56, v55
	v_add_f32_dpp v0, v0, v0 quad_perm:[1,0,3,2] row_mask:0xf bank_mask:0xf bound_ctrl:1
	v_mov_b32_e32 v77, v78
	s_nop 0
	v_add_f32_dpp v0, v0, v0 quad_perm:[2,3,0,1] row_mask:0xf bank_mask:0xf bound_ctrl:1
	s_nop 1
	v_add_f32_dpp v0, v0, v0 row_half_mirror row_mask:0xf bank_mask:0xf bound_ctrl:1
	s_nop 1
	v_add_f32_dpp v0, v0, v0 row_mirror row_mask:0xf bank_mask:0xf bound_ctrl:1
	s_nop 0
	v_readlane_b32 s2, v0, 16
	v_readlane_b32 s3, v0, 48
	v_readlane_b32 s0, v0, 0
	v_readlane_b32 s1, v0, 32
	v_mov_b32_e32 v34, s2
	v_mov_b32_e32 v35, s3
	v_pk_add_f32 v[34:35], s[0:1], v[34:35]
	s_nop 0
	v_add_f32_e32 v0, v34, v35
	v_fmamk_f32 v0, v0, 0x3a800000, v216
	v_mul_f32_e32 v34, 0x4f800000, v0
	v_cmp_gt_f32_e32 vcc, s60, v0
	v_mov_b32_e32 v35, v48
	s_nop 0
	v_cndmask_b32_e32 v0, v0, v34, vcc
	v_sqrt_f32_e32 v75, v0
	v_mov_b32_e32 v34, v46
	v_add_u32_e32 v46, -1, v75
	v_fma_f32 v48, -v46, v75, v0
	v_cmp_ge_f32_e64 s[2:3], 0, v48
	v_add_u32_e32 v48, 1, v75
	v_fma_f32 v54, -v48, v75, v0
	v_cndmask_b32_e64 v46, v75, v46, s[2:3]
	v_cmp_lt_f32_e64 s[2:3], 0, v54
	s_nop 1
	v_cndmask_b32_e64 v46, v46, v48, s[2:3]
	v_mul_f32_e32 v48, 0x37800000, v46
	v_cndmask_b32_e32 v46, v46, v48, vcc
	v_cmp_class_f32_e32 vcc, v0, v217
	v_mov_b32_e32 v48, v47
	s_nop 0
	v_cndmask_b32_e32 v0, v46, v0, vcc
	v_div_scale_f32 v46, s[0:1], v0, v0, 1.0
	v_rcp_f32_e32 v54, v46
	s_nop 0
	v_fma_f32 v47, -v46, v54, 1.0
	v_fmac_f32_e32 v54, v47, v54
	v_div_scale_f32 v47, vcc, 1.0, v0, 1.0
	v_mul_f32_e32 v55, v47, v54
	v_fma_f32 v75, -v46, v55, v47
	v_fmac_f32_e32 v55, v75, v54
	v_fma_f32 v46, -v46, v55, v47
	v_div_fmas_f32 v46, v46, v54, v55
	v_div_fixup_f32 v0, v46, v0, 1.0
	v_pk_mul_f32 v[36:37], v[36:37], v[0:1] op_sel_hi:[1,0]
	v_mov_b32_e32 v47, v44
	v_pk_fma_f32 v[34:35], v[34:35], v[36:37], v[96:97]
	v_pk_mul_f32 v[36:37], v[38:39], v[0:1] op_sel_hi:[1,0]
	v_pk_mul_f32 v[40:41], v[40:41], v[0:1] op_sel_hi:[1,0]
	v_pk_fma_f32 v[36:37], v[48:49], v[36:37], v[56:57]
	v_mov_b32_e32 v49, v52
	v_mov_b32_e32 v44, v43
	v_mov_b32_e32 v52, v51
	v_pk_mul_f32 v[38:39], v[80:81], v[0:1] op_sel_hi:[1,0]
	v_mov_b32_e32 v46, v42
	v_mov_b32_e32 v48, v50
	v_pk_fma_f32 v[40:41], v[44:45], v[40:41], v[52:53]
	v_pk_fma_f32 v[38:39], v[46:47], v[38:39], v[48:49]
	v_cvt_pk_bf16_f32 v35, v35, v37
	v_cvt_pk_bf16_f32 v37, v39, v41
	v_cvt_pk_bf16_f32 v34, v34, v36
	v_cvt_pk_bf16_f32 v36, v38, v40
	v_lshl_add_u64 v[38:39], v[88:89], 0, s[20:21]
	v_mov_b32_e32 v75, v79
	global_store_dwordx4 v[38:39], v[34:37], off
	s_waitcnt vmcnt(1)
	v_mov_b32_e32 v40, v70
	v_mov_b32_e32 v41, v72
	v_pk_mul_f32 v[34:35], v[74:75], v[0:1] op_sel_hi:[1,0]
	v_mov_b32_e32 v36, v62
	v_mov_b32_e32 v37, v64
	v_pk_fma_f32 v[34:35], v[36:37], v[34:35], v[40:41]
	v_mov_b32_e32 v40, v95
	v_mov_b32_e32 v41, v93
	v_pk_mul_f32 v[40:41], v[40:41], v[0:1] op_sel_hi:[1,0]
	v_mov_b32_e32 v42, v58
	v_mov_b32_e32 v43, v60
	v_mov_b32_e32 v44, v66
	v_mov_b32_e32 v45, v68
	v_mov_b32_e32 v95, v92
	v_pk_mul_f32 v[36:37], v[76:77], v[0:1] op_sel_hi:[1,0]
	v_mov_b32_e32 v64, v63
	v_mov_b32_e32 v72, v71
	v_pk_fma_f32 v[40:41], v[40:41], v[42:43], v[44:45]
	v_pk_mul_f32 v[42:43], v[94:95], v[0:1] op_sel_hi:[1,0]
	v_mov_b32_e32 v60, v59
	v_mov_b32_e32 v68, v67
	v_pk_fma_f32 v[36:37], v[64:65], v[36:37], v[72:73]
	v_pk_fma_f32 v[42:43], v[42:43], v[60:61], v[68:69]
	v_cvt_pk_bf16_f32 v35, v35, v37
	v_cvt_pk_bf16_f32 v37, v41, v43
	v_cvt_pk_bf16_f32 v34, v34, v36
	v_cvt_pk_bf16_f32 v36, v40, v42
	global_store_dwordx4 v[38:39], v[34:37], off offset:1024
	global_load_dwordx4 v[34:37], v[84:85], off offset:16
	s_nop 0
	global_load_dwordx4 v[38:41], v[84:85], off
	global_load_dwordx4 v[42:45], v[86:87], off offset:16
	global_load_dwordx4 v[46:49], v[86:87], off
	global_load_dwordx4 v[50:53], v[84:85], off offset:2064
	global_load_dwordx4 v[54:57], v[84:85], off offset:2048
	global_load_dwordx4 v[58:61], v[86:87], off offset:2064
	global_load_dwordx4 v[62:65], v[86:87], off offset:2048
	v_lshlrev_b32_e32 v70, 16, v30
	v_and_b32_e32 v30, 0xffff0000, v30
	v_add_f32_e32 v0, 0, v70
	v_lshlrev_b32_e32 v71, 16, v31
	v_add_f32_e32 v0, v0, v30
	v_and_b32_e32 v31, 0xffff0000, v31
	v_add_f32_e32 v0, v0, v71
	v_add_f32_e32 v0, v0, v31
	v_lshlrev_b32_e32 v72, 16, v32
	v_and_b32_e32 v32, 0xffff0000, v32
	v_add_f32_e32 v0, v0, v72
	v_lshlrev_b32_e32 v73, 16, v33
	v_add_f32_e32 v0, v0, v32
	v_and_b32_e32 v33, 0xffff0000, v33
	v_add_f32_e32 v0, v0, v73
	v_lshlrev_b32_e32 v66, 16, v26
	v_add_f32_e32 v0, v0, v33
	v_and_b32_e32 v68, 0xffff0000, v26
	v_add_f32_e32 v0, v0, v66
	v_add_f32_e32 v0, v0, v68
	v_and_b32_e32 v26, 0xffff0000, v27
	v_lshlrev_b32_e32 v27, 16, v27
	v_add_f32_e32 v0, v0, v27
	v_lshlrev_b32_e32 v77, 16, v28
	v_add_f32_e32 v0, v0, v26
	v_and_b32_e32 v76, 0xffff0000, v28
	v_add_f32_e32 v0, v0, v77
	v_lshlrev_b32_e32 v75, 16, v29
	v_add_f32_e32 v0, v0, v76
	v_and_b32_e32 v74, 0xffff0000, v29
	v_add_f32_e32 v0, v0, v75
	v_add_f32_e32 v0, v0, v74
	s_nop 1
	v_add_f32_dpp v0, v0, v0 quad_perm:[1,0,3,2] row_mask:0xf bank_mask:0xf bound_ctrl:1
	s_nop 1
	v_add_f32_dpp v0, v0, v0 quad_perm:[2,3,0,1] row_mask:0xf bank_mask:0xf bound_ctrl:1
	s_nop 1
	v_add_f32_dpp v0, v0, v0 row_half_mirror row_mask:0xf bank_mask:0xf bound_ctrl:1
	s_nop 1
	v_add_f32_dpp v0, v0, v0 row_mirror row_mask:0xf bank_mask:0xf bound_ctrl:1
	s_nop 0
	v_readlane_b32 s2, v0, 16
	v_readlane_b32 s3, v0, 48
	v_readlane_b32 s0, v0, 0
	v_readlane_b32 s1, v0, 32
	v_mov_b32_e32 v28, s2
	v_mov_b32_e32 v29, s3
	v_pk_add_f32 v[28:29], s[0:1], v[28:29]
	s_nop 0
	v_add_f32_e32 v67, v28, v29
	v_mul_f32_e32 v0, 0x3a800000, v67
	v_pk_add_f32 v[28:29], v[70:71], v[0:1] op_sel_hi:[1,0] neg_lo:[0,1] neg_hi:[0,1]
	v_pk_add_f32 v[30:31], v[30:31], v[0:1] op_sel_hi:[1,0] neg_lo:[0,1] neg_hi:[0,1]
	v_pk_mul_f32 v[70:71], v[28:29], v[28:29]
	v_pk_mul_f32 v[78:79], v[30:31], v[30:31]
	v_pk_add_f32 v[72:73], v[72:73], v[0:1] op_sel_hi:[1,0] neg_lo:[0,1] neg_hi:[0,1]
	v_add_f32_e32 v69, v70, v78
	v_add_f32_e32 v69, v71, v69
	v_pk_mul_f32 v[80:81], v[72:73], v[72:73]
	v_pk_add_f32 v[32:33], v[32:33], v[0:1] op_sel_hi:[1,0] neg_lo:[0,1] neg_hi:[0,1]
	v_add_f32_e32 v69, v79, v69
	v_pk_mul_f32 v[92:93], v[32:33], v[32:33]
	v_add_f32_e32 v69, v80, v69
	v_add_f32_e32 v69, v92, v69
	v_add_f32_e32 v69, v81, v69
	v_add_f32_e32 v69, v93, v69
	v_fmac_f32_e32 v66, 0xba800000, v67
	v_fmac_f32_e32 v69, v66, v66
	v_fmac_f32_e32 v68, 0xba800000, v67
	v_pk_add_f32 v[70:71], v[26:27], v[0:1] op_sel_hi:[1,0] neg_lo:[0,1] neg_hi:[0,1]
	v_fmac_f32_e32 v69, v68, v68
	v_pk_mul_f32 v[26:27], v[70:71], v[70:71]
	v_pk_add_f32 v[76:77], v[76:77], v[0:1] op_sel_hi:[1,0] neg_lo:[0,1] neg_hi:[0,1]
	v_add_f32_e32 v27, v27, v69
	v_add_f32_e32 v67, v26, v27
	v_pk_mul_f32 v[26:27], v[76:77], v[76:77]
	v_pk_add_f32 v[74:75], v[74:75], v[0:1] op_sel_hi:[1,0] neg_lo:[0,1] neg_hi:[0,1]
	v_add_f32_e32 v27, v27, v67
	v_add_f32_e32 v67, v26, v27
	v_pk_mul_f32 v[26:27], v[74:75], v[74:75]
	s_waitcnt vmcnt(4)
	v_mov_b32_e32 v78, v46
	v_add_f32_e32 v0, v27, v67
	v_add_f32_e32 v0, v26, v0
	v_mov_b32_e32 v79, v48
	v_mov_b32_e32 v48, v47
	v_add_f32_dpp v0, v0, v0 quad_perm:[1,0,3,2] row_mask:0xf bank_mask:0xf bound_ctrl:1
	v_mov_b32_e32 v69, v70
	s_nop 0
	v_add_f32_dpp v0, v0, v0 quad_perm:[2,3,0,1] row_mask:0xf bank_mask:0xf bound_ctrl:1
	s_nop 1
	v_add_f32_dpp v0, v0, v0 row_half_mirror row_mask:0xf bank_mask:0xf bound_ctrl:1
	s_nop 1
	v_add_f32_dpp v0, v0, v0 row_mirror row_mask:0xf bank_mask:0xf bound_ctrl:1
	s_nop 0
	v_readlane_b32 s2, v0, 16
	v_readlane_b32 s3, v0, 48
	v_readlane_b32 s0, v0, 0
	v_readlane_b32 s1, v0, 32
	v_mov_b32_e32 v26, s2
	v_mov_b32_e32 v27, s3
	v_pk_add_f32 v[26:27], s[0:1], v[26:27]
	s_nop 0
	v_add_f32_e32 v0, v26, v27
	v_fmamk_f32 v0, v0, 0x3a800000, v216
	v_mul_f32_e32 v26, 0x4f800000, v0
	v_cmp_gt_f32_e32 vcc, s60, v0
	v_mov_b32_e32 v27, v40
	s_nop 0
	v_cndmask_b32_e32 v0, v0, v26, vcc
	v_sqrt_f32_e32 v67, v0
	v_mov_b32_e32 v26, v38
	v_add_u32_e32 v38, -1, v67
	v_fma_f32 v40, -v38, v67, v0
	v_cmp_ge_f32_e64 s[2:3], 0, v40
	v_add_u32_e32 v40, 1, v67
	v_fma_f32 v46, -v40, v67, v0
	v_cndmask_b32_e64 v38, v67, v38, s[2:3]
	v_cmp_lt_f32_e64 s[2:3], 0, v46
	s_nop 1
	v_cndmask_b32_e64 v38, v38, v40, s[2:3]
	v_mul_f32_e32 v40, 0x37800000, v38
	v_cndmask_b32_e32 v38, v38, v40, vcc
	v_cmp_class_f32_e32 vcc, v0, v217
	v_mov_b32_e32 v40, v39
	s_nop 0
	v_cndmask_b32_e32 v0, v38, v0, vcc
	v_div_scale_f32 v38, s[0:1], v0, v0, 1.0
	v_rcp_f32_e32 v46, v38
	s_nop 0
	v_fma_f32 v39, -v38, v46, 1.0
	v_fmac_f32_e32 v46, v39, v46
	v_div_scale_f32 v39, vcc, 1.0, v0, 1.0
	v_mul_f32_e32 v47, v39, v46
	v_fma_f32 v67, -v38, v47, v39
	v_fmac_f32_e32 v47, v67, v46
	v_fma_f32 v38, -v38, v47, v39
	v_div_fmas_f32 v38, v38, v46, v47
	v_div_fixup_f32 v0, v38, v0, 1.0
	v_pk_mul_f32 v[28:29], v[28:29], v[0:1] op_sel_hi:[1,0]
	v_mov_b32_e32 v39, v36
	v_pk_fma_f32 v[26:27], v[26:27], v[28:29], v[78:79]
	v_pk_mul_f32 v[28:29], v[30:31], v[0:1] op_sel_hi:[1,0]
	v_pk_mul_f32 v[32:33], v[32:33], v[0:1] op_sel_hi:[1,0]
	v_pk_fma_f32 v[28:29], v[40:41], v[28:29], v[48:49]
	v_mov_b32_e32 v41, v44
	v_mov_b32_e32 v36, v35
	v_mov_b32_e32 v44, v43
	v_pk_mul_f32 v[30:31], v[72:73], v[0:1] op_sel_hi:[1,0]
	v_mov_b32_e32 v38, v34
	v_mov_b32_e32 v40, v42
	v_pk_fma_f32 v[32:33], v[36:37], v[32:33], v[44:45]
	v_pk_fma_f32 v[30:31], v[38:39], v[30:31], v[40:41]
	v_cvt_pk_bf16_f32 v27, v27, v29
	v_cvt_pk_bf16_f32 v29, v31, v33
	v_cvt_pk_bf16_f32 v26, v26, v28
	v_cvt_pk_bf16_f32 v28, v30, v32
	v_lshl_add_u64 v[30:31], v[88:89], 0, s[24:25]
	v_mov_b32_e32 v67, v71
	global_store_dwordx4 v[30:31], v[26:29], off
	s_waitcnt vmcnt(1)
	v_mov_b32_e32 v32, v62
	v_mov_b32_e32 v33, v64
	v_pk_mul_f32 v[26:27], v[66:67], v[0:1] op_sel_hi:[1,0]
	v_mov_b32_e32 v28, v54
	v_mov_b32_e32 v29, v56
	v_pk_fma_f32 v[26:27], v[28:29], v[26:27], v[32:33]
	v_mov_b32_e32 v32, v77
	v_mov_b32_e32 v33, v75
	v_pk_mul_f32 v[32:33], v[32:33], v[0:1] op_sel_hi:[1,0]
	v_mov_b32_e32 v34, v50
	v_mov_b32_e32 v35, v52
	v_mov_b32_e32 v36, v58
	v_mov_b32_e32 v37, v60
	v_mov_b32_e32 v77, v74
	v_pk_mul_f32 v[28:29], v[68:69], v[0:1] op_sel_hi:[1,0]
	v_mov_b32_e32 v56, v55
	v_mov_b32_e32 v64, v63
	v_pk_fma_f32 v[32:33], v[32:33], v[34:35], v[36:37]
	v_pk_mul_f32 v[34:35], v[76:77], v[0:1] op_sel_hi:[1,0]
	v_mov_b32_e32 v52, v51
	v_mov_b32_e32 v60, v59
	v_pk_fma_f32 v[28:29], v[56:57], v[28:29], v[64:65]
	v_pk_fma_f32 v[34:35], v[34:35], v[52:53], v[60:61]
	v_cvt_pk_bf16_f32 v27, v27, v29
	v_cvt_pk_bf16_f32 v29, v33, v35
	v_cvt_pk_bf16_f32 v26, v26, v28
	v_cvt_pk_bf16_f32 v28, v32, v34
	global_store_dwordx4 v[30:31], v[26:29], off offset:1024
	global_load_dwordx4 v[26:29], v[84:85], off offset:16
	s_nop 0
	global_load_dwordx4 v[30:33], v[84:85], off
	global_load_dwordx4 v[34:37], v[86:87], off offset:16
	global_load_dwordx4 v[38:41], v[86:87], off
	global_load_dwordx4 v[42:45], v[84:85], off offset:2064
	global_load_dwordx4 v[46:49], v[84:85], off offset:2048
	global_load_dwordx4 v[50:53], v[86:87], off offset:2064
	global_load_dwordx4 v[54:57], v[86:87], off offset:2048
	v_lshlrev_b32_e32 v62, 16, v22
	v_and_b32_e32 v22, 0xffff0000, v22
	v_add_f32_e32 v0, 0, v62
	v_lshlrev_b32_e32 v63, 16, v23
	v_add_f32_e32 v0, v0, v22
	v_and_b32_e32 v23, 0xffff0000, v23
	v_add_f32_e32 v0, v0, v63
	v_add_f32_e32 v0, v0, v23
	v_lshlrev_b32_e32 v64, 16, v24
	v_and_b32_e32 v24, 0xffff0000, v24
	v_add_f32_e32 v0, v0, v64
	v_lshlrev_b32_e32 v65, 16, v25
	v_add_f32_e32 v0, v0, v24
	v_and_b32_e32 v25, 0xffff0000, v25
	v_add_f32_e32 v0, v0, v65
	v_lshlrev_b32_e32 v58, 16, v18
	v_add_f32_e32 v0, v0, v25
	v_and_b32_e32 v60, 0xffff0000, v18
	v_add_f32_e32 v0, v0, v58
	v_add_f32_e32 v0, v0, v60
	v_and_b32_e32 v18, 0xffff0000, v19
	v_lshlrev_b32_e32 v19, 16, v19
	v_add_f32_e32 v0, v0, v19
	v_lshlrev_b32_e32 v69, 16, v20
	v_add_f32_e32 v0, v0, v18
	v_and_b32_e32 v68, 0xffff0000, v20
	v_add_f32_e32 v0, v0, v69
	v_lshlrev_b32_e32 v67, 16, v21
	v_add_f32_e32 v0, v0, v68
	v_and_b32_e32 v66, 0xffff0000, v21
	v_add_f32_e32 v0, v0, v67
	v_add_f32_e32 v0, v0, v66
	s_nop 1
	v_add_f32_dpp v0, v0, v0 quad_perm:[1,0,3,2] row_mask:0xf bank_mask:0xf bound_ctrl:1
	s_nop 1
	v_add_f32_dpp v0, v0, v0 quad_perm:[2,3,0,1] row_mask:0xf bank_mask:0xf bound_ctrl:1
	s_nop 1
	v_add_f32_dpp v0, v0, v0 row_half_mirror row_mask:0xf bank_mask:0xf bound_ctrl:1
	s_nop 1
	v_add_f32_dpp v0, v0, v0 row_mirror row_mask:0xf bank_mask:0xf bound_ctrl:1
	s_nop 0
	v_readlane_b32 s2, v0, 16
	v_readlane_b32 s3, v0, 48
	v_readlane_b32 s0, v0, 0
	v_readlane_b32 s1, v0, 32
	v_mov_b32_e32 v20, s2
	v_mov_b32_e32 v21, s3
	v_pk_add_f32 v[20:21], s[0:1], v[20:21]
	s_nop 0
	v_add_f32_e32 v59, v20, v21
	v_mul_f32_e32 v0, 0x3a800000, v59
	v_pk_add_f32 v[20:21], v[62:63], v[0:1] op_sel_hi:[1,0] neg_lo:[0,1] neg_hi:[0,1]
	v_pk_add_f32 v[22:23], v[22:23], v[0:1] op_sel_hi:[1,0] neg_lo:[0,1] neg_hi:[0,1]
	v_pk_mul_f32 v[62:63], v[20:21], v[20:21]
	v_pk_mul_f32 v[70:71], v[22:23], v[22:23]
	v_pk_add_f32 v[64:65], v[64:65], v[0:1] op_sel_hi:[1,0] neg_lo:[0,1] neg_hi:[0,1]
	v_add_f32_e32 v61, v62, v70
	v_add_f32_e32 v61, v63, v61
	v_pk_mul_f32 v[72:73], v[64:65], v[64:65]
	v_pk_add_f32 v[24:25], v[24:25], v[0:1] op_sel_hi:[1,0] neg_lo:[0,1] neg_hi:[0,1]
	v_add_f32_e32 v61, v71, v61
	v_pk_mul_f32 v[74:75], v[24:25], v[24:25]
	v_add_f32_e32 v61, v72, v61
	v_add_f32_e32 v61, v74, v61
	v_add_f32_e32 v61, v73, v61
	v_add_f32_e32 v61, v75, v61
	v_fmac_f32_e32 v58, 0xba800000, v59
	v_fmac_f32_e32 v61, v58, v58
	v_fmac_f32_e32 v60, 0xba800000, v59
	v_pk_add_f32 v[62:63], v[18:19], v[0:1] op_sel_hi:[1,0] neg_lo:[0,1] neg_hi:[0,1]
	v_fmac_f32_e32 v61, v60, v60
	v_pk_mul_f32 v[18:19], v[62:63], v[62:63]
	v_pk_add_f32 v[68:69], v[68:69], v[0:1] op_sel_hi:[1,0] neg_lo:[0,1] neg_hi:[0,1]
	v_add_f32_e32 v19, v19, v61
	v_add_f32_e32 v59, v18, v19
	v_pk_mul_f32 v[18:19], v[68:69], v[68:69]
	v_pk_add_f32 v[66:67], v[66:67], v[0:1] op_sel_hi:[1,0] neg_lo:[0,1] neg_hi:[0,1]
	v_add_f32_e32 v19, v19, v59
	v_add_f32_e32 v59, v18, v19
	v_pk_mul_f32 v[18:19], v[66:67], v[66:67]
	s_waitcnt vmcnt(4)
	v_mov_b32_e32 v70, v38
	v_add_f32_e32 v0, v19, v59
	v_add_f32_e32 v0, v18, v0
	v_mov_b32_e32 v71, v40
	v_mov_b32_e32 v40, v39
	v_add_f32_dpp v0, v0, v0 quad_perm:[1,0,3,2] row_mask:0xf bank_mask:0xf bound_ctrl:1
	v_mov_b32_e32 v61, v62
	s_nop 0
	v_add_f32_dpp v0, v0, v0 quad_perm:[2,3,0,1] row_mask:0xf bank_mask:0xf bound_ctrl:1
	s_nop 1
	v_add_f32_dpp v0, v0, v0 row_half_mirror row_mask:0xf bank_mask:0xf bound_ctrl:1
	s_nop 1
	v_add_f32_dpp v0, v0, v0 row_mirror row_mask:0xf bank_mask:0xf bound_ctrl:1
	s_nop 0
	v_readlane_b32 s2, v0, 16
	v_readlane_b32 s3, v0, 48
	v_readlane_b32 s0, v0, 0
	v_readlane_b32 s1, v0, 32
	v_mov_b32_e32 v18, s2
	v_mov_b32_e32 v19, s3
	v_pk_add_f32 v[18:19], s[0:1], v[18:19]
	s_nop 0
	v_add_f32_e32 v0, v18, v19
	v_fmamk_f32 v0, v0, 0x3a800000, v216
	v_mul_f32_e32 v18, 0x4f800000, v0
	v_cmp_gt_f32_e32 vcc, s60, v0
	v_mov_b32_e32 v19, v32
	s_nop 0
	v_cndmask_b32_e32 v0, v0, v18, vcc
	v_sqrt_f32_e32 v59, v0
	v_mov_b32_e32 v18, v30
	v_add_u32_e32 v30, -1, v59
	v_fma_f32 v32, -v30, v59, v0
	v_cmp_ge_f32_e64 s[2:3], 0, v32
	v_add_u32_e32 v32, 1, v59
	v_fma_f32 v38, -v32, v59, v0
	v_cndmask_b32_e64 v30, v59, v30, s[2:3]
	v_cmp_lt_f32_e64 s[2:3], 0, v38
	s_nop 1
	v_cndmask_b32_e64 v30, v30, v32, s[2:3]
	v_mul_f32_e32 v32, 0x37800000, v30
	v_cndmask_b32_e32 v30, v30, v32, vcc
	v_cmp_class_f32_e32 vcc, v0, v217
	v_mov_b32_e32 v32, v31
	s_nop 0
	v_cndmask_b32_e32 v0, v30, v0, vcc
	v_div_scale_f32 v30, s[0:1], v0, v0, 1.0
	v_rcp_f32_e32 v38, v30
	s_nop 0
	v_fma_f32 v31, -v30, v38, 1.0
	v_fmac_f32_e32 v38, v31, v38
	v_div_scale_f32 v31, vcc, 1.0, v0, 1.0
	v_mul_f32_e32 v39, v31, v38
	v_fma_f32 v59, -v30, v39, v31
	v_fmac_f32_e32 v39, v59, v38
	v_fma_f32 v30, -v30, v39, v31
	v_div_fmas_f32 v30, v30, v38, v39
	v_div_fixup_f32 v0, v30, v0, 1.0
	v_pk_mul_f32 v[20:21], v[20:21], v[0:1] op_sel_hi:[1,0]
	v_mov_b32_e32 v31, v28
	v_pk_fma_f32 v[18:19], v[18:19], v[20:21], v[70:71]
	v_pk_mul_f32 v[20:21], v[22:23], v[0:1] op_sel_hi:[1,0]
	v_pk_mul_f32 v[24:25], v[24:25], v[0:1] op_sel_hi:[1,0]
	v_pk_fma_f32 v[20:21], v[32:33], v[20:21], v[40:41]
	v_mov_b32_e32 v33, v36
	v_mov_b32_e32 v28, v27
	v_mov_b32_e32 v36, v35
	v_pk_mul_f32 v[22:23], v[64:65], v[0:1] op_sel_hi:[1,0]
	v_mov_b32_e32 v30, v26
	v_mov_b32_e32 v32, v34
	v_pk_fma_f32 v[24:25], v[28:29], v[24:25], v[36:37]
	v_pk_fma_f32 v[22:23], v[30:31], v[22:23], v[32:33]
	v_cvt_pk_bf16_f32 v19, v19, v21
	v_cvt_pk_bf16_f32 v21, v23, v25
	v_cvt_pk_bf16_f32 v18, v18, v20
	v_cvt_pk_bf16_f32 v20, v22, v24
	v_lshl_add_u64 v[22:23], v[88:89], 0, s[36:37]
	v_mov_b32_e32 v59, v63
	global_store_dwordx4 v[22:23], v[18:21], off
	s_waitcnt vmcnt(1)
	v_mov_b32_e32 v24, v54
	v_mov_b32_e32 v25, v56
	v_pk_mul_f32 v[18:19], v[58:59], v[0:1] op_sel_hi:[1,0]
	v_mov_b32_e32 v20, v46
	v_mov_b32_e32 v21, v48
	v_pk_fma_f32 v[18:19], v[20:21], v[18:19], v[24:25]
	v_mov_b32_e32 v24, v69
	v_mov_b32_e32 v25, v67
	v_pk_mul_f32 v[24:25], v[24:25], v[0:1] op_sel_hi:[1,0]
	v_mov_b32_e32 v26, v42
	v_mov_b32_e32 v27, v44
	v_mov_b32_e32 v28, v50
	v_mov_b32_e32 v29, v52
	v_mov_b32_e32 v69, v66
	v_pk_mul_f32 v[20:21], v[60:61], v[0:1] op_sel_hi:[1,0]
	v_mov_b32_e32 v48, v47
	v_mov_b32_e32 v56, v55
	v_pk_fma_f32 v[24:25], v[24:25], v[26:27], v[28:29]
	v_pk_mul_f32 v[26:27], v[68:69], v[0:1] op_sel_hi:[1,0]
	v_mov_b32_e32 v44, v43
	v_mov_b32_e32 v52, v51
	v_pk_fma_f32 v[20:21], v[48:49], v[20:21], v[56:57]
	v_pk_fma_f32 v[26:27], v[26:27], v[44:45], v[52:53]
	v_cvt_pk_bf16_f32 v19, v19, v21
	v_cvt_pk_bf16_f32 v21, v25, v27
	v_cvt_pk_bf16_f32 v18, v18, v20
	v_cvt_pk_bf16_f32 v20, v24, v26
	global_store_dwordx4 v[22:23], v[18:21], off offset:1024
	global_load_dwordx4 v[18:21], v[84:85], off offset:16
	s_nop 0
	global_load_dwordx4 v[22:25], v[84:85], off
	global_load_dwordx4 v[26:29], v[86:87], off offset:16
	global_load_dwordx4 v[30:33], v[86:87], off
	global_load_dwordx4 v[34:37], v[84:85], off offset:2064
	global_load_dwordx4 v[38:41], v[84:85], off offset:2048
	global_load_dwordx4 v[42:45], v[86:87], off offset:2064
	global_load_dwordx4 v[46:49], v[86:87], off offset:2048
	v_lshlrev_b32_e32 v54, 16, v14
	v_and_b32_e32 v14, 0xffff0000, v14
	v_add_f32_e32 v0, 0, v54
	v_lshlrev_b32_e32 v55, 16, v15
	v_add_f32_e32 v0, v0, v14
	v_and_b32_e32 v15, 0xffff0000, v15
	v_add_f32_e32 v0, v0, v55
	v_add_f32_e32 v0, v0, v15
	v_lshlrev_b32_e32 v56, 16, v16
	v_and_b32_e32 v16, 0xffff0000, v16
	v_add_f32_e32 v0, v0, v56
	v_lshlrev_b32_e32 v57, 16, v17
	v_add_f32_e32 v0, v0, v16
	v_and_b32_e32 v17, 0xffff0000, v17
	v_add_f32_e32 v0, v0, v57
	v_lshlrev_b32_e32 v50, 16, v10
	v_add_f32_e32 v0, v0, v17
	v_and_b32_e32 v52, 0xffff0000, v10
	v_add_f32_e32 v0, v0, v50
	v_add_f32_e32 v0, v0, v52
	v_and_b32_e32 v10, 0xffff0000, v11
	v_lshlrev_b32_e32 v11, 16, v11
	v_add_f32_e32 v0, v0, v11
	v_lshlrev_b32_e32 v61, 16, v12
	v_add_f32_e32 v0, v0, v10
	v_and_b32_e32 v60, 0xffff0000, v12
	v_add_f32_e32 v0, v0, v61
	v_lshlrev_b32_e32 v59, 16, v13
	v_add_f32_e32 v0, v0, v60
	v_and_b32_e32 v58, 0xffff0000, v13
	v_add_f32_e32 v0, v0, v59
	v_add_f32_e32 v0, v0, v58
	s_nop 1
	v_add_f32_dpp v0, v0, v0 quad_perm:[1,0,3,2] row_mask:0xf bank_mask:0xf bound_ctrl:1
	s_nop 1
	v_add_f32_dpp v0, v0, v0 quad_perm:[2,3,0,1] row_mask:0xf bank_mask:0xf bound_ctrl:1
	s_nop 1
	v_add_f32_dpp v0, v0, v0 row_half_mirror row_mask:0xf bank_mask:0xf bound_ctrl:1
	s_nop 1
	v_add_f32_dpp v0, v0, v0 row_mirror row_mask:0xf bank_mask:0xf bound_ctrl:1
	s_nop 0
	v_readlane_b32 s2, v0, 16
	v_readlane_b32 s3, v0, 48
	v_readlane_b32 s0, v0, 0
	v_readlane_b32 s1, v0, 32
	v_mov_b32_e32 v12, s2
	v_mov_b32_e32 v13, s3
	v_pk_add_f32 v[12:13], s[0:1], v[12:13]
	s_nop 0
	v_add_f32_e32 v51, v12, v13
	v_mul_f32_e32 v0, 0x3a800000, v51
	v_pk_add_f32 v[12:13], v[54:55], v[0:1] op_sel_hi:[1,0] neg_lo:[0,1] neg_hi:[0,1]
	v_pk_add_f32 v[14:15], v[14:15], v[0:1] op_sel_hi:[1,0] neg_lo:[0,1] neg_hi:[0,1]
	v_pk_mul_f32 v[54:55], v[12:13], v[12:13]
	v_pk_mul_f32 v[62:63], v[14:15], v[14:15]
	v_pk_add_f32 v[56:57], v[56:57], v[0:1] op_sel_hi:[1,0] neg_lo:[0,1] neg_hi:[0,1]
	v_add_f32_e32 v53, v54, v62
	v_add_f32_e32 v53, v55, v53
	v_pk_mul_f32 v[64:65], v[56:57], v[56:57]
	v_pk_add_f32 v[16:17], v[16:17], v[0:1] op_sel_hi:[1,0] neg_lo:[0,1] neg_hi:[0,1]
	v_add_f32_e32 v53, v63, v53
	v_pk_mul_f32 v[66:67], v[16:17], v[16:17]
	v_add_f32_e32 v53, v64, v53
	v_add_f32_e32 v53, v66, v53
	v_add_f32_e32 v53, v65, v53
	v_add_f32_e32 v53, v67, v53
	v_fmac_f32_e32 v50, 0xba800000, v51
	v_fmac_f32_e32 v53, v50, v50
	v_fmac_f32_e32 v52, 0xba800000, v51
	v_pk_add_f32 v[54:55], v[10:11], v[0:1] op_sel_hi:[1,0] neg_lo:[0,1] neg_hi:[0,1]
	v_fmac_f32_e32 v53, v52, v52
	v_pk_mul_f32 v[10:11], v[54:55], v[54:55]
	v_pk_add_f32 v[60:61], v[60:61], v[0:1] op_sel_hi:[1,0] neg_lo:[0,1] neg_hi:[0,1]
	v_add_f32_e32 v11, v11, v53
	v_add_f32_e32 v51, v10, v11
	v_pk_mul_f32 v[10:11], v[60:61], v[60:61]
	v_pk_add_f32 v[58:59], v[58:59], v[0:1] op_sel_hi:[1,0] neg_lo:[0,1] neg_hi:[0,1]
	v_add_f32_e32 v11, v11, v51
	v_add_f32_e32 v51, v10, v11
	v_pk_mul_f32 v[10:11], v[58:59], v[58:59]
	s_waitcnt vmcnt(4)
	v_mov_b32_e32 v62, v30
	v_add_f32_e32 v0, v11, v51
	v_add_f32_e32 v0, v10, v0
	v_mov_b32_e32 v63, v32
	v_mov_b32_e32 v32, v31
	v_add_f32_dpp v0, v0, v0 quad_perm:[1,0,3,2] row_mask:0xf bank_mask:0xf bound_ctrl:1
	v_mov_b32_e32 v53, v54
	s_nop 0
	v_add_f32_dpp v0, v0, v0 quad_perm:[2,3,0,1] row_mask:0xf bank_mask:0xf bound_ctrl:1
	s_nop 1
	v_add_f32_dpp v0, v0, v0 row_half_mirror row_mask:0xf bank_mask:0xf bound_ctrl:1
	s_nop 1
	v_add_f32_dpp v0, v0, v0 row_mirror row_mask:0xf bank_mask:0xf bound_ctrl:1
	s_nop 0
	v_readlane_b32 s2, v0, 16
	v_readlane_b32 s3, v0, 48
	v_readlane_b32 s0, v0, 0
	v_readlane_b32 s1, v0, 32
	v_mov_b32_e32 v10, s2
	v_mov_b32_e32 v11, s3
	v_pk_add_f32 v[10:11], s[0:1], v[10:11]
	s_nop 0
	v_add_f32_e32 v0, v10, v11
	v_fmamk_f32 v0, v0, 0x3a800000, v216
	v_mul_f32_e32 v10, 0x4f800000, v0
	v_cmp_gt_f32_e32 vcc, s60, v0
	v_mov_b32_e32 v11, v24
	s_nop 0
	v_cndmask_b32_e32 v0, v0, v10, vcc
	v_sqrt_f32_e32 v51, v0
	v_mov_b32_e32 v10, v22
	v_add_u32_e32 v22, -1, v51
	v_fma_f32 v24, -v22, v51, v0
	v_cmp_ge_f32_e64 s[2:3], 0, v24
	v_add_u32_e32 v24, 1, v51
	v_fma_f32 v30, -v24, v51, v0
	v_cndmask_b32_e64 v22, v51, v22, s[2:3]
	v_cmp_lt_f32_e64 s[2:3], 0, v30
	s_nop 1
	v_cndmask_b32_e64 v22, v22, v24, s[2:3]
	v_mul_f32_e32 v24, 0x37800000, v22
	v_cndmask_b32_e32 v22, v22, v24, vcc
	v_cmp_class_f32_e32 vcc, v0, v217
	v_mov_b32_e32 v24, v23
	s_nop 0
	v_cndmask_b32_e32 v0, v22, v0, vcc
	v_div_scale_f32 v22, s[0:1], v0, v0, 1.0
	v_rcp_f32_e32 v30, v22
	s_nop 0
	v_fma_f32 v23, -v22, v30, 1.0
	v_fmac_f32_e32 v30, v23, v30
	v_div_scale_f32 v23, vcc, 1.0, v0, 1.0
	v_mul_f32_e32 v31, v23, v30
	v_fma_f32 v51, -v22, v31, v23
	v_fmac_f32_e32 v31, v51, v30
	v_fma_f32 v22, -v22, v31, v23
	v_div_fmas_f32 v22, v22, v30, v31
	v_div_fixup_f32 v0, v22, v0, 1.0
	v_pk_mul_f32 v[12:13], v[12:13], v[0:1] op_sel_hi:[1,0]
	v_mov_b32_e32 v23, v20
	v_pk_fma_f32 v[10:11], v[10:11], v[12:13], v[62:63]
	v_pk_mul_f32 v[12:13], v[14:15], v[0:1] op_sel_hi:[1,0]
	v_pk_mul_f32 v[16:17], v[16:17], v[0:1] op_sel_hi:[1,0]
	v_pk_fma_f32 v[12:13], v[24:25], v[12:13], v[32:33]
	v_mov_b32_e32 v25, v28
	v_mov_b32_e32 v20, v19
	v_mov_b32_e32 v28, v27
	v_pk_mul_f32 v[14:15], v[56:57], v[0:1] op_sel_hi:[1,0]
	v_mov_b32_e32 v22, v18
	v_mov_b32_e32 v24, v26
	v_pk_fma_f32 v[16:17], v[20:21], v[16:17], v[28:29]
	v_pk_fma_f32 v[14:15], v[22:23], v[14:15], v[24:25]
	v_cvt_pk_bf16_f32 v11, v11, v13
	v_cvt_pk_bf16_f32 v13, v15, v17
	v_cvt_pk_bf16_f32 v10, v10, v12
	v_cvt_pk_bf16_f32 v12, v14, v16
	v_lshl_add_u64 v[14:15], v[88:89], 0, s[16:17]
	v_mov_b32_e32 v51, v55
	global_store_dwordx4 v[14:15], v[10:13], off
	s_waitcnt vmcnt(1)
	v_mov_b32_e32 v16, v46
	v_mov_b32_e32 v17, v48
	v_pk_mul_f32 v[10:11], v[50:51], v[0:1] op_sel_hi:[1,0]
	v_mov_b32_e32 v12, v38
	v_mov_b32_e32 v13, v40
	v_pk_fma_f32 v[10:11], v[12:13], v[10:11], v[16:17]
	v_mov_b32_e32 v16, v61
	v_mov_b32_e32 v17, v59
	v_pk_mul_f32 v[16:17], v[16:17], v[0:1] op_sel_hi:[1,0]
	v_mov_b32_e32 v18, v34
	v_mov_b32_e32 v19, v36
	v_mov_b32_e32 v20, v42
	v_mov_b32_e32 v21, v44
	v_mov_b32_e32 v61, v58
	v_pk_mul_f32 v[12:13], v[52:53], v[0:1] op_sel_hi:[1,0]
	v_mov_b32_e32 v40, v39
	v_mov_b32_e32 v48, v47
	v_pk_fma_f32 v[16:17], v[16:17], v[18:19], v[20:21]
	v_pk_mul_f32 v[18:19], v[60:61], v[0:1] op_sel_hi:[1,0]
	v_mov_b32_e32 v36, v35
	v_mov_b32_e32 v44, v43
	v_pk_fma_f32 v[12:13], v[40:41], v[12:13], v[48:49]
	v_pk_fma_f32 v[18:19], v[18:19], v[36:37], v[44:45]
	v_cvt_pk_bf16_f32 v11, v11, v13
	v_cvt_pk_bf16_f32 v13, v17, v19
	v_cvt_pk_bf16_f32 v10, v10, v12
	v_cvt_pk_bf16_f32 v12, v16, v18
	global_store_dwordx4 v[14:15], v[10:13], off offset:1024
	global_load_dwordx4 v[10:13], v[84:85], off offset:16
	s_nop 0
	global_load_dwordx4 v[14:17], v[84:85], off
	global_load_dwordx4 v[18:21], v[86:87], off offset:16
	global_load_dwordx4 v[22:25], v[86:87], off
	global_load_dwordx4 v[26:29], v[84:85], off offset:2064
	global_load_dwordx4 v[30:33], v[84:85], off offset:2048
	global_load_dwordx4 v[34:37], v[86:87], off offset:2064
	global_load_dwordx4 v[38:41], v[86:87], off offset:2048
	v_lshlrev_b32_e32 v46, 16, v6
	v_and_b32_e32 v6, 0xffff0000, v6
	v_add_f32_e32 v0, 0, v46
	v_lshlrev_b32_e32 v47, 16, v7
	v_add_f32_e32 v0, v0, v6
	v_and_b32_e32 v7, 0xffff0000, v7
	v_add_f32_e32 v0, v0, v47
	v_add_f32_e32 v0, v0, v7
	v_lshlrev_b32_e32 v48, 16, v8
	v_and_b32_e32 v8, 0xffff0000, v8
	v_add_f32_e32 v0, v0, v48
	v_lshlrev_b32_e32 v49, 16, v9
	v_add_f32_e32 v0, v0, v8
	v_and_b32_e32 v9, 0xffff0000, v9
	v_add_f32_e32 v0, v0, v49
	v_lshlrev_b32_e32 v42, 16, v2
	v_add_f32_e32 v0, v0, v9
	v_and_b32_e32 v44, 0xffff0000, v2
	v_add_f32_e32 v0, v0, v42
	v_add_f32_e32 v0, v0, v44
	v_and_b32_e32 v2, 0xffff0000, v3
	v_lshlrev_b32_e32 v3, 16, v3
	v_add_f32_e32 v0, v0, v3
	v_lshlrev_b32_e32 v53, 16, v4
	v_add_f32_e32 v0, v0, v2
	v_and_b32_e32 v52, 0xffff0000, v4
	v_add_f32_e32 v0, v0, v53
	v_lshlrev_b32_e32 v51, 16, v5
	v_add_f32_e32 v0, v0, v52
	v_and_b32_e32 v50, 0xffff0000, v5
	v_add_f32_e32 v0, v0, v51
	v_add_f32_e32 v0, v0, v50
	s_nop 1
	v_add_f32_dpp v0, v0, v0 quad_perm:[1,0,3,2] row_mask:0xf bank_mask:0xf bound_ctrl:1
	s_nop 1
	v_add_f32_dpp v0, v0, v0 quad_perm:[2,3,0,1] row_mask:0xf bank_mask:0xf bound_ctrl:1
	s_nop 1
	v_add_f32_dpp v0, v0, v0 row_half_mirror row_mask:0xf bank_mask:0xf bound_ctrl:1
	s_nop 1
	v_add_f32_dpp v0, v0, v0 row_mirror row_mask:0xf bank_mask:0xf bound_ctrl:1
	s_nop 0
	v_readlane_b32 s2, v0, 16
	v_readlane_b32 s3, v0, 48
	v_readlane_b32 s0, v0, 0
	v_readlane_b32 s1, v0, 32
	v_mov_b32_e32 v4, s2
	v_mov_b32_e32 v5, s3
	v_pk_add_f32 v[4:5], s[0:1], v[4:5]
	s_nop 0
	v_add_f32_e32 v43, v4, v5
	v_mul_f32_e32 v0, 0x3a800000, v43
	v_pk_add_f32 v[4:5], v[46:47], v[0:1] op_sel_hi:[1,0] neg_lo:[0,1] neg_hi:[0,1]
	v_pk_add_f32 v[6:7], v[6:7], v[0:1] op_sel_hi:[1,0] neg_lo:[0,1] neg_hi:[0,1]
	v_pk_mul_f32 v[46:47], v[4:5], v[4:5]
	v_pk_mul_f32 v[54:55], v[6:7], v[6:7]
	v_pk_add_f32 v[48:49], v[48:49], v[0:1] op_sel_hi:[1,0] neg_lo:[0,1] neg_hi:[0,1]
	v_add_f32_e32 v45, v46, v54
	v_add_f32_e32 v45, v47, v45
	v_pk_mul_f32 v[56:57], v[48:49], v[48:49]
	v_pk_add_f32 v[8:9], v[8:9], v[0:1] op_sel_hi:[1,0] neg_lo:[0,1] neg_hi:[0,1]
	v_add_f32_e32 v45, v55, v45
	v_pk_mul_f32 v[58:59], v[8:9], v[8:9]
	v_add_f32_e32 v45, v56, v45
	v_add_f32_e32 v45, v58, v45
	v_add_f32_e32 v45, v57, v45
	v_add_f32_e32 v45, v59, v45
	v_fmac_f32_e32 v42, 0xba800000, v43
	v_fmac_f32_e32 v45, v42, v42
	v_fmac_f32_e32 v44, 0xba800000, v43
	v_pk_add_f32 v[46:47], v[2:3], v[0:1] op_sel_hi:[1,0] neg_lo:[0,1] neg_hi:[0,1]
	v_fmac_f32_e32 v45, v44, v44
	v_pk_mul_f32 v[2:3], v[46:47], v[46:47]
	v_pk_add_f32 v[52:53], v[52:53], v[0:1] op_sel_hi:[1,0] neg_lo:[0,1] neg_hi:[0,1]
	v_add_f32_e32 v3, v3, v45
	v_add_f32_e32 v43, v2, v3
	v_pk_mul_f32 v[2:3], v[52:53], v[52:53]
	v_pk_add_f32 v[50:51], v[50:51], v[0:1] op_sel_hi:[1,0] neg_lo:[0,1] neg_hi:[0,1]
	v_add_f32_e32 v3, v3, v43
	v_add_f32_e32 v43, v2, v3
	v_pk_mul_f32 v[2:3], v[50:51], v[50:51]
	s_waitcnt vmcnt(4)
	v_mov_b32_e32 v54, v22
	v_add_f32_e32 v0, v3, v43
	v_add_f32_e32 v0, v2, v0
	v_mov_b32_e32 v55, v24
	v_mov_b32_e32 v24, v23
	v_add_f32_dpp v0, v0, v0 quad_perm:[1,0,3,2] row_mask:0xf bank_mask:0xf bound_ctrl:1
	v_mov_b32_e32 v45, v46
	s_nop 0
	v_add_f32_dpp v0, v0, v0 quad_perm:[2,3,0,1] row_mask:0xf bank_mask:0xf bound_ctrl:1
	s_nop 1
	v_add_f32_dpp v0, v0, v0 row_half_mirror row_mask:0xf bank_mask:0xf bound_ctrl:1
	s_nop 1
	v_add_f32_dpp v0, v0, v0 row_mirror row_mask:0xf bank_mask:0xf bound_ctrl:1
	s_nop 0
	v_readlane_b32 s2, v0, 16
	v_readlane_b32 s3, v0, 48
	v_readlane_b32 s0, v0, 0
	v_readlane_b32 s1, v0, 32
	v_mov_b32_e32 v2, s2
	v_mov_b32_e32 v3, s3
	v_pk_add_f32 v[2:3], s[0:1], v[2:3]
	s_nop 0
	v_add_f32_e32 v0, v2, v3
	v_fmamk_f32 v0, v0, 0x3a800000, v216
	v_mul_f32_e32 v2, 0x4f800000, v0
	v_cmp_gt_f32_e32 vcc, s60, v0
	v_mov_b32_e32 v3, v16
	s_nop 0
	v_cndmask_b32_e32 v0, v0, v2, vcc
	v_sqrt_f32_e32 v43, v0
	v_mov_b32_e32 v2, v14
	v_add_u32_e32 v14, -1, v43
	v_fma_f32 v16, -v14, v43, v0
	v_cmp_ge_f32_e64 s[2:3], 0, v16
	v_add_u32_e32 v16, 1, v43
	v_fma_f32 v22, -v16, v43, v0
	v_cndmask_b32_e64 v14, v43, v14, s[2:3]
	v_cmp_lt_f32_e64 s[2:3], 0, v22
	s_nop 1
	v_cndmask_b32_e64 v14, v14, v16, s[2:3]
	v_mul_f32_e32 v16, 0x37800000, v14
	v_cndmask_b32_e32 v14, v14, v16, vcc
	v_cmp_class_f32_e32 vcc, v0, v217
	v_mov_b32_e32 v16, v15
	s_nop 0
	v_cndmask_b32_e32 v0, v14, v0, vcc
	v_div_scale_f32 v14, s[0:1], v0, v0, 1.0
	v_rcp_f32_e32 v22, v14
	s_nop 0
	v_fma_f32 v15, -v14, v22, 1.0
	v_fmac_f32_e32 v22, v15, v22
	v_div_scale_f32 v15, vcc, 1.0, v0, 1.0
	v_mul_f32_e32 v23, v15, v22
	v_fma_f32 v43, -v14, v23, v15
	v_fmac_f32_e32 v23, v43, v22
	v_fma_f32 v14, -v14, v23, v15
	v_div_fmas_f32 v14, v14, v22, v23
	v_div_fixup_f32 v0, v14, v0, 1.0
	v_pk_mul_f32 v[4:5], v[4:5], v[0:1] op_sel_hi:[1,0]
	v_mov_b32_e32 v15, v12
	v_pk_fma_f32 v[2:3], v[2:3], v[4:5], v[54:55]
	v_pk_mul_f32 v[4:5], v[6:7], v[0:1] op_sel_hi:[1,0]
	v_pk_mul_f32 v[8:9], v[8:9], v[0:1] op_sel_hi:[1,0]
	v_pk_fma_f32 v[4:5], v[16:17], v[4:5], v[24:25]
	v_mov_b32_e32 v17, v20
	v_mov_b32_e32 v12, v11
	v_mov_b32_e32 v20, v19
	v_pk_mul_f32 v[6:7], v[48:49], v[0:1] op_sel_hi:[1,0]
	v_mov_b32_e32 v14, v10
	v_mov_b32_e32 v16, v18
	v_pk_fma_f32 v[8:9], v[12:13], v[8:9], v[20:21]
	v_pk_fma_f32 v[6:7], v[14:15], v[6:7], v[16:17]
	v_cvt_pk_bf16_f32 v3, v3, v5
	v_cvt_pk_bf16_f32 v5, v7, v9
	v_cvt_pk_bf16_f32 v2, v2, v4
	v_cvt_pk_bf16_f32 v4, v6, v8
	v_lshl_add_u64 v[6:7], v[88:89], 0, s[12:13]
	v_mov_b32_e32 v43, v47
	global_store_dwordx4 v[6:7], v[2:5], off
	s_waitcnt vmcnt(1)
	v_mov_b32_e32 v8, v38
	v_mov_b32_e32 v9, v40
	v_pk_mul_f32 v[2:3], v[42:43], v[0:1] op_sel_hi:[1,0]
	v_mov_b32_e32 v4, v30
	v_mov_b32_e32 v5, v32
	v_pk_fma_f32 v[2:3], v[4:5], v[2:3], v[8:9]
	v_mov_b32_e32 v8, v53
	v_mov_b32_e32 v9, v51
	v_pk_mul_f32 v[8:9], v[8:9], v[0:1] op_sel_hi:[1,0]
	v_mov_b32_e32 v10, v26
	v_mov_b32_e32 v11, v28
	v_mov_b32_e32 v12, v34
	v_mov_b32_e32 v13, v36
	v_mov_b32_e32 v53, v50
	v_pk_mul_f32 v[4:5], v[44:45], v[0:1] op_sel_hi:[1,0]
	v_mov_b32_e32 v32, v31
	v_mov_b32_e32 v40, v39
	v_pk_fma_f32 v[8:9], v[8:9], v[10:11], v[12:13]
	v_pk_mul_f32 v[10:11], v[52:53], v[0:1] op_sel_hi:[1,0]
	v_mov_b32_e32 v28, v27
	v_mov_b32_e32 v36, v35
	v_pk_fma_f32 v[4:5], v[32:33], v[4:5], v[40:41]
	v_pk_fma_f32 v[10:11], v[10:11], v[28:29], v[36:37]
	v_cvt_pk_bf16_f32 v3, v3, v5
	v_cvt_pk_bf16_f32 v5, v9, v11
	v_cvt_pk_bf16_f32 v2, v2, v4
	v_cvt_pk_bf16_f32 v4, v8, v10
	s_mov_b64 s[12:13], 0
	global_store_dwordx4 v[6:7], v[2:5], off offset:1024
	s_branch .LBB0_965
.LBB0_971:
	s_lshr_b32 s2, s15, 3
	s_lshl_b32 s100, s7, 8
	s_add_i32 s2, s2, s100
	s_cmpk_gt_i32 s2, 0x7f
	s_cbranch_scc1 .LBB0_974
	s_add_i32 s8, s2, 0x4000
	s_ashr_i32 s3, s2, 31
	s_lshl_b64 s[0:1], s[2:3], 12
	v_and_b32_e32 v0, 63, v90
	s_ashr_i32 s9, s8, 31
	v_lshl_or_b32 v88, v0, 5, s0
	v_mov_b32_e32 v89, s1
	s_ashr_i32 s7, s6, 31
	s_lshl_b64 s[0:1], s[8:9], 11
	s_lshl_b64 s[10:11], s[6:7], 12
	v_lshl_or_b32 v90, v0, 4, s0
	v_mov_b32_e32 v91, s1
	s_lshl_b64 s[12:13], s[6:7], 11
	s_mov_b32 s7, 0x5080000
	s_mov_b32 s9, 0x5100000
	s_mov_b32 s15, 0x5180000
	s_mov_b32 s16, 0x5200000
	s_mov_b32 s17, 0x5280000
	s_mov_b32 s19, 0x5300000
	s_mov_b32 s20, 0x5380000
	s_mov_b32 s22, 0x3fb504f3
	s_mov_b64 s[24:25], 0x5080000
	s_mov_b64 s[28:29], 0x5080800
	s_mov_b64 s[36:37], 0x5100000
	s_mov_b64 s[38:39], 0x5100800
	s_mov_b64 s[40:41], 0x5180000
	s_mov_b64 s[42:43], 0x5180800
	s_mov_b64 s[44:45], 0x5200000
	s_mov_b64 s[46:47], 0x5200800
	s_mov_b64 s[48:49], 0x5280000
	s_mov_b64 s[50:51], 0x5280800
	s_mov_b64 s[52:53], 0x5300000
	s_mov_b64 s[58:59], 0x5300800
	s_mov_b64 s[64:65], 0x5380000
	s_mov_b64 s[66:67], 0x5380800
.LBB0_973:
	v_lshl_add_u64 v[92:93], s[4:5], 0, v[90:91]
	v_add_co_u32_e32 v2, vcc, 0x9580000, v92
	v_lshl_add_u64 v[66:67], s[4:5], 0, v[88:89]
	s_nop 0
	v_addc_co_u32_e32 v3, vcc, 0, v93, vcc
	global_load_dwordx4 v[50:53], v[2:3], off
	global_load_dwordx4 v[80:83], v[2:3], off offset:1024
	v_add_co_u32_e32 v4, vcc, s7, v66
	v_lshl_add_u64 v[2:3], v[66:67], 0, s[24:25]
	s_nop 0
	v_addc_co_u32_e32 v5, vcc, 0, v67, vcc
	v_lshl_add_u64 v[6:7], v[66:67], 0, s[28:29]
	global_load_dwordx4 v[54:57], v[4:5], off
	global_load_dwordx4 v[58:61], v[2:3], off offset:16
	s_nop 0
	global_load_dwordx4 v[2:5], v[4:5], off offset:2048
	s_nop 0
	global_load_dwordx4 v[6:9], v[6:7], off offset:16
	s_mov_b64 s[0:1], 0x5400000
	s_add_i32 s8, s8, s6
	v_lshl_add_u64 v[88:89], v[88:89], 0, s[10:11]
	v_lshl_add_u64 v[90:91], v[90:91], 0, s[12:13]
	s_cmpk_lt_i32 s8, 0x4080
	s_waitcnt vmcnt(4)
	v_and_b32_e32 v10, 0xffff0000, v80
	v_lshlrev_b32_e32 v0, 16, v80
	v_lshlrev_b32_e32 v94, 16, v81
	v_and_b32_e32 v95, 0xffff0000, v81
	v_lshlrev_b32_e32 v96, 16, v82
	v_and_b32_e32 v97, 0xffff0000, v82
	s_waitcnt vmcnt(1)
	v_fmamk_f32 v18, v10, 0x3fb504f3, v3
	v_add_co_u32_e32 v10, vcc, s9, v66
	v_fmamk_f32 v0, v0, 0x3fb504f3, v2
	v_lshl_add_u64 v[2:3], v[66:67], 0, s[36:37]
	v_addc_co_u32_e32 v11, vcc, 0, v67, vcc
	global_load_dwordx4 v[62:65], v[10:11], off
	global_load_dwordx4 v[68:71], v[2:3], off offset:16
	v_lshl_add_u64 v[2:3], v[66:67], 0, s[38:39]
	global_load_dwordx4 v[10:13], v[10:11], off offset:2048
	s_nop 0
	global_load_dwordx4 v[14:17], v[2:3], off offset:16
	v_lshl_add_u64 v[2:3], v[66:67], 0, s[40:41]
	v_pk_fma_f32 v[4:5], v[94:95], s[22:23], v[4:5] op_sel_hi:[1,0,1]
	s_waitcnt vmcnt(4)
	v_pk_fma_f32 v[6:7], v[96:97], s[22:23], v[6:7] op_sel_hi:[1,0,1]
	s_waitcnt vmcnt(1)
	v_add_f32_e32 v0, v0, v10
	v_add_co_u32_e32 v10, vcc, s15, v66
	v_add_f32_e32 v26, v18, v11
	s_nop 0
	v_addc_co_u32_e32 v11, vcc, 0, v67, vcc
	global_load_dwordx4 v[72:75], v[10:11], off
	global_load_dwordx4 v[76:79], v[2:3], off offset:16
	v_lshl_add_u64 v[2:3], v[66:67], 0, s[42:43]
	global_load_dwordx4 v[18:21], v[10:11], off offset:2048
	global_load_dwordx4 v[22:25], v[2:3], off offset:16
	v_add_co_u32_e32 v10, vcc, s16, v66
	v_lshl_add_u64 v[2:3], v[66:67], 0, s[44:45]
	s_nop 0
	v_addc_co_u32_e32 v11, vcc, 0, v67, vcc
	global_load_dwordx4 v[102:105], v[10:11], off
	global_load_dwordx4 v[106:109], v[2:3], off offset:16
	v_lshl_add_u64 v[2:3], v[66:67], 0, s[46:47]
	v_pk_add_f32 v[4:5], v[4:5], v[12:13]
	s_waitcnt vmcnt(6)
	v_pk_add_f32 v[6:7], v[6:7], v[14:15]
	s_waitcnt vmcnt(3)
	v_add_f32_e32 v0, v0, v18
	v_add_f32_e32 v18, v26, v19
	global_load_dwordx4 v[26:29], v[10:11], off offset:2048
	global_load_dwordx4 v[30:33], v[2:3], off offset:16
	v_add_co_u32_e32 v10, vcc, s17, v66
	v_lshl_add_u64 v[2:3], v[66:67], 0, s[48:49]
	s_nop 0
	v_addc_co_u32_e32 v11, vcc, 0, v67, vcc
	global_load_dwordx4 v[110:113], v[10:11], off
	global_load_dwordx4 v[114:117], v[2:3], off offset:16
	v_lshl_add_u64 v[2:3], v[66:67], 0, s[50:51]
	global_load_dwordx4 v[34:37], v[10:11], off offset:2048
	global_load_dwordx4 v[38:41], v[2:3], off offset:16
	v_add_co_u32_e32 v10, vcc, s19, v66
	v_lshl_add_u64 v[2:3], v[66:67], 0, s[52:53]
	s_nop 0
	v_addc_co_u32_e32 v11, vcc, 0, v67, vcc
	global_load_dwordx4 v[118:121], v[10:11], off
	global_load_dwordx4 v[122:125], v[2:3], off offset:16
	v_lshl_add_u64 v[2:3], v[66:67], 0, s[58:59]
	global_load_dwordx4 v[42:45], v[10:11], off offset:2048
	global_load_dwordx4 v[46:49], v[2:3], off offset:16
	v_lshlrev_b32_e32 v3, 16, v51
	v_lshlrev_b32_e32 v2, 16, v50
	v_mov_b32_e32 v10, v54
	v_mov_b32_e32 v11, v56
	v_pk_fma_f32 v[2:3], v[2:3], s[22:23], v[10:11] op_sel_hi:[1,0,1]
	v_mov_b32_e32 v10, v62
	v_mov_b32_e32 v11, v64
	v_pk_add_f32 v[2:3], v[2:3], v[10:11]
	v_mov_b32_e32 v10, v72
	v_mov_b32_e32 v11, v74
	v_pk_add_f32 v[2:3], v[2:3], v[10:11]
	s_waitcnt vmcnt(11)
	v_mov_b32_e32 v10, v102
	v_mov_b32_e32 v11, v104
	v_pk_add_f32 v[2:3], v[2:3], v[10:11]
	v_mov_b32_e32 v56, v55
	v_mov_b32_e32 v64, v63
	v_mov_b32_e32 v74, v73
	v_mov_b32_e32 v104, v103
	v_pk_add_f32 v[4:5], v[4:5], v[20:21]
	v_pk_add_f32 v[6:7], v[6:7], v[22:23]
	s_waitcnt vmcnt(9)
	v_add_f32_e32 v0, v0, v26
	v_add_f32_e32 v18, v18, v27
	v_pk_add_f32 v[4:5], v[4:5], v[28:29]
	s_waitcnt vmcnt(8)
	v_pk_add_f32 v[6:7], v[6:7], v[30:31]
	s_waitcnt vmcnt(7)
	v_mov_b32_e32 v10, v110
	v_mov_b32_e32 v11, v112
	v_pk_add_f32 v[2:3], v[2:3], v[10:11]
	v_mov_b32_e32 v112, v111
	s_waitcnt vmcnt(5)
	v_add_f32_e32 v0, v0, v34
	v_add_f32_e32 v18, v18, v35
	v_pk_add_f32 v[4:5], v[4:5], v[36:37]
	s_waitcnt vmcnt(4)
	v_pk_add_f32 v[6:7], v[6:7], v[38:39]
	s_waitcnt vmcnt(3)
	v_mov_b32_e32 v10, v118
	v_mov_b32_e32 v11, v120
	v_pk_add_f32 v[98:99], v[2:3], v[10:11]
	v_lshlrev_b32_e32 v3, 16, v53
	v_lshlrev_b32_e32 v2, 16, v52
	v_mov_b32_e32 v10, v58
	v_mov_b32_e32 v11, v60
	v_pk_fma_f32 v[2:3], v[2:3], s[22:23], v[10:11] op_sel_hi:[1,0,1]
	v_mov_b32_e32 v10, v68
	v_mov_b32_e32 v11, v70
	v_pk_add_f32 v[2:3], v[2:3], v[10:11]
	v_mov_b32_e32 v10, v76
	v_mov_b32_e32 v11, v78
	v_pk_add_f32 v[2:3], v[2:3], v[10:11]
	v_mov_b32_e32 v10, v106
	v_mov_b32_e32 v11, v108
	v_pk_add_f32 v[2:3], v[2:3], v[10:11]
	v_mov_b32_e32 v10, v114
	v_mov_b32_e32 v11, v116
	v_pk_add_f32 v[2:3], v[2:3], v[10:11]
	s_waitcnt vmcnt(2)
	v_mov_b32_e32 v10, v122
	v_mov_b32_e32 v11, v124
	v_pk_add_f32 v[100:101], v[2:3], v[10:11]
	v_and_b32_e32 v3, 0xffff0000, v51
	v_and_b32_e32 v2, 0xffff0000, v50
	v_pk_fma_f32 v[2:3], v[2:3], s[22:23], v[56:57] op_sel_hi:[1,0,1]
	v_mov_b32_e32 v120, v119
	v_pk_add_f32 v[2:3], v[2:3], v[64:65]
	v_mov_b32_e32 v60, v59
	v_pk_add_f32 v[2:3], v[2:3], v[74:75]
	v_mov_b32_e32 v70, v69
	v_pk_add_f32 v[2:3], v[2:3], v[104:105]
	v_mov_b32_e32 v78, v77
	v_pk_add_f32 v[2:3], v[2:3], v[112:113]
	v_mov_b32_e32 v108, v107
	v_pk_add_f32 v[104:105], v[2:3], v[120:121]
	v_and_b32_e32 v3, 0xffff0000, v53
	v_and_b32_e32 v2, 0xffff0000, v52
	v_pk_fma_f32 v[2:3], v[2:3], s[22:23], v[60:61] op_sel_hi:[1,0,1]
	v_mov_b32_e32 v116, v115
	v_pk_add_f32 v[2:3], v[2:3], v[70:71]
	v_mov_b32_e32 v124, v123
	v_pk_add_f32 v[2:3], v[2:3], v[78:79]
	v_add_co_u32_e32 v10, vcc, s20, v66
	v_pk_add_f32 v[2:3], v[2:3], v[108:109]
	s_nop 0
	v_addc_co_u32_e32 v11, vcc, 0, v67, vcc
	v_pk_add_f32 v[2:3], v[2:3], v[116:117]
	s_waitcnt vmcnt(1)
	v_add_f32_e32 v0, v0, v42
	v_pk_add_f32 v[102:103], v[2:3], v[124:125]
	v_lshl_add_u64 v[2:3], v[66:67], 0, s[64:65]
	global_load_dwordx4 v[62:65], v[10:11], off
	global_load_dwordx4 v[58:61], v[2:3], off offset:16
	v_lshl_add_u64 v[2:3], v[66:67], 0, s[66:67]
	global_load_dwordx4 v[50:53], v[10:11], off offset:2048
	global_load_dwordx4 v[54:57], v[2:3], off offset:16
	v_lshl_add_u64 v[2:3], v[66:67], 0, s[0:1]
	s_mov_b32 s0, 0x5400000
	v_add_co_u32_e32 v10, vcc, s0, v66
	s_mov_b64 s[0:1], 0x5400800
	s_nop 0
	v_addc_co_u32_e32 v11, vcc, 0, v67, vcc
	global_load_dwordx4 v[78:81], v[10:11], off
	global_load_dwordx4 v[74:77], v[2:3], off offset:16
	v_lshl_add_u64 v[2:3], v[66:67], 0, s[0:1]
	global_load_dwordx4 v[66:69], v[10:11], off offset:2048
	global_load_dwordx4 v[70:73], v[2:3], off offset:16
	v_and_b32_e32 v11, 0xffff0000, v83
	v_lshlrev_b32_e32 v10, 16, v83
	v_pk_fma_f32 v[8:9], v[10:11], s[22:23], v[8:9] op_sel_hi:[1,0,1]
	v_add_f32_e32 v18, v18, v43
	v_pk_add_f32 v[8:9], v[8:9], v[16:17]
	v_pk_add_f32 v[4:5], v[4:5], v[44:45]
	v_pk_add_f32 v[8:9], v[8:9], v[24:25]
	s_waitcnt vmcnt(8)
	v_pk_add_f32 v[6:7], v[6:7], v[46:47]
	v_pk_add_f32 v[8:9], v[8:9], v[32:33]
	s_waitcnt vmcnt(5)
	v_add_f32_e32 v0, v0, v50
	v_pk_add_f32 v[8:9], v[8:9], v[40:41]
	v_add_f32_e32 v18, v18, v51
	v_pk_add_f32 v[8:9], v[8:9], v[48:49]
	v_pk_add_f32 v[4:5], v[4:5], v[52:53]
	s_waitcnt vmcnt(4)
	v_pk_add_f32 v[8:9], v[8:9], v[56:57]
	v_mov_b32_e32 v56, v62
	v_mov_b32_e32 v57, v64
	v_mov_b32_e32 v64, v63
	v_pk_add_f32 v[56:57], v[98:99], v[56:57]
	v_pk_add_f32 v[62:63], v[104:105], v[64:65]
	s_waitcnt vmcnt(3)
	v_mov_b32_e32 v64, v78
	v_mov_b32_e32 v65, v80
	v_pk_add_f32 v[56:57], v[56:57], v[64:65]
	v_mov_b32_e32 v80, v79
	s_waitcnt vmcnt(1)
	v_add_f32_e32 v42, v0, v66
	v_pk_add_f32 v[62:63], v[62:63], v[80:81]
	v_add_f32_e32 v0, 0, v56
	s_waitcnt vmcnt(0)
	v_pk_add_f32 v[40:41], v[8:9], v[72:73]
	v_add_f32_e32 v0, v62, v0
	v_mov_b32_e32 v72, v58
	v_mov_b32_e32 v73, v60
	v_mov_b32_e32 v60, v59
	v_add_f32_e32 v0, v57, v0
	v_pk_add_f32 v[72:73], v[100:101], v[72:73]
	v_pk_add_f32 v[58:59], v[102:103], v[60:61]
	v_mov_b32_e32 v60, v74
	v_mov_b32_e32 v61, v76
	v_add_f32_e32 v0, v63, v0
	v_pk_add_f32 v[60:61], v[72:73], v[60:61]
	v_mov_b32_e32 v76, v75
	v_pk_add_f32 v[58:59], v[58:59], v[76:77]
	v_add_f32_e32 v0, v60, v0
	v_add_f32_e32 v0, v58, v0
	v_add_f32_e32 v2, v18, v67
	global_load_dwordx4 v[48:51], v[84:85], off offset:16
	global_load_dwordx4 v[106:109], v[84:85], off
	global_load_dwordx4 v[110:113], v[86:87], off offset:16
	global_load_dwordx4 v[114:117], v[86:87], off
	global_load_dwordx4 v[8:11], v[84:85], off offset:2064
	global_load_dwordx4 v[24:27], v[84:85], off offset:2048
	global_load_dwordx4 v[16:19], v[86:87], off offset:2064
	global_load_dwordx4 v[32:35], v[86:87], off offset:2048
	v_add_f32_e32 v0, v61, v0
	v_add_f32_e32 v0, v59, v0
	v_add_f32_e32 v0, v42, v0
	v_add_f32_e32 v0, v2, v0
	v_pk_add_f32 v[4:5], v[4:5], v[68:69]
	v_pk_add_f32 v[6:7], v[6:7], v[54:55]
	v_add_f32_e32 v0, v4, v0
	v_pk_add_f32 v[6:7], v[6:7], v[70:71]
	v_add_f32_e32 v0, v5, v0
	v_add_f32_e32 v0, v6, v0
	v_add_f32_e32 v0, v7, v0
	v_add_f32_e32 v0, v40, v0
	v_add_f32_e32 v0, v41, v0
	s_waitcnt vmcnt(6)
	v_mov_b32_e32 v64, v106
	v_add_f32_dpp v0, v0, v0 quad_perm:[1,0,3,2] row_mask:0xf bank_mask:0xf bound_ctrl:1
	v_mov_b32_e32 v65, v108
	s_waitcnt vmcnt(4)
	v_mov_b32_e32 v66, v114
	v_add_f32_dpp v0, v0, v0 quad_perm:[2,3,0,1] row_mask:0xf bank_mask:0xf bound_ctrl:1
	v_mov_b32_e32 v67, v116
	v_mov_b32_e32 v108, v107
	v_add_f32_dpp v0, v0, v0 row_half_mirror row_mask:0xf bank_mask:0xf bound_ctrl:1
	v_mov_b32_e32 v116, v115
	s_nop 0
	v_add_f32_dpp v0, v0, v0 row_mirror row_mask:0xf bank_mask:0xf bound_ctrl:1
	s_nop 0
	v_readlane_b32 s2, v0, 16
	v_readlane_b32 s3, v0, 48
	v_readlane_b32 s0, v0, 0
	v_readlane_b32 s1, v0, 32
	v_mov_b32_e32 v12, s2
	v_mov_b32_e32 v13, s3
	v_pk_add_f32 v[12:13], s[0:1], v[12:13]
	s_nop 0
	v_add_f32_e32 v3, v12, v13
	v_mul_f32_e32 v0, 0x3a800000, v3
	v_pk_add_f32 v[14:15], v[56:57], v[0:1] op_sel_hi:[1,0] neg_lo:[0,1] neg_hi:[0,1]
	v_pk_add_f32 v[20:21], v[62:63], v[0:1] op_sel_hi:[1,0] neg_lo:[0,1] neg_hi:[0,1]
	v_pk_mul_f32 v[12:13], v[14:15], v[14:15]
	v_pk_mul_f32 v[22:23], v[20:21], v[20:21]
	v_pk_add_f32 v[28:29], v[60:61], v[0:1] op_sel_hi:[1,0] neg_lo:[0,1] neg_hi:[0,1]
	v_add_f32_e32 v12, v12, v22
	v_add_f32_e32 v12, v13, v12
	v_pk_mul_f32 v[30:31], v[28:29], v[28:29]
	v_pk_add_f32 v[36:37], v[58:59], v[0:1] op_sel_hi:[1,0] neg_lo:[0,1] neg_hi:[0,1]
	v_add_f32_e32 v12, v23, v12
	v_pk_mul_f32 v[38:39], v[36:37], v[36:37]
	v_add_f32_e32 v12, v30, v12
	v_add_f32_e32 v12, v38, v12
	v_add_f32_e32 v12, v31, v12
	v_add_f32_e32 v22, v39, v12
	v_fmac_f32_e32 v42, 0xba800000, v3
	v_fmac_f32_e32 v22, v42, v42
	v_fmac_f32_e32 v2, 0xba800000, v3
	v_pk_add_f32 v[12:13], v[4:5], v[0:1] op_sel_hi:[1,0] neg_lo:[0,1] neg_hi:[0,1]
	v_fmac_f32_e32 v22, v2, v2
	v_pk_mul_f32 v[4:5], v[12:13], v[12:13]
	v_mov_b32_e32 v43, v12
	v_add_f32_e32 v3, v4, v22
	v_add_f32_e32 v3, v5, v3
	v_pk_add_f32 v[4:5], v[6:7], v[0:1] op_sel_hi:[1,0] neg_lo:[0,1] neg_hi:[0,1]
	s_nop 0
	v_pk_mul_f32 v[6:7], v[4:5], v[4:5]
	v_mov_b32_e32 v12, v4
	v_add_f32_e32 v3, v6, v3
	v_add_f32_e32 v3, v7, v3
	v_pk_add_f32 v[6:7], v[40:41], v[0:1] op_sel_hi:[1,0] neg_lo:[0,1] neg_hi:[0,1]
	s_nop 0
	v_pk_mul_f32 v[22:23], v[6:7], v[6:7]
	s_nop 0
	v_add_f32_e32 v0, v22, v3
	v_add_f32_e32 v0, v23, v0
	s_nop 1
	v_add_f32_dpp v0, v0, v0 quad_perm:[1,0,3,2] row_mask:0xf bank_mask:0xf bound_ctrl:1
	s_nop 1
	v_add_f32_dpp v0, v0, v0 quad_perm:[2,3,0,1] row_mask:0xf bank_mask:0xf bound_ctrl:1
	s_nop 1
	v_add_f32_dpp v0, v0, v0 row_half_mirror row_mask:0xf bank_mask:0xf bound_ctrl:1
	s_nop 1
	v_add_f32_dpp v0, v0, v0 row_mirror row_mask:0xf bank_mask:0xf bound_ctrl:1
	s_nop 0
	v_readlane_b32 s2, v0, 16
	v_readlane_b32 s3, v0, 48
	v_readlane_b32 s0, v0, 0
	v_readlane_b32 s1, v0, 32
	v_mov_b32_e32 v22, s2
	v_mov_b32_e32 v23, s3
	v_pk_add_f32 v[22:23], s[0:1], v[22:23]
	s_nop 0
	v_add_f32_e32 v0, v22, v23
	v_fmamk_f32 v0, v0, 0x3a800000, v216
	v_cmp_gt_f32_e32 vcc, s60, v0
	v_mul_f32_e32 v3, 0x4f800000, v0
	s_nop 0
	v_cndmask_b32_e32 v0, v0, v3, vcc
	v_sqrt_f32_e32 v3, v0
	s_nop 0
	v_add_u32_e32 v22, -1, v3
	v_fma_f32 v23, -v22, v3, v0
	v_cmp_ge_f32_e64 s[2:3], 0, v23
	v_add_u32_e32 v23, 1, v3
	s_nop 0
	v_cndmask_b32_e64 v22, v3, v22, s[2:3]
	v_fma_f32 v3, -v23, v3, v0
	v_cmp_lt_f32_e64 s[2:3], 0, v3
	s_nop 1
	v_cndmask_b32_e64 v3, v22, v23, s[2:3]
	v_mul_f32_e32 v22, 0x37800000, v3
	v_cndmask_b32_e32 v3, v3, v22, vcc
	v_cmp_class_f32_e32 vcc, v0, v217
	s_nop 1
	v_cndmask_b32_e32 v0, v3, v0, vcc
	v_div_scale_f32 v3, s[0:1], v0, v0, 1.0
	v_rcp_f32_e32 v22, v3
	s_mov_b32 s0, 0x1b1e0000
	v_fma_f32 v23, -v3, v22, 1.0
	v_fmac_f32_e32 v22, v23, v22
	v_div_scale_f32 v23, vcc, 1.0, v0, 1.0
	v_mul_f32_e32 v30, v23, v22
	v_fma_f32 v31, -v3, v30, v23
	v_fmac_f32_e32 v30, v31, v22
	v_fma_f32 v3, -v3, v30, v23
	v_div_fmas_f32 v3, v3, v22, v30
	v_div_fixup_f32 v0, v3, v0, 1.0
	v_pk_mul_f32 v[22:23], v[28:29], v[0:1] op_sel_hi:[1,0]
	v_mov_b32_e32 v28, v48
	v_mov_b32_e32 v29, v50
	v_mov_b32_e32 v30, v110
	v_mov_b32_e32 v31, v112
	v_pk_fma_f32 v[22:23], v[28:29], v[22:23], v[30:31]
	v_pk_mul_f32 v[28:29], v[36:37], v[0:1] op_sel_hi:[1,0]
	v_mov_b32_e32 v50, v49
	v_mov_b32_e32 v112, v111
	v_pk_mul_f32 v[14:15], v[14:15], v[0:1] op_sel_hi:[1,0]
	v_pk_mul_f32 v[20:21], v[20:21], v[0:1] op_sel_hi:[1,0]
	v_pk_fma_f32 v[28:29], v[50:51], v[28:29], v[112:113]
	v_pk_fma_f32 v[14:15], v[64:65], v[14:15], v[66:67]
	v_pk_fma_f32 v[20:21], v[108:109], v[20:21], v[116:117]
	v_bfe_u32 v3, v29, 16, 1
	v_add3_u32 v3, v29, v3, s33
	v_bfe_u32 v36, v23, 16, 1
	v_add3_u32 v23, v23, v36, s33
	v_lshrrev_b32_e32 v23, 16, v23
	v_cvt_pk_bf16_f32 v20, v14, v20
	v_add_co_u32_e32 v14, vcc, s0, v92
	v_and_or_b32 v23, v3, s26, v23
	v_cvt_pk_bf16_f32 v22, v22, v28
	v_cvt_pk_bf16_f32 v21, v15, v21
	v_addc_co_u32_e32 v15, vcc, 0, v93, vcc
	global_store_dwordx4 v[14:15], v[20:23], off
	s_waitcnt vmcnt(1)
	v_mov_b32_e32 v28, v32
	v_mov_b32_e32 v29, v34
	v_pk_mul_f32 v[20:21], v[42:43], v[0:1] op_sel_hi:[1,0]
	v_mov_b32_e32 v22, v24
	v_mov_b32_e32 v23, v26
	v_mov_b32_e32 v3, v13
	v_mov_b32_e32 v13, v6
	v_mov_b32_e32 v6, v5
	v_pk_fma_f32 v[20:21], v[22:23], v[20:21], v[28:29]
	v_pk_mul_f32 v[2:3], v[2:3], v[0:1] op_sel_hi:[1,0]
	v_mov_b32_e32 v26, v25
	v_mov_b32_e32 v34, v33
	v_mov_b32_e32 v23, v10
	v_mov_b32_e32 v25, v18
	v_pk_mul_f32 v[4:5], v[6:7], v[0:1] op_sel_hi:[1,0]
	v_mov_b32_e32 v10, v9
	v_mov_b32_e32 v18, v17
	v_pk_fma_f32 v[2:3], v[26:27], v[2:3], v[34:35]
	v_pk_mul_f32 v[12:13], v[12:13], v[0:1] op_sel_hi:[1,0]
	v_mov_b32_e32 v22, v8
	v_mov_b32_e32 v24, v16
	v_pk_fma_f32 v[4:5], v[4:5], v[10:11], v[18:19]
	v_pk_fma_f32 v[12:13], v[12:13], v[22:23], v[24:25]
	s_nop 0
	v_cvt_pk_bf16_f32 v5, v13, v5
	v_cvt_pk_bf16_f32 v4, v12, v4
	v_cvt_pk_bf16_f32 v3, v21, v3
	v_cvt_pk_bf16_f32 v2, v20, v2
	global_store_dwordx4 v[14:15], v[2:5], off offset:1024
	s_cbranch_scc1 .LBB0_973

.LBB0_1607:
	s_cmp_ge_i32 s66, s0
	s_mov_b64 s[2:3], -1
	s_cbranch_scc1 .LBB0_1604
	s_and_b64 s[0:1], s[12:13], exec
	s_cselect_b32 s40, s68, s70
	s_cmpk_lt_i32 s40, 0x4000
	s_cbranch_scc0 .LBB0_1604
	global_load_dwordx4 v[58:61], v[92:93], off
	global_load_dwordx4 v[70:73], v[94:95], off
	global_load_dwordx4 v[74:77], v[92:93], off offset:2048
	global_load_dwordx4 v[86:89], v[94:95], off offset:2048
	s_ashr_i32 s41, s40, 31
	s_lshl_b64 s[4:5], s[40:41], 11
	v_lshl_add_u64 v[2:3], v[96:97], 0, s[4:5]
	global_load_dwordx4 v[102:105], v[2:3], off
	global_load_dwordx4 v[106:109], v[2:3], off offset:1024
	global_load_dwordx4 v[78:81], v[92:93], off offset:16
	global_load_dwordx4 v[82:85], v[94:95], off offset:16
	global_load_dwordx4 v[62:65], v[92:93], off offset:2064
	global_load_dwordx4 v[66:69], v[94:95], off offset:2064
	s_or_b32 s62, s40, 1
	s_or_b32 s20, s40, 2
	s_or_b32 s24, s40, 3
	s_or_b32 s56, s40, 4
	s_or_b32 s52, s40, 5
	s_or_b32 s48, s40, 6
	s_or_b32 s44, s40, 7
	s_ashr_i32 s63, s62, 31
	s_ashr_i32 s21, s20, 31
	s_ashr_i32 s25, s24, 31
	s_ashr_i32 s57, s56, 31
	s_ashr_i32 s53, s52, 31
	s_ashr_i32 s49, s48, 31
	s_ashr_i32 s45, s44, 31
	s_lshl_b64 s[64:65], s[62:63], 11
	s_lshl_b64 s[60:61], s[20:21], 11
	s_lshl_b64 s[28:29], s[24:25], 11
	s_lshl_b64 s[58:59], s[56:57], 11
	s_lshl_b64 s[54:55], s[52:53], 11
	s_lshl_b64 s[50:51], s[48:49], 11
	s_lshl_b64 s[46:47], s[44:45], 11
	v_lshl_add_u64 v[2:3], v[96:97], 0, s[64:65]
	v_lshl_add_u64 v[4:5], v[96:97], 0, s[60:61]
	v_lshl_add_u64 v[6:7], v[96:97], 0, s[28:29]
	v_lshl_add_u64 v[8:9], v[96:97], 0, s[58:59]
	v_lshl_add_u64 v[10:11], v[96:97], 0, s[54:55]
	v_lshl_add_u64 v[12:13], v[96:97], 0, s[50:51]
	v_lshl_add_u64 v[110:111], v[96:97], 0, s[46:47]
	global_load_dwordx4 v[54:57], v[2:3], off
	global_load_dwordx4 v[50:53], v[2:3], off offset:1024
	global_load_dwordx4 v[46:49], v[4:5], off
	global_load_dwordx4 v[42:45], v[4:5], off offset:1024
	global_load_dwordx4 v[38:41], v[6:7], off
	global_load_dwordx4 v[34:37], v[6:7], off offset:1024
	global_load_dwordx4 v[30:33], v[8:9], off
	global_load_dwordx4 v[26:29], v[8:9], off offset:1024
	global_load_dwordx4 v[22:25], v[10:11], off
	global_load_dwordx4 v[18:21], v[10:11], off offset:1024
	global_load_dwordx4 v[14:17], v[12:13], off
	s_nop 0
	global_load_dwordx4 v[10:13], v[12:13], off offset:1024
	s_nop 0
	global_load_dwordx4 v[6:9], v[110:111], off
	global_load_dwordx4 v[2:5], v[110:111], off offset:1024
	s_mov_b32 s36, 0xf800000
	s_mov_b32 s35, 0xf800000
	s_waitcnt vmcnt(23)
	v_mov_b32_e32 v110, v58
	s_waitcnt vmcnt(22)
	v_mov_b32_e32 v112, v70
	s_waitcnt vmcnt(19)
	v_lshlrev_b32_e32 v58, 16, v102
	v_mov_b32_e32 v70, v74
	v_and_b32_e32 v74, 0xffff0000, v102
	v_add_f32_e32 v0, 0, v58
	v_mov_b32_e32 v111, v60
	v_mov_b32_e32 v60, v59
	v_lshlrev_b32_e32 v59, 16, v103
	v_add_f32_e32 v0, v0, v74
	v_mov_b32_e32 v113, v72
	v_mov_b32_e32 v72, v71
	v_mov_b32_e32 v71, v76
	v_mov_b32_e32 v76, v75
	v_and_b32_e32 v75, 0xffff0000, v103
	v_add_f32_e32 v0, v0, v59
	v_mov_b32_e32 v114, v86
	v_lshlrev_b32_e32 v86, 16, v104
	v_add_f32_e32 v0, v0, v75
	v_and_b32_e32 v102, 0xffff0000, v104
	v_add_f32_e32 v0, v0, v86
	v_mov_b32_e32 v115, v88
	v_mov_b32_e32 v88, v87
	v_lshlrev_b32_e32 v87, 16, v105
	v_add_f32_e32 v0, v0, v102
	v_and_b32_e32 v103, 0xffff0000, v105
	v_add_f32_e32 v0, v0, v87
	s_waitcnt vmcnt(18)
	v_lshlrev_b32_e32 v104, 16, v106
	v_add_f32_e32 v0, v0, v103
	v_and_b32_e32 v106, 0xffff0000, v106
	v_add_f32_e32 v0, v0, v104
	v_lshlrev_b32_e32 v105, 16, v107
	v_add_f32_e32 v0, v0, v106
	v_and_b32_e32 v107, 0xffff0000, v107
	v_add_f32_e32 v0, v0, v105
	v_lshlrev_b32_e32 v116, 16, v108
	v_add_f32_e32 v0, v0, v107
	v_and_b32_e32 v108, 0xffff0000, v108
	v_add_f32_e32 v0, v0, v116
	v_lshlrev_b32_e32 v117, 16, v109
	v_add_f32_e32 v0, v0, v108
	v_and_b32_e32 v109, 0xffff0000, v109
	v_add_f32_e32 v0, v0, v117
	v_add_f32_e32 v0, v0, v109
	s_nop 1
	v_add_f32_dpp v0, v0, v0 quad_perm:[1,0,3,2] row_mask:0xf bank_mask:0xf bound_ctrl:1
	s_nop 1
	v_add_f32_dpp v0, v0, v0 quad_perm:[2,3,0,1] row_mask:0xf bank_mask:0xf bound_ctrl:1
	s_nop 1
	v_add_f32_dpp v0, v0, v0 row_half_mirror row_mask:0xf bank_mask:0xf bound_ctrl:1
	s_nop 1
	v_add_f32_dpp v0, v0, v0 row_mirror row_mask:0xf bank_mask:0xf bound_ctrl:1
	s_nop 0
	v_readlane_b32 s2, v0, 16
	v_readlane_b32 s3, v0, 48
	v_readlane_b32 s0, v0, 0
	v_readlane_b32 s1, v0, 32
	v_mov_b32_e32 v118, s2
	v_mov_b32_e32 v119, s3
	v_pk_add_f32 v[118:119], s[0:1], v[118:119]
	s_nop 0
	v_add_f32_e32 v0, v118, v119
	v_mul_f32_e32 v0, 0x3a800000, v0
	v_pk_add_f32 v[58:59], v[58:59], v[0:1] op_sel_hi:[1,0] neg_lo:[0,1] neg_hi:[0,1]
	v_pk_add_f32 v[120:121], v[74:75], v[0:1] op_sel_hi:[1,0] neg_lo:[0,1] neg_hi:[0,1]
	v_pk_mul_f32 v[118:119], v[58:59], v[58:59]
	v_pk_mul_f32 v[74:75], v[120:121], v[120:121]
	v_pk_add_f32 v[86:87], v[86:87], v[0:1] op_sel_hi:[1,0] neg_lo:[0,1] neg_hi:[0,1]
	v_pk_add_f32 v[102:103], v[102:103], v[0:1] op_sel_hi:[1,0] neg_lo:[0,1] neg_hi:[0,1]
	v_pk_add_f32 v[104:105], v[104:105], v[0:1] op_sel_hi:[1,0] neg_lo:[0,1] neg_hi:[0,1]
	v_pk_add_f32 v[106:107], v[106:107], v[0:1] op_sel_hi:[1,0] neg_lo:[0,1] neg_hi:[0,1]
	v_pk_add_f32 v[116:117], v[116:117], v[0:1] op_sel_hi:[1,0] neg_lo:[0,1] neg_hi:[0,1]
	v_pk_add_f32 v[108:109], v[108:109], v[0:1] op_sel_hi:[1,0] neg_lo:[0,1] neg_hi:[0,1]
	v_add_f32_e32 v0, v118, v74
	v_add_f32_e32 v0, v119, v0
	v_pk_mul_f32 v[122:123], v[86:87], v[86:87]
	v_add_f32_e32 v0, v75, v0
	v_pk_mul_f32 v[124:125], v[102:103], v[102:103]
	v_add_f32_e32 v0, v122, v0
	v_add_f32_e32 v0, v124, v0
	v_add_f32_e32 v0, v123, v0
	v_add_f32_e32 v0, v125, v0
	v_mov_b32_e32 v126, v107
	v_mov_b32_e32 v127, v105
	v_fmac_f32_e32 v0, v104, v104
	v_pk_mul_f32 v[126:127], v[126:127], v[126:127]
	v_fmac_f32_e32 v0, v106, v106
	v_mov_b32_e32 v128, v108
	v_mov_b32_e32 v129, v116
	v_add_f32_e32 v0, v127, v0
	v_pk_mul_f32 v[128:129], v[128:129], v[128:129]
	v_add_f32_e32 v0, v126, v0
	v_mov_b32_e32 v130, v109
	v_mov_b32_e32 v131, v117
	v_add_f32_e32 v0, v129, v0
	v_pk_mul_f32 v[130:131], v[130:131], v[130:131]
	v_add_f32_e32 v0, v128, v0
	v_add_f32_e32 v0, v131, v0
	v_add_f32_e32 v0, v130, v0
	s_waitcnt vmcnt(17)
	v_mov_b32_e32 v118, v78
	v_mov_b32_e32 v119, v80
	v_add_f32_dpp v0, v0, v0 quad_perm:[1,0,3,2] row_mask:0xf bank_mask:0xf bound_ctrl:1
	v_mov_b32_e32 v80, v79
	s_waitcnt vmcnt(16)
	v_mov_b32_e32 v122, v82
	v_add_f32_dpp v0, v0, v0 quad_perm:[2,3,0,1] row_mask:0xf bank_mask:0xf bound_ctrl:1
	v_mov_b32_e32 v123, v84
	v_mov_b32_e32 v84, v83
	v_add_f32_dpp v0, v0, v0 row_half_mirror row_mask:0xf bank_mask:0xf bound_ctrl:1
	s_waitcnt vmcnt(14)
	v_mov_b32_e32 v83, v68
	v_mov_b32_e32 v68, v67
	v_add_f32_dpp v0, v0, v0 row_mirror row_mask:0xf bank_mask:0xf bound_ctrl:1
	s_nop 0
	v_readlane_b32 s2, v0, 16
	v_readlane_b32 s3, v0, 48
	v_readlane_b32 s0, v0, 0
	v_readlane_b32 s1, v0, 32
	v_mov_b32_e32 v74, s2
	v_mov_b32_e32 v75, s3
	v_pk_add_f32 v[74:75], s[0:1], v[74:75]
	s_nop 0
	v_add_f32_e32 v0, v74, v75
	v_fmamk_f32 v0, v0, 0x3a800000, v216
	v_mul_f32_e32 v74, 0x4f800000, v0
	v_cmp_gt_f32_e32 vcc, s36, v0
	s_nop 1
	v_cndmask_b32_e32 v0, v0, v74, vcc
	v_sqrt_f32_e32 v74, v0
	s_nop 0
	v_add_u32_e32 v75, -1, v74
	v_fma_f32 v78, -v75, v74, v0
	v_cmp_ge_f32_e64 s[2:3], 0, v78
	v_add_u32_e32 v78, 1, v74
	s_nop 0
	v_cndmask_b32_e64 v75, v74, v75, s[2:3]
	v_fma_f32 v74, -v78, v74, v0
	v_cmp_lt_f32_e64 s[2:3], 0, v74
	s_nop 1
	v_cndmask_b32_e64 v74, v75, v78, s[2:3]
	v_mul_f32_e32 v75, 0x37800000, v74
	v_cndmask_b32_e32 v74, v74, v75, vcc
	v_cmp_class_f32_e32 vcc, v0, v217
	s_nop 1
	v_cndmask_b32_e32 v0, v74, v0, vcc
	v_div_scale_f32 v74, s[0:1], v0, v0, 1.0
	v_rcp_f32_e32 v75, v74
	v_readlane_b32 s0, v255, 22
	v_readlane_b32 s1, v255, 23
	v_fma_f32 v78, -v74, v75, 1.0
	v_fmac_f32_e32 v75, v78, v75
	v_div_scale_f32 v78, vcc, 1.0, v0, 1.0
	v_mul_f32_e32 v79, v78, v75
	v_fma_f32 v82, -v74, v79, v78
	v_fmac_f32_e32 v79, v82, v75
	v_fma_f32 v74, -v74, v79, v78
	v_div_fmas_f32 v74, v74, v75, v79
	v_div_fixup_f32 v0, v74, v0, 1.0
	v_pk_mul_f32 v[74:75], v[104:105], v[0:1] op_sel_hi:[1,0]
	v_mov_b32_e32 v82, v66
	v_pk_fma_f32 v[74:75], v[70:71], v[74:75], v[114:115]
	v_pk_mul_f32 v[70:71], v[120:121], v[0:1] op_sel_hi:[1,0]
	v_pk_mul_f32 v[58:59], v[58:59], v[0:1] op_sel_hi:[1,0]
	v_pk_fma_f32 v[70:71], v[60:61], v[70:71], v[72:73]
	v_pk_mul_f32 v[60:61], v[106:107], v[0:1] op_sel_hi:[1,0]
	v_pk_mul_f32 v[72:73], v[86:87], v[0:1] op_sel_hi:[1,0]
	v_pk_fma_f32 v[60:61], v[76:77], v[60:61], v[88:89]
	v_pk_fma_f32 v[78:79], v[118:119], v[72:73], v[122:123]
	v_pk_mul_f32 v[72:73], v[116:117], v[0:1] op_sel_hi:[1,0]
	v_mov_b32_e32 v76, v62
	v_mov_b32_e32 v77, v64
	v_pk_fma_f32 v[76:77], v[72:73], v[76:77], v[82:83]
	v_pk_mul_f32 v[72:73], v[102:103], v[0:1] op_sel_hi:[1,0]
	v_mov_b32_e32 v64, v63
	v_pk_fma_f32 v[72:73], v[80:81], v[72:73], v[84:85]
	v_pk_mul_f32 v[80:81], v[108:109], v[0:1] op_sel_hi:[1,0]
	v_cndmask_b32_e64 v0, 0, 1, s[0:1]
	v_pk_fma_f32 v[58:59], v[110:111], v[58:59], v[112:113]
	v_cmp_ne_u32_e64 s[36:37], 1, v0
	s_andn2_b64 vcc, exec, s[0:1]
	v_pk_fma_f32 v[62:63], v[80:81], v[64:65], v[68:69]
	s_cbranch_vccnz .LBB0_1611
	v_cvt_pk_bf16_f32 v67, v79, v73
	v_cvt_pk_bf16_f32 v66, v78, v72
	v_cvt_pk_bf16_f32 v65, v59, v71
	v_cvt_pk_bf16_f32 v64, v58, v70
	v_lshl_add_u64 v[68:69], v[98:99], 0, s[4:5]
	global_store_dwordx4 v[68:69], v[64:67], off
	s_nop 1
	v_cvt_pk_bf16_f32 v67, v77, v63
	v_cvt_pk_bf16_f32 v66, v76, v62
	v_cvt_pk_bf16_f32 v65, v75, v61
	v_cvt_pk_bf16_f32 v64, v74, v60
	global_store_dwordx4 v[68:69], v[64:67], off offset:1024

.LBB0_1613:
	global_load_dwordx4 v[58:61], v[92:93], off
	s_nop 0
	global_load_dwordx4 v[64:67], v[94:95], off
	global_load_dwordx4 v[68:71], v[92:93], off offset:2048
	global_load_dwordx4 v[72:75], v[94:95], off offset:2048
	global_load_dwordx4 v[76:79], v[92:93], off offset:16
	global_load_dwordx4 v[80:83], v[94:95], off offset:16
	global_load_dwordx4 v[84:87], v[92:93], off offset:2064
	global_load_dwordx4 v[102:105], v[94:95], off offset:2064
	s_waitcnt vmcnt(21)
	v_lshlrev_b32_e32 v62, 16, v54
	v_and_b32_e32 v54, 0xffff0000, v54
	v_add_f32_e32 v0, 0, v62
	v_lshlrev_b32_e32 v63, 16, v55
	v_add_f32_e32 v0, v0, v54
	v_and_b32_e32 v55, 0xffff0000, v55
	v_add_f32_e32 v0, v0, v63
	v_lshlrev_b32_e32 v88, 16, v56
	v_add_f32_e32 v0, v0, v55
	v_and_b32_e32 v56, 0xffff0000, v56
	v_add_f32_e32 v0, v0, v88
	v_lshlrev_b32_e32 v89, 16, v57
	v_add_f32_e32 v0, v0, v56
	v_and_b32_e32 v57, 0xffff0000, v57
	v_add_f32_e32 v0, v0, v89
	s_waitcnt vmcnt(20)
	v_lshlrev_b32_e32 v106, 16, v50
	v_add_f32_e32 v0, v0, v57
	v_and_b32_e32 v50, 0xffff0000, v50
	v_add_f32_e32 v0, v0, v106
	v_lshlrev_b32_e32 v107, 16, v51
	v_add_f32_e32 v0, v0, v50
	v_and_b32_e32 v51, 0xffff0000, v51
	v_add_f32_e32 v0, v0, v107
	v_lshlrev_b32_e32 v108, 16, v52
	v_add_f32_e32 v0, v0, v51
	v_and_b32_e32 v52, 0xffff0000, v52
	v_add_f32_e32 v0, v0, v108
	v_lshlrev_b32_e32 v109, 16, v53
	v_add_f32_e32 v0, v0, v52
	v_and_b32_e32 v53, 0xffff0000, v53
	v_add_f32_e32 v0, v0, v109
	v_add_f32_e32 v0, v0, v53
	s_waitcnt vmcnt(7)
	v_mov_b32_e32 v122, v58
	v_add_f32_dpp v0, v0, v0 quad_perm:[1,0,3,2] row_mask:0xf bank_mask:0xf bound_ctrl:1
	v_mov_b32_e32 v123, v60
	v_mov_b32_e32 v60, v59
	v_add_f32_dpp v0, v0, v0 quad_perm:[2,3,0,1] row_mask:0xf bank_mask:0xf bound_ctrl:1
	s_waitcnt vmcnt(5)
	v_mov_b32_e32 v58, v68
	v_mov_b32_e32 v59, v70
	v_add_f32_dpp v0, v0, v0 row_half_mirror row_mask:0xf bank_mask:0xf bound_ctrl:1
	v_mov_b32_e32 v70, v69
	v_mov_b32_e32 v124, v64
	v_add_f32_dpp v0, v0, v0 row_mirror row_mask:0xf bank_mask:0xf bound_ctrl:1
	v_mov_b32_e32 v125, v66
	v_readlane_b32 s4, v0, 16
	v_readlane_b32 s5, v0, 48
	v_readlane_b32 s0, v0, 0
	v_readlane_b32 s1, v0, 32
	v_mov_b32_e32 v110, s4
	v_mov_b32_e32 v111, s5
	v_pk_add_f32 v[110:111], s[0:1], v[110:111]
	v_mov_b32_e32 v66, v65
	v_add_f32_e32 v0, v110, v111
	v_mul_f32_e32 v0, 0x3a800000, v0
	v_pk_add_f32 v[62:63], v[62:63], v[0:1] op_sel_hi:[1,0] neg_lo:[0,1] neg_hi:[0,1]
	v_pk_add_f32 v[54:55], v[54:55], v[0:1] op_sel_hi:[1,0] neg_lo:[0,1] neg_hi:[0,1]
	v_pk_add_f32 v[110:111], v[56:57], v[0:1] op_sel_hi:[1,0] neg_lo:[0,1] neg_hi:[0,1]
	v_pk_add_f32 v[56:57], v[106:107], v[0:1] op_sel_hi:[1,0] neg_lo:[0,1] neg_hi:[0,1]
	v_pk_add_f32 v[106:107], v[50:51], v[0:1] op_sel_hi:[1,0] neg_lo:[0,1] neg_hi:[0,1]
	v_pk_add_f32 v[112:113], v[52:53], v[0:1] op_sel_hi:[1,0] neg_lo:[0,1] neg_hi:[0,1]
	v_pk_mul_f32 v[50:51], v[62:63], v[62:63]
	v_pk_mul_f32 v[52:53], v[54:55], v[54:55]
	v_pk_add_f32 v[88:89], v[88:89], v[0:1] op_sel_hi:[1,0] neg_lo:[0,1] neg_hi:[0,1]
	v_pk_add_f32 v[108:109], v[108:109], v[0:1] op_sel_hi:[1,0] neg_lo:[0,1] neg_hi:[0,1]
	v_add_f32_e32 v0, v50, v52
	v_add_f32_e32 v0, v51, v0
	v_pk_mul_f32 v[114:115], v[88:89], v[88:89]
	v_add_f32_e32 v0, v53, v0
	v_pk_mul_f32 v[116:117], v[110:111], v[110:111]
	v_add_f32_e32 v0, v114, v0
	v_add_f32_e32 v0, v116, v0
	v_add_f32_e32 v0, v115, v0
	v_add_f32_e32 v0, v117, v0
	v_mov_b32_e32 v118, v107
	v_mov_b32_e32 v119, v57
	v_fmac_f32_e32 v0, v56, v56
	v_pk_mul_f32 v[118:119], v[118:119], v[118:119]
	v_fmac_f32_e32 v0, v106, v106
	v_mov_b32_e32 v120, v112
	v_mov_b32_e32 v121, v108
	v_add_f32_e32 v0, v119, v0
	v_pk_mul_f32 v[68:69], v[120:121], v[120:121]
	v_add_f32_e32 v0, v118, v0
	s_waitcnt vmcnt(4)
	v_mov_b32_e32 v64, v72
	v_mov_b32_e32 v65, v74
	v_mov_b32_e32 v74, v73
	v_mov_b32_e32 v72, v113
	v_mov_b32_e32 v73, v109
	v_add_f32_e32 v0, v69, v0
	v_pk_mul_f32 v[72:73], v[72:73], v[72:73]
	v_add_f32_e32 v0, v68, v0
	v_add_f32_e32 v0, v73, v0
	v_add_f32_e32 v0, v72, v0
	s_waitcnt vmcnt(3)
	v_mov_b32_e32 v68, v76
	v_mov_b32_e32 v69, v78
	v_add_f32_dpp v0, v0, v0 quad_perm:[1,0,3,2] row_mask:0xf bank_mask:0xf bound_ctrl:1
	s_waitcnt vmcnt(2)
	v_mov_b32_e32 v72, v80
	v_mov_b32_e32 v73, v82
	v_add_f32_dpp v0, v0, v0 quad_perm:[2,3,0,1] row_mask:0xf bank_mask:0xf bound_ctrl:1
	v_mov_b32_e32 v78, v77
	v_mov_b32_e32 v82, v81
	v_add_f32_dpp v0, v0, v0 row_half_mirror row_mask:0xf bank_mask:0xf bound_ctrl:1
	s_nop 1
	v_add_f32_dpp v0, v0, v0 row_mirror row_mask:0xf bank_mask:0xf bound_ctrl:1
	s_nop 0
	v_readlane_b32 s4, v0, 16
	v_readlane_b32 s5, v0, 48
	v_readlane_b32 s0, v0, 0
	v_readlane_b32 s1, v0, 32
	v_mov_b32_e32 v50, s4
	v_mov_b32_e32 v51, s5
	v_pk_add_f32 v[50:51], s[0:1], v[50:51]
	s_nop 0
	v_add_f32_e32 v0, v50, v51
	v_fmamk_f32 v0, v0, 0x3a800000, v216
	v_mul_f32_e32 v50, 0x4f800000, v0
	v_cmp_gt_f32_e32 vcc, s35, v0
	s_nop 1
	v_cndmask_b32_e32 v0, v0, v50, vcc
	v_sqrt_f32_e32 v50, v0
	s_nop 0
	v_add_u32_e32 v51, -1, v50
	v_fma_f32 v52, -v51, v50, v0
	v_cmp_ge_f32_e64 s[4:5], 0, v52
	v_add_u32_e32 v52, 1, v50
	s_nop 0
	v_cndmask_b32_e64 v51, v50, v51, s[4:5]
	v_fma_f32 v50, -v52, v50, v0
	v_cmp_lt_f32_e64 s[4:5], 0, v50
	s_nop 1
	v_cndmask_b32_e64 v50, v51, v52, s[4:5]
	v_mul_f32_e32 v51, 0x37800000, v50
	v_cndmask_b32_e32 v50, v50, v51, vcc
	v_cmp_class_f32_e32 vcc, v0, v217
	s_nop 1
	v_cndmask_b32_e32 v0, v50, v0, vcc
	v_div_scale_f32 v50, s[0:1], v0, v0, 1.0
	v_rcp_f32_e32 v51, v50
	s_nop 0
	v_fma_f32 v52, -v50, v51, 1.0
	v_fmac_f32_e32 v51, v52, v51
	v_div_scale_f32 v52, vcc, 1.0, v0, 1.0
	v_mul_f32_e32 v53, v52, v51
	v_fma_f32 v76, -v50, v53, v52
	v_fmac_f32_e32 v53, v76, v51
	v_fma_f32 v50, -v50, v53, v52
	v_div_fmas_f32 v50, v50, v51, v53
	v_div_fixup_f32 v0, v50, v0, 1.0
	v_pk_mul_f32 v[52:53], v[56:57], v[0:1] op_sel_hi:[1,0]
	v_pk_mul_f32 v[50:51], v[62:63], v[0:1] op_sel_hi:[1,0]
	v_pk_fma_f32 v[64:65], v[58:59], v[52:53], v[64:65]
	v_pk_mul_f32 v[52:53], v[54:55], v[0:1] op_sel_hi:[1,0]
	v_pk_mul_f32 v[54:55], v[88:89], v[0:1] op_sel_hi:[1,0]
	v_pk_fma_f32 v[56:57], v[60:61], v[52:53], v[66:67]
	v_pk_fma_f32 v[68:69], v[68:69], v[54:55], v[72:73]
	v_pk_mul_f32 v[54:55], v[108:109], v[0:1] op_sel_hi:[1,0]
	s_waitcnt vmcnt(1)
	v_mov_b32_e32 v58, v84
	v_mov_b32_e32 v59, v86
	s_waitcnt vmcnt(0)
	v_mov_b32_e32 v60, v102
	v_mov_b32_e32 v61, v104
	v_pk_fma_f32 v[66:67], v[54:55], v[58:59], v[60:61]
	v_pk_mul_f32 v[54:55], v[110:111], v[0:1] op_sel_hi:[1,0]
	v_pk_mul_f32 v[52:53], v[106:107], v[0:1] op_sel_hi:[1,0]
	v_pk_fma_f32 v[62:63], v[78:79], v[54:55], v[82:83]
	v_pk_mul_f32 v[54:55], v[112:113], v[0:1] op_sel_hi:[1,0]
	v_mov_b32_e32 v86, v85
	v_mov_b32_e32 v104, v103
	v_pk_fma_f32 v[50:51], v[122:123], v[50:51], v[124:125]
	v_pk_fma_f32 v[52:53], v[70:71], v[52:53], v[74:75]
	s_and_b64 vcc, exec, s[36:37]
	v_pk_fma_f32 v[58:59], v[54:55], v[86:87], v[104:105]
	s_cbranch_vccnz .LBB0_1615
	v_cvt_pk_bf16_f32 v73, v69, v63
	v_cvt_pk_bf16_f32 v72, v68, v62
	v_cvt_pk_bf16_f32 v71, v51, v57
	v_cvt_pk_bf16_f32 v70, v50, v56
	v_lshl_add_u64 v[54:55], v[98:99], 0, s[64:65]
	global_store_dwordx4 v[54:55], v[70:73], off
	s_nop 1
	v_cvt_pk_bf16_f32 v73, v67, v59
	v_cvt_pk_bf16_f32 v72, v66, v58
	v_cvt_pk_bf16_f32 v71, v65, v53
	v_cvt_pk_bf16_f32 v70, v64, v52
	global_store_dwordx4 v[54:55], v[70:73], off offset:1024

.LBB0_1617:
	global_load_dwordx4 v[50:53], v[92:93], off
	s_nop 0
	global_load_dwordx4 v[56:59], v[94:95], off
	global_load_dwordx4 v[60:63], v[92:93], off offset:2048
	global_load_dwordx4 v[64:67], v[94:95], off offset:2048
	global_load_dwordx4 v[68:71], v[92:93], off offset:16
	global_load_dwordx4 v[72:75], v[94:95], off offset:16
	global_load_dwordx4 v[76:79], v[92:93], off offset:2064
	global_load_dwordx4 v[80:83], v[94:95], off offset:2064
	v_lshlrev_b32_e32 v54, 16, v46
	v_and_b32_e32 v46, 0xffff0000, v46
	v_add_f32_e32 v0, 0, v54
	v_lshlrev_b32_e32 v55, 16, v47
	v_add_f32_e32 v0, v0, v46
	v_and_b32_e32 v47, 0xffff0000, v47
	v_add_f32_e32 v0, v0, v55
	v_lshlrev_b32_e32 v84, 16, v48
	v_add_f32_e32 v0, v0, v47
	v_and_b32_e32 v48, 0xffff0000, v48
	v_add_f32_e32 v0, v0, v84
	v_lshlrev_b32_e32 v85, 16, v49
	v_add_f32_e32 v0, v0, v48
	v_and_b32_e32 v49, 0xffff0000, v49
	v_add_f32_e32 v0, v0, v85
	v_lshlrev_b32_e32 v86, 16, v42
	v_add_f32_e32 v0, v0, v49
	v_and_b32_e32 v42, 0xffff0000, v42
	v_add_f32_e32 v0, v0, v86
	v_lshlrev_b32_e32 v87, 16, v43
	v_add_f32_e32 v0, v0, v42
	v_and_b32_e32 v43, 0xffff0000, v43
	v_add_f32_e32 v0, v0, v87
	v_lshlrev_b32_e32 v88, 16, v44
	v_add_f32_e32 v0, v0, v43
	v_and_b32_e32 v44, 0xffff0000, v44
	v_add_f32_e32 v0, v0, v88
	v_lshlrev_b32_e32 v89, 16, v45
	v_add_f32_e32 v0, v0, v44
	v_and_b32_e32 v45, 0xffff0000, v45
	v_add_f32_e32 v0, v0, v89
	v_add_f32_e32 v0, v0, v45
	s_waitcnt vmcnt(7)
	v_mov_b32_e32 v114, v50
	v_add_f32_dpp v0, v0, v0 quad_perm:[1,0,3,2] row_mask:0xf bank_mask:0xf bound_ctrl:1
	v_mov_b32_e32 v115, v52
	v_mov_b32_e32 v52, v51
	v_add_f32_dpp v0, v0, v0 quad_perm:[2,3,0,1] row_mask:0xf bank_mask:0xf bound_ctrl:1
	s_waitcnt vmcnt(5)
	v_mov_b32_e32 v50, v60
	v_mov_b32_e32 v51, v62
	v_add_f32_dpp v0, v0, v0 row_half_mirror row_mask:0xf bank_mask:0xf bound_ctrl:1
	v_mov_b32_e32 v62, v61
	v_mov_b32_e32 v116, v56
	v_add_f32_dpp v0, v0, v0 row_mirror row_mask:0xf bank_mask:0xf bound_ctrl:1
	v_mov_b32_e32 v117, v58
	v_readlane_b32 s2, v0, 16
	v_readlane_b32 s3, v0, 48
	v_readlane_b32 s0, v0, 0
	v_readlane_b32 s1, v0, 32
	v_mov_b32_e32 v102, s2
	v_mov_b32_e32 v103, s3
	v_pk_add_f32 v[102:103], s[0:1], v[102:103]
	v_mov_b32_e32 v58, v57
	v_add_f32_e32 v0, v102, v103
	v_mul_f32_e32 v0, 0x3a800000, v0
	v_pk_add_f32 v[54:55], v[54:55], v[0:1] op_sel_hi:[1,0] neg_lo:[0,1] neg_hi:[0,1]
	v_pk_add_f32 v[46:47], v[46:47], v[0:1] op_sel_hi:[1,0] neg_lo:[0,1] neg_hi:[0,1]
	v_pk_add_f32 v[102:103], v[48:49], v[0:1] op_sel_hi:[1,0] neg_lo:[0,1] neg_hi:[0,1]
	v_pk_add_f32 v[48:49], v[86:87], v[0:1] op_sel_hi:[1,0] neg_lo:[0,1] neg_hi:[0,1]
	v_pk_add_f32 v[86:87], v[42:43], v[0:1] op_sel_hi:[1,0] neg_lo:[0,1] neg_hi:[0,1]
	v_pk_add_f32 v[104:105], v[44:45], v[0:1] op_sel_hi:[1,0] neg_lo:[0,1] neg_hi:[0,1]
	v_pk_mul_f32 v[42:43], v[54:55], v[54:55]
	v_pk_mul_f32 v[44:45], v[46:47], v[46:47]
	v_pk_add_f32 v[84:85], v[84:85], v[0:1] op_sel_hi:[1,0] neg_lo:[0,1] neg_hi:[0,1]
	v_pk_add_f32 v[88:89], v[88:89], v[0:1] op_sel_hi:[1,0] neg_lo:[0,1] neg_hi:[0,1]
	v_add_f32_e32 v0, v42, v44
	v_add_f32_e32 v0, v43, v0
	v_pk_mul_f32 v[106:107], v[84:85], v[84:85]
	v_add_f32_e32 v0, v45, v0
	v_pk_mul_f32 v[108:109], v[102:103], v[102:103]
	v_add_f32_e32 v0, v106, v0
	v_add_f32_e32 v0, v108, v0
	v_add_f32_e32 v0, v107, v0
	v_add_f32_e32 v0, v109, v0
	v_mov_b32_e32 v110, v87
	v_mov_b32_e32 v111, v49
	v_fmac_f32_e32 v0, v48, v48
	v_pk_mul_f32 v[110:111], v[110:111], v[110:111]
	v_fmac_f32_e32 v0, v86, v86
	v_mov_b32_e32 v112, v104
	v_mov_b32_e32 v113, v88
	v_add_f32_e32 v0, v111, v0
	v_pk_mul_f32 v[60:61], v[112:113], v[112:113]
	v_add_f32_e32 v0, v110, v0
	s_waitcnt vmcnt(4)
	v_mov_b32_e32 v56, v64
	v_mov_b32_e32 v57, v66
	v_mov_b32_e32 v66, v65
	v_mov_b32_e32 v64, v105
	v_mov_b32_e32 v65, v89
	v_add_f32_e32 v0, v61, v0
	v_pk_mul_f32 v[64:65], v[64:65], v[64:65]
	v_add_f32_e32 v0, v60, v0
	v_add_f32_e32 v0, v65, v0
	v_add_f32_e32 v0, v64, v0
	s_waitcnt vmcnt(3)
	v_mov_b32_e32 v60, v68
	v_mov_b32_e32 v61, v70
	v_add_f32_dpp v0, v0, v0 quad_perm:[1,0,3,2] row_mask:0xf bank_mask:0xf bound_ctrl:1
	s_waitcnt vmcnt(2)
	v_mov_b32_e32 v64, v72
	v_mov_b32_e32 v65, v74
	v_add_f32_dpp v0, v0, v0 quad_perm:[2,3,0,1] row_mask:0xf bank_mask:0xf bound_ctrl:1
	v_mov_b32_e32 v70, v69
	v_mov_b32_e32 v74, v73
	v_add_f32_dpp v0, v0, v0 row_half_mirror row_mask:0xf bank_mask:0xf bound_ctrl:1
	s_nop 1
	v_add_f32_dpp v0, v0, v0 row_mirror row_mask:0xf bank_mask:0xf bound_ctrl:1
	s_nop 0
	v_readlane_b32 s2, v0, 16
	v_readlane_b32 s3, v0, 48
	v_readlane_b32 s0, v0, 0
	v_readlane_b32 s1, v0, 32
	v_mov_b32_e32 v42, s2
	v_mov_b32_e32 v43, s3
	v_pk_add_f32 v[42:43], s[0:1], v[42:43]
	s_nop 0
	v_add_f32_e32 v0, v42, v43
	v_fmamk_f32 v0, v0, 0x3a800000, v216
	v_mul_f32_e32 v42, 0x4f800000, v0
	v_cmp_gt_f32_e32 vcc, s35, v0
	s_nop 1
	v_cndmask_b32_e32 v0, v0, v42, vcc
	v_sqrt_f32_e32 v42, v0
	s_nop 0
	v_add_u32_e32 v43, -1, v42
	v_fma_f32 v44, -v43, v42, v0
	v_cmp_ge_f32_e64 s[2:3], 0, v44
	v_add_u32_e32 v44, 1, v42
	s_nop 0
	v_cndmask_b32_e64 v43, v42, v43, s[2:3]
	v_fma_f32 v42, -v44, v42, v0
	v_cmp_lt_f32_e64 s[2:3], 0, v42
	s_nop 1
	v_cndmask_b32_e64 v42, v43, v44, s[2:3]
	v_mul_f32_e32 v43, 0x37800000, v42
	v_cndmask_b32_e32 v42, v42, v43, vcc
	v_cmp_class_f32_e32 vcc, v0, v217
	s_nop 1
	v_cndmask_b32_e32 v0, v42, v0, vcc
	v_div_scale_f32 v42, s[0:1], v0, v0, 1.0
	v_rcp_f32_e32 v43, v42
	s_nop 0
	v_fma_f32 v44, -v42, v43, 1.0
	v_fmac_f32_e32 v43, v44, v43
	v_div_scale_f32 v44, vcc, 1.0, v0, 1.0
	v_mul_f32_e32 v45, v44, v43
	v_fma_f32 v68, -v42, v45, v44
	v_fmac_f32_e32 v45, v68, v43
	v_fma_f32 v42, -v42, v45, v44
	v_div_fmas_f32 v42, v42, v43, v45
	v_div_fixup_f32 v0, v42, v0, 1.0
	v_pk_mul_f32 v[44:45], v[48:49], v[0:1] op_sel_hi:[1,0]
	v_pk_mul_f32 v[42:43], v[54:55], v[0:1] op_sel_hi:[1,0]
	v_pk_fma_f32 v[56:57], v[50:51], v[44:45], v[56:57]
	v_pk_mul_f32 v[44:45], v[46:47], v[0:1] op_sel_hi:[1,0]
	v_pk_mul_f32 v[46:47], v[84:85], v[0:1] op_sel_hi:[1,0]
	v_pk_fma_f32 v[48:49], v[52:53], v[44:45], v[58:59]
	v_pk_fma_f32 v[60:61], v[60:61], v[46:47], v[64:65]
	v_pk_mul_f32 v[46:47], v[88:89], v[0:1] op_sel_hi:[1,0]
	s_waitcnt vmcnt(1)
	v_mov_b32_e32 v50, v76
	v_mov_b32_e32 v51, v78
	s_waitcnt vmcnt(0)
	v_mov_b32_e32 v52, v80
	v_mov_b32_e32 v53, v82
	v_pk_fma_f32 v[58:59], v[46:47], v[50:51], v[52:53]
	v_pk_mul_f32 v[46:47], v[102:103], v[0:1] op_sel_hi:[1,0]
	v_pk_mul_f32 v[44:45], v[86:87], v[0:1] op_sel_hi:[1,0]
	v_pk_fma_f32 v[54:55], v[70:71], v[46:47], v[74:75]
	v_pk_mul_f32 v[46:47], v[104:105], v[0:1] op_sel_hi:[1,0]
	v_mov_b32_e32 v78, v77
	v_mov_b32_e32 v82, v81
	v_pk_fma_f32 v[42:43], v[114:115], v[42:43], v[116:117]
	v_pk_fma_f32 v[44:45], v[62:63], v[44:45], v[66:67]
	s_and_b64 vcc, exec, s[36:37]
	v_pk_fma_f32 v[50:51], v[46:47], v[78:79], v[82:83]
	s_cbranch_vccnz .LBB0_1619
	v_cvt_pk_bf16_f32 v65, v61, v55
	v_cvt_pk_bf16_f32 v64, v60, v54
	v_cvt_pk_bf16_f32 v63, v43, v49
	v_cvt_pk_bf16_f32 v62, v42, v48
	v_lshl_add_u64 v[46:47], v[98:99], 0, s[60:61]
	global_store_dwordx4 v[46:47], v[62:65], off
	s_nop 1
	v_cvt_pk_bf16_f32 v65, v59, v51
	v_cvt_pk_bf16_f32 v64, v58, v50
	v_cvt_pk_bf16_f32 v63, v57, v45
	v_cvt_pk_bf16_f32 v62, v56, v44
	global_store_dwordx4 v[46:47], v[62:65], off offset:1024

.LBB0_1621:
	global_load_dwordx4 v[42:45], v[92:93], off
	s_nop 0
	global_load_dwordx4 v[48:51], v[94:95], off
	global_load_dwordx4 v[52:55], v[92:93], off offset:2048
	global_load_dwordx4 v[56:59], v[94:95], off offset:2048
	global_load_dwordx4 v[60:63], v[92:93], off offset:16
	global_load_dwordx4 v[64:67], v[94:95], off offset:16
	global_load_dwordx4 v[68:71], v[92:93], off offset:2064
	global_load_dwordx4 v[72:75], v[94:95], off offset:2064
	v_lshlrev_b32_e32 v46, 16, v38
	v_and_b32_e32 v38, 0xffff0000, v38
	v_add_f32_e32 v0, 0, v46
	v_lshlrev_b32_e32 v47, 16, v39
	v_add_f32_e32 v0, v0, v38
	v_and_b32_e32 v39, 0xffff0000, v39
	v_add_f32_e32 v0, v0, v47
	v_lshlrev_b32_e32 v76, 16, v40
	v_add_f32_e32 v0, v0, v39
	v_and_b32_e32 v40, 0xffff0000, v40
	v_add_f32_e32 v0, v0, v76
	v_lshlrev_b32_e32 v77, 16, v41
	v_add_f32_e32 v0, v0, v40
	v_and_b32_e32 v41, 0xffff0000, v41
	v_add_f32_e32 v0, v0, v77
	v_lshlrev_b32_e32 v78, 16, v34
	v_add_f32_e32 v0, v0, v41
	v_and_b32_e32 v34, 0xffff0000, v34
	v_add_f32_e32 v0, v0, v78
	v_lshlrev_b32_e32 v79, 16, v35
	v_add_f32_e32 v0, v0, v34
	v_and_b32_e32 v35, 0xffff0000, v35
	v_add_f32_e32 v0, v0, v79
	v_lshlrev_b32_e32 v80, 16, v36
	v_add_f32_e32 v0, v0, v35
	v_and_b32_e32 v36, 0xffff0000, v36
	v_add_f32_e32 v0, v0, v80
	v_lshlrev_b32_e32 v81, 16, v37
	v_add_f32_e32 v0, v0, v36
	v_and_b32_e32 v37, 0xffff0000, v37
	v_add_f32_e32 v0, v0, v81
	v_add_f32_e32 v0, v0, v37
	s_mov_b32 s60, 0xf800000
	s_waitcnt vmcnt(7)
	v_mov_b32_e32 v106, v42
	v_add_f32_dpp v0, v0, v0 quad_perm:[1,0,3,2] row_mask:0xf bank_mask:0xf bound_ctrl:1
	v_mov_b32_e32 v107, v44
	v_mov_b32_e32 v44, v43
	v_add_f32_dpp v0, v0, v0 quad_perm:[2,3,0,1] row_mask:0xf bank_mask:0xf bound_ctrl:1
	s_waitcnt vmcnt(5)
	v_mov_b32_e32 v42, v52
	v_mov_b32_e32 v43, v54
	v_add_f32_dpp v0, v0, v0 row_half_mirror row_mask:0xf bank_mask:0xf bound_ctrl:1
	v_mov_b32_e32 v54, v53
	v_mov_b32_e32 v108, v48
	v_add_f32_dpp v0, v0, v0 row_mirror row_mask:0xf bank_mask:0xf bound_ctrl:1
	v_mov_b32_e32 v109, v50
	v_readlane_b32 s2, v0, 16
	v_readlane_b32 s3, v0, 48
	v_readlane_b32 s0, v0, 0
	v_readlane_b32 s1, v0, 32
	v_mov_b32_e32 v82, s2
	v_mov_b32_e32 v83, s3
	v_pk_add_f32 v[82:83], s[0:1], v[82:83]
	v_mov_b32_e32 v50, v49
	v_add_f32_e32 v0, v82, v83
	v_mul_f32_e32 v0, 0x3a800000, v0
	v_pk_add_f32 v[46:47], v[46:47], v[0:1] op_sel_hi:[1,0] neg_lo:[0,1] neg_hi:[0,1]
	v_pk_add_f32 v[38:39], v[38:39], v[0:1] op_sel_hi:[1,0] neg_lo:[0,1] neg_hi:[0,1]
	v_pk_add_f32 v[82:83], v[40:41], v[0:1] op_sel_hi:[1,0] neg_lo:[0,1] neg_hi:[0,1]
	v_pk_add_f32 v[40:41], v[78:79], v[0:1] op_sel_hi:[1,0] neg_lo:[0,1] neg_hi:[0,1]
	v_pk_add_f32 v[78:79], v[34:35], v[0:1] op_sel_hi:[1,0] neg_lo:[0,1] neg_hi:[0,1]
	v_pk_add_f32 v[84:85], v[36:37], v[0:1] op_sel_hi:[1,0] neg_lo:[0,1] neg_hi:[0,1]
	v_pk_mul_f32 v[34:35], v[46:47], v[46:47]
	v_pk_mul_f32 v[36:37], v[38:39], v[38:39]
	v_pk_add_f32 v[76:77], v[76:77], v[0:1] op_sel_hi:[1,0] neg_lo:[0,1] neg_hi:[0,1]
	v_pk_add_f32 v[80:81], v[80:81], v[0:1] op_sel_hi:[1,0] neg_lo:[0,1] neg_hi:[0,1]
	v_add_f32_e32 v0, v34, v36
	v_add_f32_e32 v0, v35, v0
	v_pk_mul_f32 v[86:87], v[76:77], v[76:77]
	v_add_f32_e32 v0, v37, v0
	v_pk_mul_f32 v[88:89], v[82:83], v[82:83]
	v_add_f32_e32 v0, v86, v0
	v_add_f32_e32 v0, v88, v0
	v_add_f32_e32 v0, v87, v0
	v_add_f32_e32 v0, v89, v0
	v_mov_b32_e32 v102, v79
	v_mov_b32_e32 v103, v41
	v_fmac_f32_e32 v0, v40, v40
	v_pk_mul_f32 v[102:103], v[102:103], v[102:103]
	v_fmac_f32_e32 v0, v78, v78
	v_mov_b32_e32 v104, v84
	v_mov_b32_e32 v105, v80
	v_add_f32_e32 v0, v103, v0
	v_pk_mul_f32 v[52:53], v[104:105], v[104:105]
	v_add_f32_e32 v0, v102, v0
	s_waitcnt vmcnt(4)
	v_mov_b32_e32 v48, v56
	v_mov_b32_e32 v49, v58
	v_mov_b32_e32 v58, v57
	v_mov_b32_e32 v56, v85
	v_mov_b32_e32 v57, v81
	v_add_f32_e32 v0, v53, v0
	v_pk_mul_f32 v[56:57], v[56:57], v[56:57]
	v_add_f32_e32 v0, v52, v0
	v_add_f32_e32 v0, v57, v0
	v_add_f32_e32 v0, v56, v0
	s_waitcnt vmcnt(3)
	v_mov_b32_e32 v52, v60
	v_mov_b32_e32 v53, v62
	v_add_f32_dpp v0, v0, v0 quad_perm:[1,0,3,2] row_mask:0xf bank_mask:0xf bound_ctrl:1
	s_waitcnt vmcnt(2)
	v_mov_b32_e32 v56, v64
	v_mov_b32_e32 v57, v66
	v_add_f32_dpp v0, v0, v0 quad_perm:[2,3,0,1] row_mask:0xf bank_mask:0xf bound_ctrl:1
	v_mov_b32_e32 v62, v61
	v_mov_b32_e32 v66, v65
	v_add_f32_dpp v0, v0, v0 row_half_mirror row_mask:0xf bank_mask:0xf bound_ctrl:1
	s_nop 1
	v_add_f32_dpp v0, v0, v0 row_mirror row_mask:0xf bank_mask:0xf bound_ctrl:1
	s_nop 0
	v_readlane_b32 s2, v0, 16
	v_readlane_b32 s3, v0, 48
	v_readlane_b32 s0, v0, 0
	v_readlane_b32 s1, v0, 32
	v_mov_b32_e32 v34, s2
	v_mov_b32_e32 v35, s3
	v_pk_add_f32 v[34:35], s[0:1], v[34:35]
	s_nop 0
	v_add_f32_e32 v0, v34, v35
	v_fmamk_f32 v0, v0, 0x3a800000, v216
	v_mul_f32_e32 v34, 0x4f800000, v0
	v_cmp_gt_f32_e32 vcc, s60, v0
	s_nop 1
	v_cndmask_b32_e32 v0, v0, v34, vcc
	v_sqrt_f32_e32 v34, v0
	s_nop 0
	v_add_u32_e32 v35, -1, v34
	v_fma_f32 v36, -v35, v34, v0
	v_cmp_ge_f32_e64 s[2:3], 0, v36
	v_add_u32_e32 v36, 1, v34
	s_nop 0
	v_cndmask_b32_e64 v35, v34, v35, s[2:3]
	v_fma_f32 v34, -v36, v34, v0
	v_cmp_lt_f32_e64 s[2:3], 0, v34
	s_nop 1
	v_cndmask_b32_e64 v34, v35, v36, s[2:3]
	v_mul_f32_e32 v35, 0x37800000, v34
	v_cndmask_b32_e32 v34, v34, v35, vcc
	v_cmp_class_f32_e32 vcc, v0, v217
	s_nop 1
	v_cndmask_b32_e32 v0, v34, v0, vcc
	v_div_scale_f32 v34, s[0:1], v0, v0, 1.0
	v_rcp_f32_e32 v35, v34
	s_nop 0
	v_fma_f32 v36, -v34, v35, 1.0
	v_fmac_f32_e32 v35, v36, v35
	v_div_scale_f32 v36, vcc, 1.0, v0, 1.0
	v_mul_f32_e32 v37, v36, v35
	v_fma_f32 v60, -v34, v37, v36
	v_fmac_f32_e32 v37, v60, v35
	v_fma_f32 v34, -v34, v37, v36
	v_div_fmas_f32 v34, v34, v35, v37
	v_div_fixup_f32 v0, v34, v0, 1.0
	v_pk_mul_f32 v[36:37], v[40:41], v[0:1] op_sel_hi:[1,0]
	v_pk_mul_f32 v[34:35], v[46:47], v[0:1] op_sel_hi:[1,0]
	v_pk_fma_f32 v[48:49], v[42:43], v[36:37], v[48:49]
	v_pk_mul_f32 v[36:37], v[38:39], v[0:1] op_sel_hi:[1,0]
	v_pk_mul_f32 v[38:39], v[76:77], v[0:1] op_sel_hi:[1,0]
	v_pk_fma_f32 v[40:41], v[44:45], v[36:37], v[50:51]
	v_pk_fma_f32 v[52:53], v[52:53], v[38:39], v[56:57]
	v_pk_mul_f32 v[38:39], v[80:81], v[0:1] op_sel_hi:[1,0]
	s_waitcnt vmcnt(1)
	v_mov_b32_e32 v42, v68
	v_mov_b32_e32 v43, v70
	s_waitcnt vmcnt(0)
	v_mov_b32_e32 v44, v72
	v_mov_b32_e32 v45, v74
	v_pk_fma_f32 v[50:51], v[38:39], v[42:43], v[44:45]
	v_pk_mul_f32 v[38:39], v[82:83], v[0:1] op_sel_hi:[1,0]
	v_pk_mul_f32 v[36:37], v[78:79], v[0:1] op_sel_hi:[1,0]
	v_pk_fma_f32 v[46:47], v[62:63], v[38:39], v[66:67]
	v_pk_mul_f32 v[38:39], v[84:85], v[0:1] op_sel_hi:[1,0]
	v_mov_b32_e32 v70, v69
	v_mov_b32_e32 v74, v73
	v_pk_fma_f32 v[34:35], v[106:107], v[34:35], v[108:109]
	v_pk_fma_f32 v[36:37], v[54:55], v[36:37], v[58:59]
	s_and_b64 vcc, exec, s[36:37]
	v_pk_fma_f32 v[42:43], v[38:39], v[70:71], v[74:75]
	s_cbranch_vccnz .LBB0_1623
	v_cvt_pk_bf16_f32 v57, v53, v47
	v_cvt_pk_bf16_f32 v56, v52, v46
	v_cvt_pk_bf16_f32 v55, v35, v41
	v_cvt_pk_bf16_f32 v54, v34, v40
	v_lshl_add_u64 v[38:39], v[98:99], 0, s[28:29]
	global_store_dwordx4 v[38:39], v[54:57], off
	s_nop 1
	v_cvt_pk_bf16_f32 v57, v51, v43
	v_cvt_pk_bf16_f32 v56, v50, v42
	v_cvt_pk_bf16_f32 v55, v49, v37
	v_cvt_pk_bf16_f32 v54, v48, v36
	global_store_dwordx4 v[38:39], v[54:57], off offset:1024

.LBB0_1625:
	global_load_dwordx4 v[34:37], v[92:93], off
	s_nop 0
	global_load_dwordx4 v[40:43], v[94:95], off
	global_load_dwordx4 v[44:47], v[92:93], off offset:2048
	global_load_dwordx4 v[48:51], v[94:95], off offset:2048
	global_load_dwordx4 v[52:55], v[92:93], off offset:16
	global_load_dwordx4 v[56:59], v[94:95], off offset:16
	global_load_dwordx4 v[60:63], v[92:93], off offset:2064
	global_load_dwordx4 v[64:67], v[94:95], off offset:2064
	v_lshlrev_b32_e32 v38, 16, v30
	v_and_b32_e32 v30, 0xffff0000, v30
	v_add_f32_e32 v0, 0, v38
	v_lshlrev_b32_e32 v39, 16, v31
	v_add_f32_e32 v0, v0, v30
	v_and_b32_e32 v31, 0xffff0000, v31
	v_add_f32_e32 v0, v0, v39
	v_lshlrev_b32_e32 v68, 16, v32
	v_add_f32_e32 v0, v0, v31
	v_and_b32_e32 v32, 0xffff0000, v32
	v_add_f32_e32 v0, v0, v68
	v_lshlrev_b32_e32 v69, 16, v33
	v_add_f32_e32 v0, v0, v32
	v_and_b32_e32 v33, 0xffff0000, v33
	v_add_f32_e32 v0, v0, v69
	v_lshlrev_b32_e32 v70, 16, v26
	v_add_f32_e32 v0, v0, v33
	v_and_b32_e32 v26, 0xffff0000, v26
	v_add_f32_e32 v0, v0, v70
	v_lshlrev_b32_e32 v71, 16, v27
	v_add_f32_e32 v0, v0, v26
	v_and_b32_e32 v27, 0xffff0000, v27
	v_add_f32_e32 v0, v0, v71
	v_lshlrev_b32_e32 v72, 16, v28
	v_add_f32_e32 v0, v0, v27
	v_and_b32_e32 v28, 0xffff0000, v28
	v_add_f32_e32 v0, v0, v72
	v_lshlrev_b32_e32 v73, 16, v29
	v_add_f32_e32 v0, v0, v28
	v_and_b32_e32 v29, 0xffff0000, v29
	v_add_f32_e32 v0, v0, v73
	v_add_f32_e32 v0, v0, v29
	s_waitcnt vmcnt(7)
	v_mov_b32_e32 v86, v34
	v_add_f32_dpp v0, v0, v0 quad_perm:[1,0,3,2] row_mask:0xf bank_mask:0xf bound_ctrl:1
	v_mov_b32_e32 v87, v36
	v_mov_b32_e32 v36, v35
	v_add_f32_dpp v0, v0, v0 quad_perm:[2,3,0,1] row_mask:0xf bank_mask:0xf bound_ctrl:1
	s_waitcnt vmcnt(5)
	v_mov_b32_e32 v34, v44
	v_mov_b32_e32 v35, v46
	v_add_f32_dpp v0, v0, v0 row_half_mirror row_mask:0xf bank_mask:0xf bound_ctrl:1
	v_mov_b32_e32 v46, v45
	v_mov_b32_e32 v88, v40
	v_add_f32_dpp v0, v0, v0 row_mirror row_mask:0xf bank_mask:0xf bound_ctrl:1
	v_mov_b32_e32 v89, v42
	v_readlane_b32 s2, v0, 16
	v_readlane_b32 s3, v0, 48
	v_readlane_b32 s0, v0, 0
	v_readlane_b32 s1, v0, 32
	v_mov_b32_e32 v74, s2
	v_mov_b32_e32 v75, s3
	v_pk_add_f32 v[74:75], s[0:1], v[74:75]
	v_mov_b32_e32 v42, v41
	v_add_f32_e32 v0, v74, v75
	v_mul_f32_e32 v0, 0x3a800000, v0
	v_pk_add_f32 v[38:39], v[38:39], v[0:1] op_sel_hi:[1,0] neg_lo:[0,1] neg_hi:[0,1]
	v_pk_add_f32 v[30:31], v[30:31], v[0:1] op_sel_hi:[1,0] neg_lo:[0,1] neg_hi:[0,1]
	v_pk_add_f32 v[74:75], v[32:33], v[0:1] op_sel_hi:[1,0] neg_lo:[0,1] neg_hi:[0,1]
	v_pk_add_f32 v[32:33], v[70:71], v[0:1] op_sel_hi:[1,0] neg_lo:[0,1] neg_hi:[0,1]
	v_pk_add_f32 v[70:71], v[26:27], v[0:1] op_sel_hi:[1,0] neg_lo:[0,1] neg_hi:[0,1]
	v_pk_add_f32 v[76:77], v[28:29], v[0:1] op_sel_hi:[1,0] neg_lo:[0,1] neg_hi:[0,1]
	v_pk_mul_f32 v[26:27], v[38:39], v[38:39]
	v_pk_mul_f32 v[28:29], v[30:31], v[30:31]
	v_pk_add_f32 v[68:69], v[68:69], v[0:1] op_sel_hi:[1,0] neg_lo:[0,1] neg_hi:[0,1]
	v_pk_add_f32 v[72:73], v[72:73], v[0:1] op_sel_hi:[1,0] neg_lo:[0,1] neg_hi:[0,1]
	v_add_f32_e32 v0, v26, v28
	v_add_f32_e32 v0, v27, v0
	v_pk_mul_f32 v[78:79], v[68:69], v[68:69]
	v_add_f32_e32 v0, v29, v0
	v_pk_mul_f32 v[80:81], v[74:75], v[74:75]
	v_add_f32_e32 v0, v78, v0
	v_add_f32_e32 v0, v80, v0
	v_add_f32_e32 v0, v79, v0
	v_add_f32_e32 v0, v81, v0
	v_mov_b32_e32 v82, v71
	v_mov_b32_e32 v83, v33
	v_fmac_f32_e32 v0, v32, v32
	v_pk_mul_f32 v[82:83], v[82:83], v[82:83]
	v_fmac_f32_e32 v0, v70, v70
	v_mov_b32_e32 v84, v76
	v_mov_b32_e32 v85, v72
	v_add_f32_e32 v0, v83, v0
	v_pk_mul_f32 v[44:45], v[84:85], v[84:85]
	v_add_f32_e32 v0, v82, v0
	s_waitcnt vmcnt(4)
	v_mov_b32_e32 v40, v48
	v_mov_b32_e32 v41, v50
	v_mov_b32_e32 v50, v49
	v_mov_b32_e32 v48, v77
	v_mov_b32_e32 v49, v73
	v_add_f32_e32 v0, v45, v0
	v_pk_mul_f32 v[48:49], v[48:49], v[48:49]
	v_add_f32_e32 v0, v44, v0
	v_add_f32_e32 v0, v49, v0
	v_add_f32_e32 v0, v48, v0
	s_waitcnt vmcnt(3)
	v_mov_b32_e32 v44, v52
	v_mov_b32_e32 v45, v54
	v_add_f32_dpp v0, v0, v0 quad_perm:[1,0,3,2] row_mask:0xf bank_mask:0xf bound_ctrl:1
	s_waitcnt vmcnt(2)
	v_mov_b32_e32 v48, v56
	v_mov_b32_e32 v49, v58
	v_add_f32_dpp v0, v0, v0 quad_perm:[2,3,0,1] row_mask:0xf bank_mask:0xf bound_ctrl:1
	v_mov_b32_e32 v54, v53
	v_mov_b32_e32 v58, v57
	v_add_f32_dpp v0, v0, v0 row_half_mirror row_mask:0xf bank_mask:0xf bound_ctrl:1
	s_nop 1
	v_add_f32_dpp v0, v0, v0 row_mirror row_mask:0xf bank_mask:0xf bound_ctrl:1
	s_nop 0
	v_readlane_b32 s2, v0, 16
	v_readlane_b32 s3, v0, 48
	v_readlane_b32 s0, v0, 0
	v_readlane_b32 s1, v0, 32
	v_mov_b32_e32 v26, s2
	v_mov_b32_e32 v27, s3
	v_pk_add_f32 v[26:27], s[0:1], v[26:27]
	s_nop 0
	v_add_f32_e32 v0, v26, v27
	v_fmamk_f32 v0, v0, 0x3a800000, v216
	v_mul_f32_e32 v26, 0x4f800000, v0
	v_cmp_gt_f32_e32 vcc, s60, v0
	s_nop 1
	v_cndmask_b32_e32 v0, v0, v26, vcc
	v_sqrt_f32_e32 v26, v0
	s_nop 0
	v_add_u32_e32 v27, -1, v26
	v_fma_f32 v28, -v27, v26, v0
	v_cmp_ge_f32_e64 s[2:3], 0, v28
	v_add_u32_e32 v28, 1, v26
	s_nop 0
	v_cndmask_b32_e64 v27, v26, v27, s[2:3]
	v_fma_f32 v26, -v28, v26, v0
	v_cmp_lt_f32_e64 s[2:3], 0, v26
	s_nop 1
	v_cndmask_b32_e64 v26, v27, v28, s[2:3]
	v_mul_f32_e32 v27, 0x37800000, v26
	v_cndmask_b32_e32 v26, v26, v27, vcc
	v_cmp_class_f32_e32 vcc, v0, v217
	s_nop 1
	v_cndmask_b32_e32 v0, v26, v0, vcc
	v_div_scale_f32 v26, s[0:1], v0, v0, 1.0
	v_rcp_f32_e32 v27, v26
	s_nop 0
	v_fma_f32 v28, -v26, v27, 1.0
	v_fmac_f32_e32 v27, v28, v27
	v_div_scale_f32 v28, vcc, 1.0, v0, 1.0
	v_mul_f32_e32 v29, v28, v27
	v_fma_f32 v52, -v26, v29, v28
	v_fmac_f32_e32 v29, v52, v27
	v_fma_f32 v26, -v26, v29, v28
	v_div_fmas_f32 v26, v26, v27, v29
	v_div_fixup_f32 v0, v26, v0, 1.0
	v_pk_mul_f32 v[28:29], v[32:33], v[0:1] op_sel_hi:[1,0]
	v_pk_mul_f32 v[26:27], v[38:39], v[0:1] op_sel_hi:[1,0]
	v_pk_fma_f32 v[40:41], v[34:35], v[28:29], v[40:41]
	v_pk_mul_f32 v[28:29], v[30:31], v[0:1] op_sel_hi:[1,0]
	v_pk_mul_f32 v[30:31], v[68:69], v[0:1] op_sel_hi:[1,0]
	v_pk_fma_f32 v[32:33], v[36:37], v[28:29], v[42:43]
	v_pk_fma_f32 v[44:45], v[44:45], v[30:31], v[48:49]
	v_pk_mul_f32 v[30:31], v[72:73], v[0:1] op_sel_hi:[1,0]
	s_waitcnt vmcnt(1)
	v_mov_b32_e32 v34, v60
	v_mov_b32_e32 v35, v62
	s_waitcnt vmcnt(0)
	v_mov_b32_e32 v36, v64
	v_mov_b32_e32 v37, v66
	v_pk_fma_f32 v[42:43], v[30:31], v[34:35], v[36:37]
	v_pk_mul_f32 v[30:31], v[74:75], v[0:1] op_sel_hi:[1,0]
	v_pk_mul_f32 v[28:29], v[70:71], v[0:1] op_sel_hi:[1,0]
	v_pk_fma_f32 v[38:39], v[54:55], v[30:31], v[58:59]
	v_pk_mul_f32 v[30:31], v[76:77], v[0:1] op_sel_hi:[1,0]
	v_mov_b32_e32 v62, v61
	v_mov_b32_e32 v66, v65
	v_pk_fma_f32 v[26:27], v[86:87], v[26:27], v[88:89]
	v_pk_fma_f32 v[28:29], v[46:47], v[28:29], v[50:51]
	s_and_b64 vcc, exec, s[36:37]
	v_pk_fma_f32 v[34:35], v[30:31], v[62:63], v[66:67]
	s_cbranch_vccnz .LBB0_1627
	v_cvt_pk_bf16_f32 v49, v45, v39
	v_cvt_pk_bf16_f32 v48, v44, v38
	v_cvt_pk_bf16_f32 v47, v27, v33
	v_cvt_pk_bf16_f32 v46, v26, v32
	v_lshl_add_u64 v[30:31], v[98:99], 0, s[58:59]
	global_store_dwordx4 v[30:31], v[46:49], off
	s_nop 1
	v_cvt_pk_bf16_f32 v49, v43, v35
	v_cvt_pk_bf16_f32 v48, v42, v34
	v_cvt_pk_bf16_f32 v47, v41, v29
	v_cvt_pk_bf16_f32 v46, v40, v28
	global_store_dwordx4 v[30:31], v[46:49], off offset:1024

.LBB0_1629:
	global_load_dwordx4 v[26:29], v[92:93], off
	s_nop 0
	global_load_dwordx4 v[32:35], v[94:95], off
	global_load_dwordx4 v[36:39], v[92:93], off offset:2048
	global_load_dwordx4 v[40:43], v[94:95], off offset:2048
	global_load_dwordx4 v[44:47], v[92:93], off offset:16
	global_load_dwordx4 v[48:51], v[94:95], off offset:16
	global_load_dwordx4 v[52:55], v[92:93], off offset:2064
	global_load_dwordx4 v[56:59], v[94:95], off offset:2064
	v_lshlrev_b32_e32 v30, 16, v22
	v_and_b32_e32 v22, 0xffff0000, v22
	v_add_f32_e32 v0, 0, v30
	v_lshlrev_b32_e32 v31, 16, v23
	v_add_f32_e32 v0, v0, v22
	v_and_b32_e32 v23, 0xffff0000, v23
	v_add_f32_e32 v0, v0, v31
	v_lshlrev_b32_e32 v60, 16, v24
	v_add_f32_e32 v0, v0, v23
	v_and_b32_e32 v24, 0xffff0000, v24
	v_add_f32_e32 v0, v0, v60
	v_lshlrev_b32_e32 v61, 16, v25
	v_add_f32_e32 v0, v0, v24
	v_and_b32_e32 v25, 0xffff0000, v25
	v_add_f32_e32 v0, v0, v61
	v_lshlrev_b32_e32 v62, 16, v18
	v_add_f32_e32 v0, v0, v25
	v_and_b32_e32 v18, 0xffff0000, v18
	v_add_f32_e32 v0, v0, v62
	v_lshlrev_b32_e32 v63, 16, v19
	v_add_f32_e32 v0, v0, v18
	v_and_b32_e32 v19, 0xffff0000, v19
	v_add_f32_e32 v0, v0, v63
	v_lshlrev_b32_e32 v64, 16, v20
	v_add_f32_e32 v0, v0, v19
	v_and_b32_e32 v20, 0xffff0000, v20
	v_add_f32_e32 v0, v0, v64
	v_lshlrev_b32_e32 v65, 16, v21
	v_add_f32_e32 v0, v0, v20
	v_and_b32_e32 v21, 0xffff0000, v21
	v_add_f32_e32 v0, v0, v65
	v_add_f32_e32 v0, v0, v21
	s_waitcnt vmcnt(7)
	v_mov_b32_e32 v78, v26
	v_add_f32_dpp v0, v0, v0 quad_perm:[1,0,3,2] row_mask:0xf bank_mask:0xf bound_ctrl:1
	v_mov_b32_e32 v79, v28
	v_mov_b32_e32 v28, v27
	v_add_f32_dpp v0, v0, v0 quad_perm:[2,3,0,1] row_mask:0xf bank_mask:0xf bound_ctrl:1
	s_waitcnt vmcnt(5)
	v_mov_b32_e32 v26, v36
	v_mov_b32_e32 v27, v38
	v_add_f32_dpp v0, v0, v0 row_half_mirror row_mask:0xf bank_mask:0xf bound_ctrl:1
	v_mov_b32_e32 v38, v37
	v_mov_b32_e32 v80, v32
	v_add_f32_dpp v0, v0, v0 row_mirror row_mask:0xf bank_mask:0xf bound_ctrl:1
	v_mov_b32_e32 v81, v34
	v_readlane_b32 s2, v0, 16
	v_readlane_b32 s3, v0, 48
	v_readlane_b32 s0, v0, 0
	v_readlane_b32 s1, v0, 32
	v_mov_b32_e32 v66, s2
	v_mov_b32_e32 v67, s3
	v_pk_add_f32 v[66:67], s[0:1], v[66:67]
	v_mov_b32_e32 v34, v33
	v_add_f32_e32 v0, v66, v67
	v_mul_f32_e32 v0, 0x3a800000, v0
	v_pk_add_f32 v[30:31], v[30:31], v[0:1] op_sel_hi:[1,0] neg_lo:[0,1] neg_hi:[0,1]
	v_pk_add_f32 v[22:23], v[22:23], v[0:1] op_sel_hi:[1,0] neg_lo:[0,1] neg_hi:[0,1]
	v_pk_add_f32 v[66:67], v[24:25], v[0:1] op_sel_hi:[1,0] neg_lo:[0,1] neg_hi:[0,1]
	v_pk_add_f32 v[24:25], v[62:63], v[0:1] op_sel_hi:[1,0] neg_lo:[0,1] neg_hi:[0,1]
	v_pk_add_f32 v[62:63], v[18:19], v[0:1] op_sel_hi:[1,0] neg_lo:[0,1] neg_hi:[0,1]
	v_pk_add_f32 v[68:69], v[20:21], v[0:1] op_sel_hi:[1,0] neg_lo:[0,1] neg_hi:[0,1]
	v_pk_mul_f32 v[18:19], v[30:31], v[30:31]
	v_pk_mul_f32 v[20:21], v[22:23], v[22:23]
	v_pk_add_f32 v[60:61], v[60:61], v[0:1] op_sel_hi:[1,0] neg_lo:[0,1] neg_hi:[0,1]
	v_pk_add_f32 v[64:65], v[64:65], v[0:1] op_sel_hi:[1,0] neg_lo:[0,1] neg_hi:[0,1]
	v_add_f32_e32 v0, v18, v20
	v_add_f32_e32 v0, v19, v0
	v_pk_mul_f32 v[70:71], v[60:61], v[60:61]
	v_add_f32_e32 v0, v21, v0
	v_pk_mul_f32 v[72:73], v[66:67], v[66:67]
	v_add_f32_e32 v0, v70, v0
	v_add_f32_e32 v0, v72, v0
	v_add_f32_e32 v0, v71, v0
	v_add_f32_e32 v0, v73, v0
	v_mov_b32_e32 v74, v63
	v_mov_b32_e32 v75, v25
	v_fmac_f32_e32 v0, v24, v24
	v_pk_mul_f32 v[74:75], v[74:75], v[74:75]
	v_fmac_f32_e32 v0, v62, v62
	v_mov_b32_e32 v76, v68
	v_mov_b32_e32 v77, v64
	v_add_f32_e32 v0, v75, v0
	v_pk_mul_f32 v[36:37], v[76:77], v[76:77]
	v_add_f32_e32 v0, v74, v0
	s_waitcnt vmcnt(4)
	v_mov_b32_e32 v32, v40
	v_mov_b32_e32 v33, v42
	v_mov_b32_e32 v42, v41
	v_mov_b32_e32 v40, v69
	v_mov_b32_e32 v41, v65
	v_add_f32_e32 v0, v37, v0
	v_pk_mul_f32 v[40:41], v[40:41], v[40:41]
	v_add_f32_e32 v0, v36, v0
	v_add_f32_e32 v0, v41, v0
	v_add_f32_e32 v0, v40, v0
	s_waitcnt vmcnt(3)
	v_mov_b32_e32 v36, v44
	v_mov_b32_e32 v37, v46
	v_add_f32_dpp v0, v0, v0 quad_perm:[1,0,3,2] row_mask:0xf bank_mask:0xf bound_ctrl:1
	s_waitcnt vmcnt(2)
	v_mov_b32_e32 v40, v48
	v_mov_b32_e32 v41, v50
	v_add_f32_dpp v0, v0, v0 quad_perm:[2,3,0,1] row_mask:0xf bank_mask:0xf bound_ctrl:1
	v_mov_b32_e32 v46, v45
	v_mov_b32_e32 v50, v49
	v_add_f32_dpp v0, v0, v0 row_half_mirror row_mask:0xf bank_mask:0xf bound_ctrl:1
	s_nop 1
	v_add_f32_dpp v0, v0, v0 row_mirror row_mask:0xf bank_mask:0xf bound_ctrl:1
	s_nop 0
	v_readlane_b32 s2, v0, 16
	v_readlane_b32 s3, v0, 48
	v_readlane_b32 s0, v0, 0
	v_readlane_b32 s1, v0, 32
	v_mov_b32_e32 v18, s2
	v_mov_b32_e32 v19, s3
	v_pk_add_f32 v[18:19], s[0:1], v[18:19]
	s_nop 0
	v_add_f32_e32 v0, v18, v19
	v_fmamk_f32 v0, v0, 0x3a800000, v216
	v_mul_f32_e32 v18, 0x4f800000, v0
	v_cmp_gt_f32_e32 vcc, s60, v0
	s_nop 1
	v_cndmask_b32_e32 v0, v0, v18, vcc
	v_sqrt_f32_e32 v18, v0
	s_nop 0
	v_add_u32_e32 v19, -1, v18
	v_fma_f32 v20, -v19, v18, v0
	v_cmp_ge_f32_e64 s[2:3], 0, v20
	v_add_u32_e32 v20, 1, v18
	s_nop 0
	v_cndmask_b32_e64 v19, v18, v19, s[2:3]
	v_fma_f32 v18, -v20, v18, v0
	v_cmp_lt_f32_e64 s[2:3], 0, v18
	s_nop 1
	v_cndmask_b32_e64 v18, v19, v20, s[2:3]
	v_mul_f32_e32 v19, 0x37800000, v18
	v_cndmask_b32_e32 v18, v18, v19, vcc
	v_cmp_class_f32_e32 vcc, v0, v217
	s_nop 1
	v_cndmask_b32_e32 v0, v18, v0, vcc
	v_div_scale_f32 v18, s[0:1], v0, v0, 1.0
	v_rcp_f32_e32 v19, v18
	s_nop 0
	v_fma_f32 v20, -v18, v19, 1.0
	v_fmac_f32_e32 v19, v20, v19
	v_div_scale_f32 v20, vcc, 1.0, v0, 1.0
	v_mul_f32_e32 v21, v20, v19
	v_fma_f32 v44, -v18, v21, v20
	v_fmac_f32_e32 v21, v44, v19
	v_fma_f32 v18, -v18, v21, v20
	v_div_fmas_f32 v18, v18, v19, v21
	v_div_fixup_f32 v0, v18, v0, 1.0
	v_pk_mul_f32 v[20:21], v[24:25], v[0:1] op_sel_hi:[1,0]
	v_pk_mul_f32 v[18:19], v[30:31], v[0:1] op_sel_hi:[1,0]
	v_pk_fma_f32 v[32:33], v[26:27], v[20:21], v[32:33]
	v_pk_mul_f32 v[20:21], v[22:23], v[0:1] op_sel_hi:[1,0]
	v_pk_mul_f32 v[22:23], v[60:61], v[0:1] op_sel_hi:[1,0]
	v_pk_fma_f32 v[24:25], v[28:29], v[20:21], v[34:35]
	v_pk_fma_f32 v[36:37], v[36:37], v[22:23], v[40:41]
	v_pk_mul_f32 v[22:23], v[64:65], v[0:1] op_sel_hi:[1,0]
	s_waitcnt vmcnt(1)
	v_mov_b32_e32 v26, v52
	v_mov_b32_e32 v27, v54
	s_waitcnt vmcnt(0)
	v_mov_b32_e32 v28, v56
	v_mov_b32_e32 v29, v58
	v_pk_fma_f32 v[34:35], v[22:23], v[26:27], v[28:29]
	v_pk_mul_f32 v[22:23], v[66:67], v[0:1] op_sel_hi:[1,0]
	v_pk_mul_f32 v[20:21], v[62:63], v[0:1] op_sel_hi:[1,0]
	v_pk_fma_f32 v[30:31], v[46:47], v[22:23], v[50:51]
	v_pk_mul_f32 v[22:23], v[68:69], v[0:1] op_sel_hi:[1,0]
	v_mov_b32_e32 v54, v53
	v_mov_b32_e32 v58, v57
	v_pk_fma_f32 v[18:19], v[78:79], v[18:19], v[80:81]
	v_pk_fma_f32 v[20:21], v[38:39], v[20:21], v[42:43]
	s_and_b64 vcc, exec, s[36:37]
	v_pk_fma_f32 v[26:27], v[22:23], v[54:55], v[58:59]
	s_cbranch_vccnz .LBB0_1631
	v_cvt_pk_bf16_f32 v41, v37, v31
	v_cvt_pk_bf16_f32 v40, v36, v30
	v_cvt_pk_bf16_f32 v39, v19, v25
	v_cvt_pk_bf16_f32 v38, v18, v24
	v_lshl_add_u64 v[22:23], v[98:99], 0, s[54:55]
	global_store_dwordx4 v[22:23], v[38:41], off
	s_nop 1
	v_cvt_pk_bf16_f32 v41, v35, v27
	v_cvt_pk_bf16_f32 v40, v34, v26
	v_cvt_pk_bf16_f32 v39, v33, v21
	v_cvt_pk_bf16_f32 v38, v32, v20
	global_store_dwordx4 v[22:23], v[38:41], off offset:1024

.LBB0_1633:
	global_load_dwordx4 v[18:21], v[92:93], off
	s_nop 0
	global_load_dwordx4 v[24:27], v[94:95], off
	global_load_dwordx4 v[28:31], v[92:93], off offset:2048
	global_load_dwordx4 v[32:35], v[94:95], off offset:2048
	global_load_dwordx4 v[36:39], v[92:93], off offset:16
	global_load_dwordx4 v[40:43], v[94:95], off offset:16
	global_load_dwordx4 v[44:47], v[92:93], off offset:2064
	global_load_dwordx4 v[48:51], v[94:95], off offset:2064
	v_lshlrev_b32_e32 v22, 16, v14
	v_and_b32_e32 v14, 0xffff0000, v14
	v_add_f32_e32 v0, 0, v22
	v_lshlrev_b32_e32 v23, 16, v15
	v_add_f32_e32 v0, v0, v14
	v_and_b32_e32 v15, 0xffff0000, v15
	v_add_f32_e32 v0, v0, v23
	v_lshlrev_b32_e32 v52, 16, v16
	v_add_f32_e32 v0, v0, v15
	v_and_b32_e32 v16, 0xffff0000, v16
	v_add_f32_e32 v0, v0, v52
	v_lshlrev_b32_e32 v53, 16, v17
	v_add_f32_e32 v0, v0, v16
	v_and_b32_e32 v17, 0xffff0000, v17
	v_add_f32_e32 v0, v0, v53
	v_lshlrev_b32_e32 v54, 16, v10
	v_add_f32_e32 v0, v0, v17
	v_and_b32_e32 v10, 0xffff0000, v10
	v_add_f32_e32 v0, v0, v54
	v_lshlrev_b32_e32 v55, 16, v11
	v_add_f32_e32 v0, v0, v10
	v_and_b32_e32 v11, 0xffff0000, v11
	v_add_f32_e32 v0, v0, v55
	v_lshlrev_b32_e32 v56, 16, v12
	v_add_f32_e32 v0, v0, v11
	v_and_b32_e32 v12, 0xffff0000, v12
	v_add_f32_e32 v0, v0, v56
	v_lshlrev_b32_e32 v57, 16, v13
	v_add_f32_e32 v0, v0, v12
	v_and_b32_e32 v13, 0xffff0000, v13
	v_add_f32_e32 v0, v0, v57
	v_add_f32_e32 v0, v0, v13
	s_mov_b32 s55, 0x42ce8ed0
	s_waitcnt vmcnt(7)
	v_mov_b32_e32 v70, v18
	v_add_f32_dpp v0, v0, v0 quad_perm:[1,0,3,2] row_mask:0xf bank_mask:0xf bound_ctrl:1
	v_mov_b32_e32 v71, v20
	v_mov_b32_e32 v20, v19
	v_add_f32_dpp v0, v0, v0 quad_perm:[2,3,0,1] row_mask:0xf bank_mask:0xf bound_ctrl:1
	s_waitcnt vmcnt(5)
	v_mov_b32_e32 v18, v28
	v_mov_b32_e32 v19, v30
	v_add_f32_dpp v0, v0, v0 row_half_mirror row_mask:0xf bank_mask:0xf bound_ctrl:1
	v_mov_b32_e32 v30, v29
	v_mov_b32_e32 v72, v24
	v_add_f32_dpp v0, v0, v0 row_mirror row_mask:0xf bank_mask:0xf bound_ctrl:1
	v_mov_b32_e32 v73, v26
	v_readlane_b32 s2, v0, 16
	v_readlane_b32 s3, v0, 48
	v_readlane_b32 s0, v0, 0
	v_readlane_b32 s1, v0, 32
	v_mov_b32_e32 v58, s2
	v_mov_b32_e32 v59, s3
	v_pk_add_f32 v[58:59], s[0:1], v[58:59]
	v_mov_b32_e32 v26, v25
	v_add_f32_e32 v0, v58, v59
	v_mul_f32_e32 v0, 0x3a800000, v0
	v_pk_add_f32 v[22:23], v[22:23], v[0:1] op_sel_hi:[1,0] neg_lo:[0,1] neg_hi:[0,1]
	v_pk_add_f32 v[14:15], v[14:15], v[0:1] op_sel_hi:[1,0] neg_lo:[0,1] neg_hi:[0,1]
	v_pk_add_f32 v[58:59], v[16:17], v[0:1] op_sel_hi:[1,0] neg_lo:[0,1] neg_hi:[0,1]
	v_pk_add_f32 v[16:17], v[54:55], v[0:1] op_sel_hi:[1,0] neg_lo:[0,1] neg_hi:[0,1]
	v_pk_add_f32 v[54:55], v[10:11], v[0:1] op_sel_hi:[1,0] neg_lo:[0,1] neg_hi:[0,1]
	v_pk_add_f32 v[60:61], v[12:13], v[0:1] op_sel_hi:[1,0] neg_lo:[0,1] neg_hi:[0,1]
	v_pk_mul_f32 v[10:11], v[22:23], v[22:23]
	v_pk_mul_f32 v[12:13], v[14:15], v[14:15]
	v_pk_add_f32 v[52:53], v[52:53], v[0:1] op_sel_hi:[1,0] neg_lo:[0,1] neg_hi:[0,1]
	v_pk_add_f32 v[56:57], v[56:57], v[0:1] op_sel_hi:[1,0] neg_lo:[0,1] neg_hi:[0,1]
	v_add_f32_e32 v0, v10, v12
	v_add_f32_e32 v0, v11, v0
	v_pk_mul_f32 v[62:63], v[52:53], v[52:53]
	v_add_f32_e32 v0, v13, v0
	v_pk_mul_f32 v[64:65], v[58:59], v[58:59]
	v_add_f32_e32 v0, v62, v0
	v_add_f32_e32 v0, v64, v0
	v_add_f32_e32 v0, v63, v0
	v_add_f32_e32 v0, v65, v0
	v_mov_b32_e32 v66, v55
	v_mov_b32_e32 v67, v17
	v_fmac_f32_e32 v0, v16, v16
	v_pk_mul_f32 v[66:67], v[66:67], v[66:67]
	v_fmac_f32_e32 v0, v54, v54
	v_mov_b32_e32 v68, v60
	v_mov_b32_e32 v69, v56
	v_add_f32_e32 v0, v67, v0
	v_pk_mul_f32 v[28:29], v[68:69], v[68:69]
	v_add_f32_e32 v0, v66, v0
	s_waitcnt vmcnt(4)
	v_mov_b32_e32 v24, v32
	v_mov_b32_e32 v25, v34
	v_mov_b32_e32 v34, v33
	v_mov_b32_e32 v32, v61
	v_mov_b32_e32 v33, v57
	v_add_f32_e32 v0, v29, v0
	v_pk_mul_f32 v[32:33], v[32:33], v[32:33]
	v_add_f32_e32 v0, v28, v0
	v_add_f32_e32 v0, v33, v0
	v_add_f32_e32 v0, v32, v0
	s_waitcnt vmcnt(3)
	v_mov_b32_e32 v28, v36
	v_mov_b32_e32 v29, v38
	v_add_f32_dpp v0, v0, v0 quad_perm:[1,0,3,2] row_mask:0xf bank_mask:0xf bound_ctrl:1
	s_waitcnt vmcnt(2)
	v_mov_b32_e32 v32, v40
	v_mov_b32_e32 v33, v42
	v_add_f32_dpp v0, v0, v0 quad_perm:[2,3,0,1] row_mask:0xf bank_mask:0xf bound_ctrl:1
	v_mov_b32_e32 v38, v37
	v_mov_b32_e32 v42, v41
	v_add_f32_dpp v0, v0, v0 row_half_mirror row_mask:0xf bank_mask:0xf bound_ctrl:1
	s_nop 1
	v_add_f32_dpp v0, v0, v0 row_mirror row_mask:0xf bank_mask:0xf bound_ctrl:1
	s_nop 0
	v_readlane_b32 s2, v0, 16
	v_readlane_b32 s3, v0, 48
	v_readlane_b32 s0, v0, 0
	v_readlane_b32 s1, v0, 32
	v_mov_b32_e32 v10, s2
	v_mov_b32_e32 v11, s3
	v_pk_add_f32 v[10:11], s[0:1], v[10:11]
	s_nop 0
	v_add_f32_e32 v0, v10, v11
	v_fmamk_f32 v0, v0, 0x3a800000, v216
	v_mul_f32_e32 v10, 0x4f800000, v0
	v_cmp_gt_f32_e32 vcc, s60, v0
	s_nop 1
	v_cndmask_b32_e32 v0, v0, v10, vcc
	v_sqrt_f32_e32 v10, v0
	s_nop 0
	v_add_u32_e32 v11, -1, v10
	v_fma_f32 v12, -v11, v10, v0
	v_cmp_ge_f32_e64 s[2:3], 0, v12
	v_add_u32_e32 v12, 1, v10
	s_nop 0
	v_cndmask_b32_e64 v11, v10, v11, s[2:3]
	v_fma_f32 v10, -v12, v10, v0
	v_cmp_lt_f32_e64 s[2:3], 0, v10
	s_nop 1
	v_cndmask_b32_e64 v10, v11, v12, s[2:3]
	v_mul_f32_e32 v11, 0x37800000, v10
	v_cndmask_b32_e32 v10, v10, v11, vcc
	v_cmp_class_f32_e32 vcc, v0, v217
	s_nop 1
	v_cndmask_b32_e32 v0, v10, v0, vcc
	v_div_scale_f32 v10, s[0:1], v0, v0, 1.0
	v_rcp_f32_e32 v11, v10
	s_nop 0
	v_fma_f32 v12, -v10, v11, 1.0
	v_fmac_f32_e32 v11, v12, v11
	v_div_scale_f32 v12, vcc, 1.0, v0, 1.0
	v_mul_f32_e32 v13, v12, v11
	v_fma_f32 v36, -v10, v13, v12
	v_fmac_f32_e32 v13, v36, v11
	v_fma_f32 v10, -v10, v13, v12
	v_div_fmas_f32 v10, v10, v11, v13
	v_div_fixup_f32 v0, v10, v0, 1.0
	v_pk_mul_f32 v[12:13], v[16:17], v[0:1] op_sel_hi:[1,0]
	v_pk_mul_f32 v[10:11], v[22:23], v[0:1] op_sel_hi:[1,0]
	v_pk_fma_f32 v[24:25], v[18:19], v[12:13], v[24:25]
	v_pk_mul_f32 v[12:13], v[14:15], v[0:1] op_sel_hi:[1,0]
	v_pk_mul_f32 v[14:15], v[52:53], v[0:1] op_sel_hi:[1,0]
	v_pk_fma_f32 v[16:17], v[20:21], v[12:13], v[26:27]
	v_pk_fma_f32 v[28:29], v[28:29], v[14:15], v[32:33]
	v_pk_mul_f32 v[14:15], v[56:57], v[0:1] op_sel_hi:[1,0]
	s_waitcnt vmcnt(1)
	v_mov_b32_e32 v18, v44
	v_mov_b32_e32 v19, v46
	s_waitcnt vmcnt(0)
	v_mov_b32_e32 v20, v48
	v_mov_b32_e32 v21, v50
	v_pk_fma_f32 v[26:27], v[14:15], v[18:19], v[20:21]
	v_pk_mul_f32 v[14:15], v[58:59], v[0:1] op_sel_hi:[1,0]
	v_pk_mul_f32 v[12:13], v[54:55], v[0:1] op_sel_hi:[1,0]
	v_pk_fma_f32 v[22:23], v[38:39], v[14:15], v[42:43]
	v_pk_mul_f32 v[14:15], v[60:61], v[0:1] op_sel_hi:[1,0]
	v_mov_b32_e32 v46, v45
	v_mov_b32_e32 v50, v49
	v_pk_fma_f32 v[10:11], v[70:71], v[10:11], v[72:73]
	v_pk_fma_f32 v[12:13], v[30:31], v[12:13], v[34:35]
	s_and_b64 vcc, exec, s[36:37]
	v_pk_fma_f32 v[18:19], v[14:15], v[46:47], v[50:51]
	s_cbranch_vccnz .LBB0_1635
	v_cvt_pk_bf16_f32 v33, v29, v23
	v_cvt_pk_bf16_f32 v32, v28, v22
	v_cvt_pk_bf16_f32 v31, v11, v17
	v_cvt_pk_bf16_f32 v30, v10, v16
	v_lshl_add_u64 v[14:15], v[98:99], 0, s[50:51]
	global_store_dwordx4 v[14:15], v[30:33], off
	s_nop 1
	v_cvt_pk_bf16_f32 v33, v27, v19
	v_cvt_pk_bf16_f32 v32, v26, v18
	v_cvt_pk_bf16_f32 v31, v25, v13
	v_cvt_pk_bf16_f32 v30, v24, v12
	global_store_dwordx4 v[14:15], v[30:33], off offset:1024

.LBB0_1637:
	global_load_dwordx4 v[10:13], v[92:93], off
	s_nop 0
	global_load_dwordx4 v[16:19], v[94:95], off
	global_load_dwordx4 v[20:23], v[92:93], off offset:2048
	global_load_dwordx4 v[24:27], v[94:95], off offset:2048
	global_load_dwordx4 v[28:31], v[92:93], off offset:16
	global_load_dwordx4 v[32:35], v[94:95], off offset:16
	global_load_dwordx4 v[36:39], v[92:93], off offset:2064
	global_load_dwordx4 v[40:43], v[94:95], off offset:2064
	v_lshlrev_b32_e32 v14, 16, v6
	v_and_b32_e32 v6, 0xffff0000, v6
	v_add_f32_e32 v0, 0, v14
	v_lshlrev_b32_e32 v15, 16, v7
	v_add_f32_e32 v0, v0, v6
	v_and_b32_e32 v7, 0xffff0000, v7
	v_add_f32_e32 v0, v0, v15
	v_lshlrev_b32_e32 v44, 16, v8
	v_add_f32_e32 v0, v0, v7
	v_and_b32_e32 v8, 0xffff0000, v8
	v_add_f32_e32 v0, v0, v44
	v_lshlrev_b32_e32 v45, 16, v9
	v_add_f32_e32 v0, v0, v8
	v_and_b32_e32 v9, 0xffff0000, v9
	v_add_f32_e32 v0, v0, v45
	v_lshlrev_b32_e32 v46, 16, v2
	v_add_f32_e32 v0, v0, v9
	v_and_b32_e32 v2, 0xffff0000, v2
	v_add_f32_e32 v0, v0, v46
	v_lshlrev_b32_e32 v47, 16, v3
	v_add_f32_e32 v0, v0, v2
	v_and_b32_e32 v3, 0xffff0000, v3
	v_add_f32_e32 v0, v0, v47
	v_lshlrev_b32_e32 v48, 16, v4
	v_add_f32_e32 v0, v0, v3
	v_and_b32_e32 v4, 0xffff0000, v4
	v_add_f32_e32 v0, v0, v48
	v_lshlrev_b32_e32 v49, 16, v5
	v_add_f32_e32 v0, v0, v4
	v_and_b32_e32 v5, 0xffff0000, v5
	v_add_f32_e32 v0, v0, v49
	v_add_f32_e32 v0, v0, v5
	s_waitcnt vmcnt(7)
	v_mov_b32_e32 v62, v10
	v_add_f32_dpp v0, v0, v0 quad_perm:[1,0,3,2] row_mask:0xf bank_mask:0xf bound_ctrl:1
	v_mov_b32_e32 v63, v12
	v_mov_b32_e32 v12, v11
	v_add_f32_dpp v0, v0, v0 quad_perm:[2,3,0,1] row_mask:0xf bank_mask:0xf bound_ctrl:1
	s_waitcnt vmcnt(5)
	v_mov_b32_e32 v10, v20
	v_mov_b32_e32 v11, v22
	v_add_f32_dpp v0, v0, v0 row_half_mirror row_mask:0xf bank_mask:0xf bound_ctrl:1
	v_mov_b32_e32 v22, v21
	v_mov_b32_e32 v64, v16
	v_add_f32_dpp v0, v0, v0 row_mirror row_mask:0xf bank_mask:0xf bound_ctrl:1
	v_mov_b32_e32 v65, v18
	v_readlane_b32 s2, v0, 16
	v_readlane_b32 s3, v0, 48
	v_readlane_b32 s0, v0, 0
	v_readlane_b32 s1, v0, 32
	v_mov_b32_e32 v50, s2
	v_mov_b32_e32 v51, s3
	v_pk_add_f32 v[50:51], s[0:1], v[50:51]
	v_mov_b32_e32 v18, v17
	v_add_f32_e32 v0, v50, v51
	v_mul_f32_e32 v0, 0x3a800000, v0
	v_pk_add_f32 v[14:15], v[14:15], v[0:1] op_sel_hi:[1,0] neg_lo:[0,1] neg_hi:[0,1]
	v_pk_add_f32 v[6:7], v[6:7], v[0:1] op_sel_hi:[1,0] neg_lo:[0,1] neg_hi:[0,1]
	v_pk_add_f32 v[50:51], v[8:9], v[0:1] op_sel_hi:[1,0] neg_lo:[0,1] neg_hi:[0,1]
	v_pk_add_f32 v[8:9], v[46:47], v[0:1] op_sel_hi:[1,0] neg_lo:[0,1] neg_hi:[0,1]
	v_pk_add_f32 v[46:47], v[2:3], v[0:1] op_sel_hi:[1,0] neg_lo:[0,1] neg_hi:[0,1]
	v_pk_add_f32 v[52:53], v[4:5], v[0:1] op_sel_hi:[1,0] neg_lo:[0,1] neg_hi:[0,1]
	v_pk_mul_f32 v[2:3], v[14:15], v[14:15]
	v_pk_mul_f32 v[4:5], v[6:7], v[6:7]
	v_pk_add_f32 v[44:45], v[44:45], v[0:1] op_sel_hi:[1,0] neg_lo:[0,1] neg_hi:[0,1]
	v_pk_add_f32 v[48:49], v[48:49], v[0:1] op_sel_hi:[1,0] neg_lo:[0,1] neg_hi:[0,1]
	v_add_f32_e32 v0, v2, v4
	v_add_f32_e32 v0, v3, v0
	v_pk_mul_f32 v[54:55], v[44:45], v[44:45]
	v_add_f32_e32 v0, v5, v0
	v_pk_mul_f32 v[56:57], v[50:51], v[50:51]
	v_add_f32_e32 v0, v54, v0
	v_add_f32_e32 v0, v56, v0
	v_add_f32_e32 v0, v55, v0
	v_add_f32_e32 v0, v57, v0
	v_mov_b32_e32 v58, v47
	v_mov_b32_e32 v59, v9
	v_fmac_f32_e32 v0, v8, v8
	v_pk_mul_f32 v[58:59], v[58:59], v[58:59]
	v_fmac_f32_e32 v0, v46, v46
	v_mov_b32_e32 v60, v52
	v_mov_b32_e32 v61, v48
	v_add_f32_e32 v0, v59, v0
	v_pk_mul_f32 v[20:21], v[60:61], v[60:61]
	v_add_f32_e32 v0, v58, v0
	s_waitcnt vmcnt(4)
	v_mov_b32_e32 v16, v24
	v_mov_b32_e32 v17, v26
	v_mov_b32_e32 v26, v25
	v_mov_b32_e32 v24, v53
	v_mov_b32_e32 v25, v49
	v_add_f32_e32 v0, v21, v0
	v_pk_mul_f32 v[24:25], v[24:25], v[24:25]
	v_add_f32_e32 v0, v20, v0
	v_add_f32_e32 v0, v25, v0
	v_add_f32_e32 v0, v24, v0
	s_waitcnt vmcnt(3)
	v_mov_b32_e32 v20, v28
	v_mov_b32_e32 v21, v30
	v_add_f32_dpp v0, v0, v0 quad_perm:[1,0,3,2] row_mask:0xf bank_mask:0xf bound_ctrl:1
	s_waitcnt vmcnt(2)
	v_mov_b32_e32 v24, v32
	v_mov_b32_e32 v25, v34
	v_add_f32_dpp v0, v0, v0 quad_perm:[2,3,0,1] row_mask:0xf bank_mask:0xf bound_ctrl:1
	v_mov_b32_e32 v30, v29
	v_mov_b32_e32 v34, v33
	v_add_f32_dpp v0, v0, v0 row_half_mirror row_mask:0xf bank_mask:0xf bound_ctrl:1
	s_nop 1
	v_add_f32_dpp v0, v0, v0 row_mirror row_mask:0xf bank_mask:0xf bound_ctrl:1
	s_nop 0
	v_readlane_b32 s2, v0, 16
	v_readlane_b32 s3, v0, 48
	v_readlane_b32 s0, v0, 0
	v_readlane_b32 s1, v0, 32
	v_mov_b32_e32 v2, s2
	v_mov_b32_e32 v3, s3
	v_pk_add_f32 v[2:3], s[0:1], v[2:3]
	s_nop 0
	v_add_f32_e32 v0, v2, v3
	v_fmamk_f32 v0, v0, 0x3a800000, v216
	v_mul_f32_e32 v2, 0x4f800000, v0
	v_cmp_gt_f32_e32 vcc, s60, v0
	s_nop 1
	v_cndmask_b32_e32 v0, v0, v2, vcc
	v_sqrt_f32_e32 v2, v0
	s_nop 0
	v_add_u32_e32 v3, -1, v2
	v_fma_f32 v4, -v3, v2, v0
	v_cmp_ge_f32_e64 s[2:3], 0, v4
	v_add_u32_e32 v4, 1, v2
	s_nop 0
	v_cndmask_b32_e64 v3, v2, v3, s[2:3]
	v_fma_f32 v2, -v4, v2, v0
	v_cmp_lt_f32_e64 s[2:3], 0, v2
	s_nop 1
	v_cndmask_b32_e64 v2, v3, v4, s[2:3]
	v_mul_f32_e32 v3, 0x37800000, v2
	v_cndmask_b32_e32 v2, v2, v3, vcc
	v_cmp_class_f32_e32 vcc, v0, v217
	s_nop 1
	v_cndmask_b32_e32 v0, v2, v0, vcc
	v_div_scale_f32 v2, s[0:1], v0, v0, 1.0
	v_rcp_f32_e32 v3, v2
	s_nop 0
	v_fma_f32 v4, -v2, v3, 1.0
	v_fmac_f32_e32 v3, v4, v3
	v_div_scale_f32 v4, vcc, 1.0, v0, 1.0
	v_mul_f32_e32 v5, v4, v3
	v_fma_f32 v28, -v2, v5, v4
	v_fmac_f32_e32 v5, v28, v3
	v_fma_f32 v2, -v2, v5, v4
	v_div_fmas_f32 v2, v2, v3, v5
	v_div_fixup_f32 v0, v2, v0, 1.0
	v_pk_mul_f32 v[4:5], v[8:9], v[0:1] op_sel_hi:[1,0]
	v_pk_mul_f32 v[2:3], v[14:15], v[0:1] op_sel_hi:[1,0]
	v_pk_fma_f32 v[16:17], v[10:11], v[4:5], v[16:17]
	v_pk_mul_f32 v[4:5], v[6:7], v[0:1] op_sel_hi:[1,0]
	v_pk_mul_f32 v[6:7], v[44:45], v[0:1] op_sel_hi:[1,0]
	v_pk_fma_f32 v[8:9], v[12:13], v[4:5], v[18:19]
	v_pk_fma_f32 v[20:21], v[20:21], v[6:7], v[24:25]
	v_pk_mul_f32 v[6:7], v[48:49], v[0:1] op_sel_hi:[1,0]
	s_waitcnt vmcnt(1)
	v_mov_b32_e32 v10, v36
	v_mov_b32_e32 v11, v38
	s_waitcnt vmcnt(0)
	v_mov_b32_e32 v12, v40
	v_mov_b32_e32 v13, v42
	v_pk_fma_f32 v[18:19], v[6:7], v[10:11], v[12:13]
	v_pk_mul_f32 v[6:7], v[50:51], v[0:1] op_sel_hi:[1,0]
	v_pk_mul_f32 v[4:5], v[46:47], v[0:1] op_sel_hi:[1,0]
	v_pk_fma_f32 v[14:15], v[30:31], v[6:7], v[34:35]
	v_pk_mul_f32 v[6:7], v[52:53], v[0:1] op_sel_hi:[1,0]
	v_mov_b32_e32 v38, v37
	v_mov_b32_e32 v42, v41
	v_pk_fma_f32 v[2:3], v[62:63], v[2:3], v[64:65]
	v_pk_fma_f32 v[4:5], v[22:23], v[4:5], v[26:27]
	s_and_b64 vcc, exec, s[36:37]
	v_pk_fma_f32 v[10:11], v[6:7], v[38:39], v[42:43]
	s_cbranch_vccnz .LBB0_1639
	v_cvt_pk_bf16_f32 v25, v21, v15
	v_cvt_pk_bf16_f32 v24, v20, v14
	v_cvt_pk_bf16_f32 v23, v3, v9
	v_cvt_pk_bf16_f32 v22, v2, v8
	v_lshl_add_u64 v[6:7], v[98:99], 0, s[46:47]
	global_store_dwordx4 v[6:7], v[22:25], off
	s_nop 1
	v_cvt_pk_bf16_f32 v25, v19, v11
	v_cvt_pk_bf16_f32 v24, v18, v10
	v_cvt_pk_bf16_f32 v23, v17, v5
	v_cvt_pk_bf16_f32 v22, v16, v4
	global_store_dwordx4 v[6:7], v[22:25], off offset:1024

.LBB0_1641:
	s_lshr_b32 s4, s67, 3
	s_lshl_b32 s100, s11, 8
	s_add_i32 s4, s4, s100
	s_cmpk_gt_i32 s4, 0x7f
	s_cbranch_scc1 .LBB0_1648
	s_add_i32 s12, s4, 0x4000
	s_ashr_i32 s5, s4, 31
	s_lshl_b64 s[0:1], s[4:5], 12
	v_and_b32_e32 v0, 63, v91
	s_ashr_i32 s13, s12, 31
	v_lshl_or_b32 v96, v0, 5, s0
	v_mov_b32_e32 v97, s1
	s_ashr_i32 s11, s10, 31
	s_lshl_b64 s[0:1], s[12:13], 11
	s_lshl_b64 s[16:17], s[10:11], 12
	v_lshl_or_b32 v98, v0, 4, s0
	v_mov_b32_e32 v99, s1
	s_lshl_b64 s[36:37], s[10:11], 11
	s_branch .LBB0_1644

.LBB0_1644:
	v_lshl_add_u64 v[100:101], s[42:43], 0, v[98:99]
	v_add_co_u32_e32 v2, vcc, 0x1b1e0000, v100
	v_lshl_add_u64 v[102:103], s[42:43], 0, v[96:97]
	s_mov_b64 s[0:1], 0x5080000
	v_addc_co_u32_e32 v3, vcc, 0, v101, vcc
	v_lshl_add_u64 v[6:7], v[102:103], 0, s[0:1]
	s_mov_b32 s0, 0x5080000
	v_add_co_u32_e32 v8, vcc, s0, v102
	s_mov_b64 s[0:1], 0x5080800
	s_nop 0
	v_addc_co_u32_e32 v9, vcc, 0, v103, vcc
	global_load_dwordx4 v[10:13], v[2:3], off
	s_nop 0
	global_load_dwordx4 v[2:5], v[2:3], off offset:1024
	s_nop 0
	global_load_dwordx4 v[22:25], v[8:9], off
	global_load_dwordx4 v[18:21], v[6:7], off offset:16
	v_lshl_add_u64 v[6:7], v[102:103], 0, s[0:1]
	s_mov_b64 s[0:1], 0x5100000
	v_lshl_add_u64 v[26:27], v[102:103], 0, s[0:1]
	s_mov_b32 s0, 0x5100000
	v_add_co_u32_e32 v28, vcc, s0, v102
	s_mov_b64 s[0:1], 0x5100800
	s_nop 0
	v_addc_co_u32_e32 v29, vcc, 0, v103, vcc
	global_load_dwordx4 v[14:17], v[8:9], off offset:2048
	s_nop 0
	global_load_dwordx4 v[6:9], v[6:7], off offset:16
	s_nop 0
	global_load_dwordx4 v[38:41], v[28:29], off
	global_load_dwordx4 v[34:37], v[26:27], off offset:16
	v_lshl_add_u64 v[26:27], v[102:103], 0, s[0:1]
	s_mov_b64 s[0:1], 0x5180000
	v_lshl_add_u64 v[42:43], v[102:103], 0, s[0:1]
	s_mov_b32 s0, 0x5180000
	v_add_co_u32_e32 v44, vcc, s0, v102
	s_mov_b64 s[0:1], 0x5180800
	s_nop 0
	v_addc_co_u32_e32 v45, vcc, 0, v103, vcc
	global_load_dwordx4 v[30:33], v[28:29], off offset:2048
	s_nop 0
	global_load_dwordx4 v[26:29], v[26:27], off offset:16
	s_nop 0
	global_load_dwordx4 v[54:57], v[44:45], off
	global_load_dwordx4 v[50:53], v[42:43], off offset:16
	v_lshl_add_u64 v[42:43], v[102:103], 0, s[0:1]
	s_mov_b64 s[0:1], 0x5200000
	v_lshl_add_u64 v[58:59], v[102:103], 0, s[0:1]
	s_mov_b32 s0, 0x5200000
	v_add_co_u32_e32 v60, vcc, s0, v102
	s_mov_b64 s[0:1], 0x5200800
	s_nop 0
	v_addc_co_u32_e32 v61, vcc, 0, v103, vcc
	global_load_dwordx4 v[46:49], v[44:45], off offset:2048
	s_nop 0
	global_load_dwordx4 v[42:45], v[42:43], off offset:16
	s_nop 0
	global_load_dwordx4 v[70:73], v[60:61], off
	global_load_dwordx4 v[66:69], v[58:59], off offset:16
	v_lshl_add_u64 v[58:59], v[102:103], 0, s[0:1]
	s_mov_b64 s[0:1], 0x5280000
	v_lshl_add_u64 v[78:79], v[102:103], 0, s[0:1]
	s_mov_b32 s0, 0x5280000
	v_add_co_u32_e32 v82, vcc, s0, v102
	global_load_dwordx4 v[62:65], v[60:61], off offset:2048
	s_nop 0
	global_load_dwordx4 v[58:61], v[58:59], off offset:16
	v_addc_co_u32_e32 v83, vcc, 0, v103, vcc
	global_load_dwordx4 v[74:77], v[82:83], off
	s_nop 0
	global_load_dwordx4 v[78:81], v[78:79], off offset:16
	s_mov_b64 s[0:1], 0x5280800
	v_lshl_add_u64 v[86:87], v[102:103], 0, s[0:1]
	global_load_dwordx4 v[82:85], v[82:83], off offset:2048
	s_nop 0
	global_load_dwordx4 v[86:89], v[86:87], off offset:16
	s_mov_b32 s0, 0x3fb504f3
	s_waitcnt vmcnt(21)
	v_lshlrev_b32_e32 v105, 16, v11
	v_lshlrev_b32_e32 v104, 16, v10
	s_waitcnt vmcnt(19)
	v_mov_b32_e32 v106, v22
	v_mov_b32_e32 v107, v24
	v_pk_fma_f32 v[104:105], v[104:105], s[0:1], v[106:107] op_sel_hi:[1,0,1]
	s_waitcnt vmcnt(18)
	v_mov_b32_e32 v108, v18
	v_mov_b32_e32 v109, v20
	v_and_b32_e32 v11, 0xffff0000, v11
	v_and_b32_e32 v10, 0xffff0000, v10
	v_mov_b32_e32 v24, v23
	v_pk_fma_f32 v[10:11], v[10:11], s[0:1], v[24:25] op_sel_hi:[1,0,1]
	s_waitcnt vmcnt(17)
	v_mov_b32_e32 v110, v14
	s_waitcnt vmcnt(15)
	v_mov_b32_e32 v106, v38
	v_mov_b32_e32 v107, v40
	v_pk_add_f32 v[104:105], v[104:105], v[106:107]
	v_mov_b32_e32 v40, v39
	v_pk_add_f32 v[10:11], v[10:11], v[40:41]
	v_mov_b32_e32 v111, v16
	v_mov_b32_e32 v16, v15
	v_mov_b32_e32 v20, v19
	v_mov_b32_e32 v112, v6
	v_mov_b32_e32 v113, v8
	v_mov_b32_e32 v8, v7
	s_waitcnt vmcnt(11)
	v_mov_b32_e32 v106, v54
	v_mov_b32_e32 v107, v56
	v_pk_add_f32 v[104:105], v[104:105], v[106:107]
	v_mov_b32_e32 v56, v55
	v_pk_add_f32 v[10:11], v[10:11], v[56:57]
	s_waitcnt vmcnt(7)
	v_mov_b32_e32 v106, v70
	v_mov_b32_e32 v107, v72
	v_pk_add_f32 v[104:105], v[104:105], v[106:107]
	v_mov_b32_e32 v72, v71
	v_pk_add_f32 v[10:11], v[10:11], v[72:73]
	s_waitcnt vmcnt(3)
	v_mov_b32_e32 v106, v74
	v_mov_b32_e32 v107, v76
	v_pk_add_f32 v[104:105], v[104:105], v[106:107]
	v_lshlrev_b32_e32 v107, 16, v13
	v_lshlrev_b32_e32 v106, 16, v12
	v_pk_fma_f32 v[106:107], v[106:107], s[0:1], v[108:109] op_sel_hi:[1,0,1]
	v_mov_b32_e32 v108, v34
	v_mov_b32_e32 v109, v36
	v_pk_add_f32 v[106:107], v[106:107], v[108:109]
	v_mov_b32_e32 v108, v50
	v_mov_b32_e32 v109, v52
	v_pk_add_f32 v[106:107], v[106:107], v[108:109]
	v_mov_b32_e32 v108, v66
	v_mov_b32_e32 v109, v68
	v_pk_add_f32 v[106:107], v[106:107], v[108:109]
	s_waitcnt vmcnt(2)
	v_mov_b32_e32 v108, v78
	v_mov_b32_e32 v109, v80
	v_pk_add_f32 v[108:109], v[106:107], v[108:109]
	v_lshlrev_b32_e32 v107, 16, v3
	v_lshlrev_b32_e32 v106, 16, v2
	v_mov_b32_e32 v76, v75
	v_and_b32_e32 v3, 0xffff0000, v3
	v_and_b32_e32 v2, 0xffff0000, v2
	v_pk_fma_f32 v[106:107], v[106:107], s[0:1], v[110:111] op_sel_hi:[1,0,1]
	v_mov_b32_e32 v110, v30
	v_mov_b32_e32 v111, v32
	v_pk_add_f32 v[72:73], v[10:11], v[76:77]
	v_and_b32_e32 v11, 0xffff0000, v13
	v_and_b32_e32 v10, 0xffff0000, v12
	v_pk_fma_f32 v[2:3], v[2:3], s[0:1], v[16:17] op_sel_hi:[1,0,1]
	v_mov_b32_e32 v32, v31
	v_pk_add_f32 v[106:107], v[106:107], v[110:111]
	v_mov_b32_e32 v110, v46
	v_mov_b32_e32 v111, v48
	v_pk_fma_f32 v[10:11], v[10:11], s[0:1], v[20:21] op_sel_hi:[1,0,1]
	v_mov_b32_e32 v36, v35
	v_pk_add_f32 v[2:3], v[2:3], v[32:33]
	v_mov_b32_e32 v48, v47
	v_pk_add_f32 v[106:107], v[106:107], v[110:111]
	v_mov_b32_e32 v110, v62
	v_mov_b32_e32 v111, v64
	v_pk_add_f32 v[10:11], v[10:11], v[36:37]
	v_mov_b32_e32 v52, v51
	v_pk_add_f32 v[2:3], v[2:3], v[48:49]
	v_mov_b32_e32 v64, v63
	v_pk_add_f32 v[106:107], v[106:107], v[110:111]
	s_waitcnt vmcnt(1)
	v_mov_b32_e32 v110, v82
	v_mov_b32_e32 v111, v84
	v_pk_add_f32 v[10:11], v[10:11], v[52:53]
	v_mov_b32_e32 v68, v67
	v_pk_add_f32 v[2:3], v[2:3], v[64:65]
	v_mov_b32_e32 v84, v83
	v_pk_add_f32 v[110:111], v[106:107], v[110:111]
	v_lshlrev_b32_e32 v107, 16, v5
	v_lshlrev_b32_e32 v106, 16, v4
	v_pk_add_f32 v[10:11], v[10:11], v[68:69]
	v_pk_add_f32 v[68:69], v[2:3], v[84:85]
	v_and_b32_e32 v3, 0xffff0000, v5
	v_and_b32_e32 v2, 0xffff0000, v4
	v_pk_fma_f32 v[106:107], v[106:107], s[0:1], v[112:113] op_sel_hi:[1,0,1]
	v_mov_b32_e32 v112, v26
	v_mov_b32_e32 v113, v28
	v_pk_fma_f32 v[2:3], v[2:3], s[0:1], v[8:9] op_sel_hi:[1,0,1]
	v_mov_b32_e32 v28, v27
	v_pk_add_f32 v[106:107], v[106:107], v[112:113]
	v_mov_b32_e32 v112, v42
	v_mov_b32_e32 v113, v44
	v_pk_add_f32 v[2:3], v[2:3], v[28:29]
	v_mov_b32_e32 v44, v43
	v_pk_add_f32 v[106:107], v[106:107], v[112:113]
	v_mov_b32_e32 v112, v58
	v_mov_b32_e32 v113, v60
	v_pk_add_f32 v[2:3], v[2:3], v[44:45]
	v_mov_b32_e32 v60, v59
	v_pk_add_f32 v[106:107], v[106:107], v[112:113]
	s_waitcnt vmcnt(0)
	v_mov_b32_e32 v113, v88
	v_pk_add_f32 v[2:3], v[2:3], v[60:61]
	v_mov_b32_e32 v88, v87
	s_mov_b64 s[0:1], 0x5300000
	v_pk_add_f32 v[66:67], v[2:3], v[88:89]
	v_lshl_add_u64 v[2:3], v[102:103], 0, s[0:1]
	s_mov_b32 s0, 0x5300000
	v_add_co_u32_e32 v4, vcc, s0, v102
	s_mov_b64 s[0:1], 0x5300800
	s_nop 0
	v_addc_co_u32_e32 v5, vcc, 0, v103, vcc
	global_load_dwordx4 v[54:57], v[4:5], off
	global_load_dwordx4 v[38:41], v[2:3], off offset:16
	v_lshl_add_u64 v[2:3], v[102:103], 0, s[0:1]
	s_mov_b64 s[0:1], 0x5380000
	global_load_dwordx4 v[30:33], v[4:5], off offset:2048
	global_load_dwordx4 v[22:25], v[2:3], off offset:16
	v_lshl_add_u64 v[2:3], v[102:103], 0, s[0:1]
	s_mov_b32 s0, 0x5380000
	v_add_co_u32_e32 v4, vcc, s0, v102
	s_mov_b64 s[0:1], 0x5380800
	s_nop 0
	v_addc_co_u32_e32 v5, vcc, 0, v103, vcc
	global_load_dwordx4 v[62:65], v[4:5], off
	global_load_dwordx4 v[58:61], v[2:3], off offset:16
	v_mov_b32_e32 v80, v79
	v_lshl_add_u64 v[2:3], v[102:103], 0, s[0:1]
	v_pk_add_f32 v[70:71], v[10:11], v[80:81]
	global_load_dwordx4 v[50:53], v[4:5], off offset:2048
	global_load_dwordx4 v[26:29], v[2:3], off offset:16
	s_nop 0
	global_load_dwordx4 v[2:5], v[92:93], off offset:16
	global_load_dwordx4 v[10:13], v[92:93], off
	global_load_dwordx4 v[6:9], v[94:95], off offset:16
	global_load_dwordx4 v[14:17], v[94:95], off
	global_load_dwordx4 v[18:21], v[92:93], off offset:2064
	global_load_dwordx4 v[42:45], v[92:93], off offset:2048
	global_load_dwordx4 v[34:37], v[94:95], off offset:2064
	global_load_dwordx4 v[46:49], v[94:95], off offset:2048
	v_mov_b32_e32 v112, v86
	v_pk_add_f32 v[106:107], v[106:107], v[112:113]
	s_waitcnt vmcnt(15)
	v_mov_b32_e32 v74, v54
	v_mov_b32_e32 v75, v56
	v_mov_b32_e32 v56, v55
	v_pk_add_f32 v[74:75], v[104:105], v[74:75]
	v_pk_add_f32 v[54:55], v[72:73], v[56:57]
	s_waitcnt vmcnt(11)
	v_mov_b32_e32 v56, v62
	v_mov_b32_e32 v57, v64
	v_pk_add_f32 v[56:57], v[74:75], v[56:57]
	v_mov_b32_e32 v64, v63
	v_pk_add_f32 v[54:55], v[54:55], v[64:65]
	v_add_f32_e32 v0, 0, v56
	v_add_f32_e32 v0, v54, v0
	s_waitcnt vmcnt(6)
	v_mov_b32_e32 v62, v10
	v_mov_b32_e32 v63, v12
	v_mov_b32_e32 v12, v11
	v_mov_b32_e32 v10, v38
	v_mov_b32_e32 v11, v40
	v_add_f32_e32 v0, v57, v0
	v_pk_add_f32 v[10:11], v[108:109], v[10:11]
	v_mov_b32_e32 v40, v39
	v_mov_b32_e32 v38, v58
	v_mov_b32_e32 v39, v60
	v_add_f32_e32 v0, v55, v0
	s_waitcnt vmcnt(4)
	v_mov_b32_e32 v64, v14
	v_mov_b32_e32 v65, v16
	v_mov_b32_e32 v16, v15
	v_pk_add_f32 v[14:15], v[70:71], v[40:41]
	v_pk_add_f32 v[10:11], v[10:11], v[38:39]
	v_mov_b32_e32 v60, v59
	v_pk_add_f32 v[14:15], v[14:15], v[60:61]
	v_add_f32_e32 v0, v10, v0
	v_add_f32_e32 v0, v14, v0
	v_mov_b32_e32 v38, v30
	v_mov_b32_e32 v39, v32
	v_mov_b32_e32 v32, v31
	v_add_f32_e32 v0, v11, v0
	v_pk_add_f32 v[38:39], v[110:111], v[38:39]
	v_pk_add_f32 v[30:31], v[68:69], v[32:33]
	v_mov_b32_e32 v32, v50
	v_mov_b32_e32 v33, v52
	v_add_f32_e32 v0, v15, v0
	v_pk_add_f32 v[32:33], v[38:39], v[32:33]
	v_mov_b32_e32 v52, v51
	v_pk_add_f32 v[30:31], v[30:31], v[52:53]
	v_add_f32_e32 v0, v32, v0
	v_add_f32_e32 v0, v30, v0
	s_waitcnt vmcnt(2)
	v_mov_b32_e32 v38, v42
	v_mov_b32_e32 v39, v44
	v_mov_b32_e32 v44, v43
	v_mov_b32_e32 v42, v2
	v_mov_b32_e32 v43, v4
	v_mov_b32_e32 v4, v3
	v_mov_b32_e32 v2, v22
	v_mov_b32_e32 v3, v24
	v_add_f32_e32 v0, v33, v0
	v_pk_add_f32 v[2:3], v[106:107], v[2:3]
	v_mov_b32_e32 v24, v23
	v_mov_b32_e32 v22, v26
	v_mov_b32_e32 v23, v28
	v_add_f32_e32 v0, v31, v0
	s_waitcnt vmcnt(0)
	v_mov_b32_e32 v40, v46
	v_mov_b32_e32 v41, v48
	v_mov_b32_e32 v48, v47
	v_mov_b32_e32 v46, v6
	v_mov_b32_e32 v47, v8
	v_mov_b32_e32 v8, v7
	v_pk_add_f32 v[6:7], v[66:67], v[24:25]
	v_pk_add_f32 v[2:3], v[2:3], v[22:23]
	v_mov_b32_e32 v28, v27
	v_pk_add_f32 v[6:7], v[6:7], v[28:29]
	v_add_f32_e32 v0, v2, v0
	v_add_f32_e32 v0, v6, v0
	v_add_f32_e32 v0, v3, v0
	v_add_f32_e32 v0, v7, v0
	s_nop 1
	v_add_f32_dpp v0, v0, v0 quad_perm:[1,0,3,2] row_mask:0xf bank_mask:0xf bound_ctrl:1
	s_nop 1
	v_add_f32_dpp v0, v0, v0 quad_perm:[2,3,0,1] row_mask:0xf bank_mask:0xf bound_ctrl:1
	s_nop 1
	v_add_f32_dpp v0, v0, v0 row_half_mirror row_mask:0xf bank_mask:0xf bound_ctrl:1
	s_nop 1
	v_add_f32_dpp v0, v0, v0 row_mirror row_mask:0xf bank_mask:0xf bound_ctrl:1
	s_nop 0
	v_readlane_b32 s2, v0, 16
	v_readlane_b32 s3, v0, 48
	v_readlane_b32 s0, v0, 0
	v_readlane_b32 s1, v0, 32
	v_mov_b32_e32 v22, s2
	v_mov_b32_e32 v23, s3
	v_pk_add_f32 v[22:23], s[0:1], v[22:23]
	s_nop 0
	v_add_f32_e32 v0, v22, v23
	v_mul_f32_e32 v0, 0x3a800000, v0
	v_pk_add_f32 v[22:23], v[56:57], v[0:1] op_sel_hi:[1,0] neg_lo:[0,1] neg_hi:[0,1]
	v_pk_add_f32 v[26:27], v[54:55], v[0:1] op_sel_hi:[1,0] neg_lo:[0,1] neg_hi:[0,1]
	v_pk_mul_f32 v[24:25], v[22:23], v[22:23]
	v_pk_mul_f32 v[28:29], v[26:27], v[26:27]
	v_pk_add_f32 v[50:51], v[10:11], v[0:1] op_sel_hi:[1,0] neg_lo:[0,1] neg_hi:[0,1]
	v_pk_add_f32 v[52:53], v[14:15], v[0:1] op_sel_hi:[1,0] neg_lo:[0,1] neg_hi:[0,1]
	v_pk_add_f32 v[32:33], v[32:33], v[0:1] op_sel_hi:[1,0] neg_lo:[0,1] neg_hi:[0,1]
	v_pk_add_f32 v[30:31], v[30:31], v[0:1] op_sel_hi:[1,0] neg_lo:[0,1] neg_hi:[0,1]
	v_pk_add_f32 v[56:57], v[2:3], v[0:1] op_sel_hi:[1,0] neg_lo:[0,1] neg_hi:[0,1]
	v_pk_add_f32 v[58:59], v[6:7], v[0:1] op_sel_hi:[1,0] neg_lo:[0,1] neg_hi:[0,1]
	v_add_f32_e32 v0, v24, v28
	v_add_f32_e32 v0, v25, v0
	v_pk_mul_f32 v[10:11], v[50:51], v[50:51]
	v_add_f32_e32 v0, v29, v0
	v_pk_mul_f32 v[14:15], v[52:53], v[52:53]
	v_add_f32_e32 v0, v10, v0
	v_add_f32_e32 v0, v14, v0
	v_add_f32_e32 v0, v11, v0
	v_add_f32_e32 v0, v15, v0
	v_mov_b32_e32 v54, v31
	v_mov_b32_e32 v55, v33
	v_fmac_f32_e32 v0, v32, v32
	v_pk_mul_f32 v[54:55], v[54:55], v[54:55]
	v_fmac_f32_e32 v0, v30, v30
	v_mov_b32_e32 v2, v58
	v_mov_b32_e32 v3, v56
	v_add_f32_e32 v0, v55, v0
	v_pk_mul_f32 v[2:3], v[2:3], v[2:3]
	v_add_f32_e32 v0, v54, v0
	v_mov_b32_e32 v6, v59
	v_mov_b32_e32 v7, v57
	v_add_f32_e32 v0, v3, v0
	v_pk_mul_f32 v[6:7], v[6:7], v[6:7]
	v_add_f32_e32 v0, v2, v0
	v_add_f32_e32 v0, v7, v0
	v_add_f32_e32 v0, v6, v0
	v_mov_b32_e32 v24, v34
	v_mov_b32_e32 v25, v36
	v_add_f32_dpp v0, v0, v0 quad_perm:[1,0,3,2] row_mask:0xf bank_mask:0xf bound_ctrl:1
	v_mov_b32_e32 v36, v35
	s_nop 0
	v_add_f32_dpp v0, v0, v0 quad_perm:[2,3,0,1] row_mask:0xf bank_mask:0xf bound_ctrl:1
	s_nop 1
	v_add_f32_dpp v0, v0, v0 row_half_mirror row_mask:0xf bank_mask:0xf bound_ctrl:1
	s_nop 1
	v_add_f32_dpp v0, v0, v0 row_mirror row_mask:0xf bank_mask:0xf bound_ctrl:1
	s_nop 0
	v_readlane_b32 s2, v0, 16
	v_readlane_b32 s3, v0, 48
	v_readlane_b32 s0, v0, 0
	v_readlane_b32 s1, v0, 32
	v_mov_b32_e32 v2, s2
	v_mov_b32_e32 v3, s3
	v_pk_add_f32 v[2:3], s[0:1], v[2:3]
	s_nop 0
	v_add_f32_e32 v0, v2, v3
	v_fmamk_f32 v0, v0, 0x3a800000, v216
	v_cmp_gt_f32_e32 vcc, s60, v0
	v_mul_f32_e32 v2, 0x4f800000, v0
	s_nop 0
	v_cndmask_b32_e32 v0, v0, v2, vcc
	v_sqrt_f32_e32 v2, v0
	s_nop 0
	v_add_u32_e32 v3, -1, v2
	v_fma_f32 v6, -v3, v2, v0
	v_cmp_ge_f32_e64 s[2:3], 0, v6
	v_add_u32_e32 v6, 1, v2
	s_nop 0
	v_cndmask_b32_e64 v3, v2, v3, s[2:3]
	v_fma_f32 v2, -v6, v2, v0
	v_cmp_lt_f32_e64 s[2:3], 0, v2
	s_nop 1
	v_cndmask_b32_e64 v2, v3, v6, s[2:3]
	v_mul_f32_e32 v3, 0x37800000, v2
	v_cndmask_b32_e32 v2, v2, v3, vcc
	v_cmp_class_f32_e32 vcc, v0, v217
	s_nop 1
	v_cndmask_b32_e32 v0, v2, v0, vcc
	v_div_scale_f32 v2, s[0:1], v0, v0, 1.0
	v_rcp_f32_e32 v3, v2
	v_readlane_b32 s0, v255, 22
	v_readlane_b32 s1, v255, 23
	v_fma_f32 v6, -v2, v3, 1.0
	v_fmac_f32_e32 v3, v6, v3
	v_div_scale_f32 v6, vcc, 1.0, v0, 1.0
	v_mul_f32_e32 v7, v6, v3
	v_fma_f32 v10, -v2, v7, v6
	v_fmac_f32_e32 v7, v10, v3
	v_fma_f32 v2, -v2, v7, v6
	v_div_fmas_f32 v2, v2, v3, v7
	v_div_fixup_f32 v0, v2, v0, 1.0
	v_pk_mul_f32 v[6:7], v[32:33], v[0:1] op_sel_hi:[1,0]
	v_pk_mul_f32 v[2:3], v[22:23], v[0:1] op_sel_hi:[1,0]
	v_pk_fma_f32 v[14:15], v[38:39], v[6:7], v[40:41]
	v_pk_mul_f32 v[6:7], v[26:27], v[0:1] op_sel_hi:[1,0]
	v_pk_fma_f32 v[2:3], v[62:63], v[2:3], v[64:65]
	v_pk_fma_f32 v[10:11], v[12:13], v[6:7], v[16:17]
	v_pk_mul_f32 v[12:13], v[50:51], v[0:1] op_sel_hi:[1,0]
	v_mov_b32_e32 v16, v18
	v_pk_fma_f32 v[22:23], v[42:43], v[12:13], v[46:47]
	v_pk_mul_f32 v[12:13], v[56:57], v[0:1] op_sel_hi:[1,0]
	v_mov_b32_e32 v17, v20
	v_pk_fma_f32 v[16:17], v[12:13], v[16:17], v[24:25]
	v_pk_mul_f32 v[12:13], v[52:53], v[0:1] op_sel_hi:[1,0]
	v_pk_mul_f32 v[6:7], v[30:31], v[0:1] op_sel_hi:[1,0]
	v_pk_fma_f32 v[4:5], v[4:5], v[12:13], v[8:9]
	v_pk_mul_f32 v[8:9], v[58:59], v[0:1] op_sel_hi:[1,0]
	v_mov_b32_e32 v20, v19
	v_pk_fma_f32 v[6:7], v[44:45], v[6:7], v[48:49]
	v_pk_fma_f32 v[12:13], v[8:9], v[20:21], v[36:37]
	s_andn2_b64 vcc, exec, s[0:1]
	s_cbranch_vccnz .LBB0_1646
	s_mov_b32 s0, 0x9580000
	v_cvt_pk_bf16_f32 v20, v22, v4
	v_add_co_u32_e32 v8, vcc, s0, v100
	v_cvt_pk_bf16_f32 v21, v23, v5
	v_cvt_pk_bf16_f32 v19, v3, v11
	v_cvt_pk_bf16_f32 v18, v2, v10
	v_addc_co_u32_e32 v9, vcc, 0, v101, vcc
	global_store_dwordx4 v[8:9], v[18:21], off
	s_nop 1
	v_cvt_pk_bf16_f32 v21, v17, v13
	v_cvt_pk_bf16_f32 v20, v16, v12
	v_cvt_pk_bf16_f32 v19, v15, v7
	v_cvt_pk_bf16_f32 v18, v14, v6
	global_store_dwordx4 v[8:9], v[18:21], off offset:1024
